# static priority: s_setprio 1 once for waves 4-7 at entry, all 208 per-cluster s_setprio flips deleted (v20 otherwise)
# speedup vs baseline: 1.0088x; 1.0005x over previous
_Z6mk_fwd4Args:
	s_load_dwordx8 s[4:11], s[0:1], 0xc0
	s_load_dwordx4 s[76:79], s[0:1], 0xe0
	s_load_dword s3, s[0:1], 0xf8
	v_readfirstlane_b32 s96, v0
	s_nop 3
	s_cmp_ge_u32 s96, 0x100
	s_cbranch_scc0 .Lprio_done
	s_setprio 1
.Lprio_done:
	v_mbcnt_lo_u32_b32 v0, -1, 0
	v_mbcnt_hi_u32_b32 v0, -1, v0
	s_waitcnt lgkmcnt(0)
	v_writelane_b32 v255, s4, 0
	s_nop 1
	v_writelane_b32 v255, s5, 1
	v_writelane_b32 v255, s6, 2
	v_writelane_b32 v255, s7, 3
	v_writelane_b32 v255, s8, 4
	v_writelane_b32 v255, s9, 5
	v_writelane_b32 v255, s10, 6
	v_writelane_b32 v255, s11, 7
	s_add_u32 s4, s0, 0xf8
	s_addc_u32 s5, s1, 0
	v_writelane_b32 v255, s4, 8
	s_and_b32 s97, s96, 0xffffffc0
	v_or_b32_e32 v1, s97, v0
	v_writelane_b32 v255, s5, 9
	v_writelane_b32 v255, s3, 10
	s_movk_i32 s3, 0xc0
	v_cmp_gt_i32_e32 vcc, s3, v1
	s_and_saveexec_b64 s[4:5], vcc
	s_cbranch_execz .LBB0_3
	v_add_u32_e32 v0, 0xfffffe00, v1
	v_lshl_add_u32 v1, v1, 2, 0
	v_add_u32_e32 v1, 0x27d00, v1
	s_mov_b64 s[6:7], 0
	v_mov_b32_e32 v2, 0
	s_movk_i32 s3, 0xfebf

.LBB0_188:
	ds_read_b128 v[128:131], v168
	ds_read_b128 v[152:155], v168 offset:1024
	ds_read_b128 v[180:183], v168 offset:2048
	ds_read_b128 v[184:187], v168 offset:3072
	ds_read_b128 v[188:191], v169
	ds_read_b128 v[192:195], v169 offset:1024
	ds_read_b128 v[196:199], v169 offset:2048
	ds_read_b128 v[200:203], v169 offset:3072
	s_add_u32 s4, s0, 0x100
	s_addc_u32 s5, s1, 0
	s_cmp_eq_u32 s16, 12
	s_cselect_b32 s13, s95, s5
	s_cselect_b32 s12, s94, s4
	s_cselect_b32 s11, s97, s15
	s_cselect_b32 s10, s96, s14
	v_lshl_add_u64 v[156:157], s[0:1], 0, v[144:145]
	s_add_i32 m0, s89, 0xc000
	ds_read_b128 v[204:207], v170
	ds_read_b128 v[208:211], v170 offset:1024
	ds_read_b128 v[212:215], v170 offset:2048
	ds_read_b128 v[216:219], v170 offset:3072
	ds_read_b128 v[220:223], v170 offset:4096
	ds_read_b128 v[224:227], v170 offset:5120
	ds_read_b128 v[228:231], v170 offset:6144
	ds_read_b128 v[232:235], v170 offset:7168
	global_load_lds_dwordx4 v[156:157], off
	v_lshl_add_u64 v[156:157], s[0:1], 0, v[146:147]
	s_add_i32 m0, s89, 0xe000
	s_nop 0
	global_load_lds_dwordx4 v[156:157], off
	s_waitcnt vmcnt(8)
	s_waitcnt lgkmcnt(0)
	s_barrier
	s_waitcnt lgkmcnt(0)
	v_mfma_f32_16x16x32_f16 v[84:87], v[128:131], v[204:207], v[84:87]
	v_mfma_f32_16x16x32_f16 v[92:95], v[180:183], v[204:207], v[92:95]
	v_mfma_f32_16x16x32_f16 v[68:71], v[128:131], v[212:215], v[68:71]
	v_mfma_f32_16x16x32_f16 v[76:79], v[180:183], v[212:215], v[76:79]
	v_mfma_f32_16x16x32_f16 v[52:55], v[128:131], v[220:223], v[52:55]
	v_mfma_f32_16x16x32_f16 v[124:127], v[180:183], v[220:223], v[124:127]
	v_mfma_f32_16x16x32_f16 v[60:63], v[128:131], v[228:231], v[60:63]
	v_mfma_f32_16x16x32_f16 v[116:119], v[180:183], v[228:231], v[116:119]
	v_mfma_f32_16x16x32_f16 v[84:87], v[152:155], v[208:211], v[84:87]
	v_mfma_f32_16x16x32_f16 v[92:95], v[184:187], v[208:211], v[92:95]
	v_mfma_f32_16x16x32_f16 v[68:71], v[152:155], v[216:219], v[68:71]
	v_mfma_f32_16x16x32_f16 v[76:79], v[184:187], v[216:219], v[76:79]
	v_mfma_f32_16x16x32_f16 v[52:55], v[152:155], v[224:227], v[52:55]
	v_mfma_f32_16x16x32_f16 v[124:127], v[184:187], v[224:227], v[124:127]
	v_mfma_f32_16x16x32_f16 v[60:63], v[152:155], v[232:235], v[60:63]
	v_mfma_f32_16x16x32_f16 v[116:119], v[184:187], v[232:235], v[116:119]
	v_mfma_f32_16x16x32_f16 v[88:91], v[188:191], v[204:207], v[88:91]
	v_mfma_f32_16x16x32_f16 v[80:83], v[196:199], v[204:207], v[80:83]
	v_mfma_f32_16x16x32_f16 v[72:75], v[188:191], v[212:215], v[72:75]
	v_mfma_f32_16x16x32_f16 v[64:67], v[196:199], v[212:215], v[64:67]
	v_mfma_f32_16x16x32_f16 v[120:123], v[188:191], v[220:223], v[120:123]
	v_mfma_f32_16x16x32_f16 v[48:51], v[196:199], v[220:223], v[48:51]
	v_mfma_f32_16x16x32_f16 v[112:115], v[188:191], v[228:231], v[112:115]
	v_mfma_f32_16x16x32_f16 v[56:59], v[196:199], v[228:231], v[56:59]
	v_mfma_f32_16x16x32_f16 v[88:91], v[192:195], v[208:211], v[88:91]
	v_mfma_f32_16x16x32_f16 v[80:83], v[200:203], v[208:211], v[80:83]
	v_mfma_f32_16x16x32_f16 v[72:75], v[192:195], v[216:219], v[72:75]
	v_mfma_f32_16x16x32_f16 v[64:67], v[200:203], v[216:219], v[64:67]
	v_mfma_f32_16x16x32_f16 v[120:123], v[192:195], v[224:227], v[120:123]
	v_mfma_f32_16x16x32_f16 v[48:51], v[200:203], v[224:227], v[48:51]
	v_mfma_f32_16x16x32_f16 v[112:115], v[192:195], v[232:235], v[112:115]
	v_mfma_f32_16x16x32_f16 v[56:59], v[200:203], v[232:235], v[56:59]
	s_barrier
	s_add_i32 s0, s23, s88
	v_lshl_add_u64 v[156:157], s[10:11], 0, v[134:135]
	s_mov_b32 m0, s0
	ds_read_b128 v[204:207], v170 offset:16384
	ds_read_b128 v[208:211], v170 offset:17408
	ds_read_b128 v[212:215], v170 offset:18432
	ds_read_b128 v[216:219], v170 offset:19456
	ds_read_b128 v[220:223], v170 offset:20480
	ds_read_b128 v[224:227], v170 offset:21504
	ds_read_b128 v[228:231], v170 offset:22528
	ds_read_b128 v[232:235], v170 offset:23552
	global_load_lds_dwordx4 v[156:157], off
	s_add_i32 m0, s0, 0x2000
	s_add_u32 s0, s10, 0x40000
	v_lshl_add_u64 v[236:237], s[10:11], 0, v[138:139]
	s_addc_u32 s1, s11, 0
	s_add_i32 s17, s22, s88
	global_load_lds_dwordx4 v[236:237], off
	v_lshl_add_u64 v[238:239], s[0:1], 0, v[134:135]
	s_mov_b32 m0, s17
	v_lshl_add_u64 v[240:241], s[12:13], 0, v[136:137]
	global_load_lds_dwordx4 v[238:239], off
	v_lshl_add_u64 v[238:239], s[0:1], 0, v[138:139]
	s_add_i32 m0, s17, 0x2000
	s_nop 0
	global_load_lds_dwordx4 v[238:239], off
	v_lshl_add_u64 v[238:239], s[12:13], 0, v[132:133]
	s_mov_b32 m0, s89
	s_nop 0
	global_load_lds_dwordx4 v[238:239], off
	s_mov_b32 m0, s3
	s_nop 0
	global_load_lds_dwordx4 v[240:241], off
	s_waitcnt vmcnt(8)
	s_waitcnt lgkmcnt(0)
	s_barrier
	s_waitcnt lgkmcnt(0)
	v_mfma_f32_16x16x32_f16 v[36:39], v[128:131], v[204:207], v[36:39]
	v_mfma_f32_16x16x32_f16 v[44:47], v[180:183], v[204:207], v[44:47]
	v_mfma_f32_16x16x32_f16 v[20:23], v[128:131], v[212:215], v[20:23]
	v_mfma_f32_16x16x32_f16 v[32:35], v[180:183], v[212:215], v[32:35]
	v_mfma_f32_16x16x32_f16 v[4:7], v[128:131], v[220:223], v[4:7]
	v_mfma_f32_16x16x32_f16 v[108:111], v[180:183], v[220:223], v[108:111]
	v_mfma_f32_16x16x32_f16 v[12:15], v[128:131], v[228:231], v[12:15]
	v_mfma_f32_16x16x32_f16 v[100:103], v[180:183], v[228:231], v[100:103]
	v_mfma_f32_16x16x32_f16 v[36:39], v[152:155], v[208:211], v[36:39]
	v_mfma_f32_16x16x32_f16 v[44:47], v[184:187], v[208:211], v[44:47]
	v_mfma_f32_16x16x32_f16 v[20:23], v[152:155], v[216:219], v[20:23]
	v_mfma_f32_16x16x32_f16 v[32:35], v[184:187], v[216:219], v[32:35]
	v_mfma_f32_16x16x32_f16 v[4:7], v[152:155], v[224:227], v[4:7]
	v_mfma_f32_16x16x32_f16 v[108:111], v[184:187], v[224:227], v[108:111]
	v_mfma_f32_16x16x32_f16 v[12:15], v[152:155], v[232:235], v[12:15]
	v_mfma_f32_16x16x32_f16 v[100:103], v[184:187], v[232:235], v[100:103]
	v_mfma_f32_16x16x32_f16 v[40:43], v[188:191], v[204:207], v[40:43]
	v_mfma_f32_16x16x32_f16 v[28:31], v[196:199], v[204:207], v[28:31]
	v_mfma_f32_16x16x32_f16 v[24:27], v[188:191], v[212:215], v[24:27]
	v_mfma_f32_16x16x32_f16 v[16:19], v[196:199], v[212:215], v[16:19]
	v_mfma_f32_16x16x32_f16 v[104:107], v[188:191], v[220:223], v[104:107]
	v_mfma_f32_16x16x32_f16 v[0:3], v[196:199], v[220:223], v[0:3]
	v_mfma_f32_16x16x32_f16 v[96:99], v[188:191], v[228:231], v[96:99]
	v_mfma_f32_16x16x32_f16 v[8:11], v[196:199], v[228:231], v[8:11]
	v_mfma_f32_16x16x32_f16 v[40:43], v[192:195], v[208:211], v[40:43]
	v_mfma_f32_16x16x32_f16 v[28:31], v[200:203], v[208:211], v[28:31]
	v_mfma_f32_16x16x32_f16 v[24:27], v[192:195], v[216:219], v[24:27]
	v_mfma_f32_16x16x32_f16 v[16:19], v[200:203], v[216:219], v[16:19]
	v_mfma_f32_16x16x32_f16 v[104:107], v[192:195], v[224:227], v[104:107]
	v_mfma_f32_16x16x32_f16 v[0:3], v[200:203], v[224:227], v[0:3]
	v_mfma_f32_16x16x32_f16 v[96:99], v[192:195], v[232:235], v[96:99]
	v_mfma_f32_16x16x32_f16 v[8:11], v[200:203], v[232:235], v[8:11]
	s_barrier
	ds_read_b128 v[128:131], v171
	ds_read_b128 v[152:155], v171 offset:1024
	ds_read_b128 v[180:183], v171 offset:2048
	ds_read_b128 v[184:187], v171 offset:3072
	ds_read_b128 v[188:191], v172
	ds_read_b128 v[192:195], v172 offset:1024
	ds_read_b128 v[196:199], v172 offset:2048
	ds_read_b128 v[200:203], v172 offset:3072
	s_add_u32 s0, s12, 0x40000
	s_addc_u32 s1, s13, 0
	s_mov_b32 m0, s33
	v_lshl_add_u64 v[242:243], s[0:1], 0, v[132:133]
	ds_read_b128 v[204:207], v170 offset:32768
	ds_read_b128 v[208:211], v170 offset:33792
	ds_read_b128 v[212:215], v170 offset:34816
	ds_read_b128 v[216:219], v170 offset:35840
	ds_read_b128 v[220:223], v170 offset:36864
	ds_read_b128 v[224:227], v170 offset:37888
	ds_read_b128 v[228:231], v170 offset:38912
	ds_read_b128 v[232:235], v170 offset:39936
	global_load_lds_dwordx4 v[242:243], off
	v_lshl_add_u64 v[242:243], s[0:1], 0, v[136:137]
	s_mov_b32 m0, s50
	s_nop 0
	global_load_lds_dwordx4 v[242:243], off
	s_waitcnt vmcnt(8)
	s_waitcnt lgkmcnt(0)
	s_barrier
	s_waitcnt lgkmcnt(0)
	v_mfma_f32_16x16x32_f16 v[84:87], v[128:131], v[204:207], v[84:87]
	v_mfma_f32_16x16x32_f16 v[92:95], v[180:183], v[204:207], v[92:95]
	v_mfma_f32_16x16x32_f16 v[68:71], v[128:131], v[212:215], v[68:71]
	v_mfma_f32_16x16x32_f16 v[76:79], v[180:183], v[212:215], v[76:79]
	v_mfma_f32_16x16x32_f16 v[52:55], v[128:131], v[220:223], v[52:55]
	v_mfma_f32_16x16x32_f16 v[124:127], v[180:183], v[220:223], v[124:127]
	v_mfma_f32_16x16x32_f16 v[60:63], v[128:131], v[228:231], v[60:63]
	v_mfma_f32_16x16x32_f16 v[116:119], v[180:183], v[228:231], v[116:119]
	v_mfma_f32_16x16x32_f16 v[84:87], v[152:155], v[208:211], v[84:87]
	v_mfma_f32_16x16x32_f16 v[92:95], v[184:187], v[208:211], v[92:95]
	v_mfma_f32_16x16x32_f16 v[68:71], v[152:155], v[216:219], v[68:71]
	v_mfma_f32_16x16x32_f16 v[76:79], v[184:187], v[216:219], v[76:79]
	v_mfma_f32_16x16x32_f16 v[52:55], v[152:155], v[224:227], v[52:55]
	v_mfma_f32_16x16x32_f16 v[124:127], v[184:187], v[224:227], v[124:127]
	v_mfma_f32_16x16x32_f16 v[60:63], v[152:155], v[232:235], v[60:63]
	v_mfma_f32_16x16x32_f16 v[116:119], v[184:187], v[232:235], v[116:119]
	v_mfma_f32_16x16x32_f16 v[88:91], v[188:191], v[204:207], v[88:91]
	v_mfma_f32_16x16x32_f16 v[80:83], v[196:199], v[204:207], v[80:83]
	v_mfma_f32_16x16x32_f16 v[72:75], v[188:191], v[212:215], v[72:75]
	v_mfma_f32_16x16x32_f16 v[64:67], v[196:199], v[212:215], v[64:67]
	v_mfma_f32_16x16x32_f16 v[120:123], v[188:191], v[220:223], v[120:123]
	v_mfma_f32_16x16x32_f16 v[48:51], v[196:199], v[220:223], v[48:51]
	v_mfma_f32_16x16x32_f16 v[112:115], v[188:191], v[228:231], v[112:115]
	v_mfma_f32_16x16x32_f16 v[56:59], v[196:199], v[228:231], v[56:59]
	v_mfma_f32_16x16x32_f16 v[88:91], v[192:195], v[208:211], v[88:91]
	v_mfma_f32_16x16x32_f16 v[80:83], v[200:203], v[208:211], v[80:83]
	v_mfma_f32_16x16x32_f16 v[72:75], v[192:195], v[216:219], v[72:75]
	v_mfma_f32_16x16x32_f16 v[64:67], v[200:203], v[216:219], v[64:67]
	v_mfma_f32_16x16x32_f16 v[120:123], v[192:195], v[224:227], v[120:123]
	v_mfma_f32_16x16x32_f16 v[48:51], v[200:203], v[224:227], v[48:51]
	v_mfma_f32_16x16x32_f16 v[112:115], v[192:195], v[232:235], v[112:115]
	v_mfma_f32_16x16x32_f16 v[56:59], v[200:203], v[232:235], v[56:59]
	s_barrier
	s_add_i32 s0, s36, s88
	v_lshl_add_u64 v[156:157], v[156:157], 0, s[26:27]
	s_mov_b32 m0, s0
	ds_read_b128 v[204:207], v170 offset:49152
	ds_read_b128 v[208:211], v170 offset:50176
	ds_read_b128 v[212:215], v170 offset:51200
	ds_read_b128 v[216:219], v170 offset:52224
	ds_read_b128 v[220:223], v170 offset:53248
	ds_read_b128 v[224:227], v170 offset:54272
	ds_read_b128 v[228:231], v170 offset:55296
	ds_read_b128 v[232:235], v170 offset:56320
	global_load_lds_dwordx4 v[156:157], off
	s_add_i32 m0, s0, 0x2000
	s_add_u32 s0, s10, 0x40080
	v_lshl_add_u64 v[156:157], v[236:237], 0, s[26:27]
	s_addc_u32 s1, s11, 0
	s_add_i32 s10, s37, s88
	global_load_lds_dwordx4 v[156:157], off
	v_lshl_add_u64 v[156:157], s[0:1], 0, v[134:135]
	s_mov_b32 m0, s10
	s_nop 0
	global_load_lds_dwordx4 v[156:157], off
	v_lshl_add_u64 v[156:157], s[0:1], 0, v[138:139]
	s_add_i32 m0, s10, 0x2000
	s_nop 0
	global_load_lds_dwordx4 v[156:157], off
	v_lshl_add_u64 v[156:157], v[238:239], 0, s[26:27]
	s_mov_b32 m0, s51
	s_nop 0
	global_load_lds_dwordx4 v[156:157], off
	v_lshl_add_u64 v[156:157], v[240:241], 0, s[26:27]
	s_mov_b32 m0, s82
	s_nop 0
	global_load_lds_dwordx4 v[156:157], off
	s_waitcnt vmcnt(8)
	s_waitcnt lgkmcnt(0)
	s_barrier
	s_waitcnt lgkmcnt(0)
	v_mfma_f32_16x16x32_f16 v[36:39], v[128:131], v[204:207], v[36:39]
	v_mfma_f32_16x16x32_f16 v[44:47], v[180:183], v[204:207], v[44:47]
	v_mfma_f32_16x16x32_f16 v[20:23], v[128:131], v[212:215], v[20:23]
	v_mfma_f32_16x16x32_f16 v[32:35], v[180:183], v[212:215], v[32:35]
	v_mfma_f32_16x16x32_f16 v[4:7], v[128:131], v[220:223], v[4:7]
	v_mfma_f32_16x16x32_f16 v[108:111], v[180:183], v[220:223], v[108:111]
	v_mfma_f32_16x16x32_f16 v[12:15], v[128:131], v[228:231], v[12:15]
	v_mfma_f32_16x16x32_f16 v[100:103], v[180:183], v[228:231], v[100:103]
	v_mfma_f32_16x16x32_f16 v[36:39], v[152:155], v[208:211], v[36:39]
	v_mfma_f32_16x16x32_f16 v[44:47], v[184:187], v[208:211], v[44:47]
	v_mfma_f32_16x16x32_f16 v[20:23], v[152:155], v[216:219], v[20:23]
	v_mfma_f32_16x16x32_f16 v[32:35], v[184:187], v[216:219], v[32:35]
	v_mfma_f32_16x16x32_f16 v[4:7], v[152:155], v[224:227], v[4:7]
	v_mfma_f32_16x16x32_f16 v[108:111], v[184:187], v[224:227], v[108:111]
	v_mfma_f32_16x16x32_f16 v[12:15], v[152:155], v[232:235], v[12:15]
	v_mfma_f32_16x16x32_f16 v[100:103], v[184:187], v[232:235], v[100:103]
	v_mfma_f32_16x16x32_f16 v[40:43], v[188:191], v[204:207], v[40:43]
	v_mfma_f32_16x16x32_f16 v[28:31], v[196:199], v[204:207], v[28:31]
	v_mfma_f32_16x16x32_f16 v[24:27], v[188:191], v[212:215], v[24:27]
	v_mfma_f32_16x16x32_f16 v[16:19], v[196:199], v[212:215], v[16:19]
	v_mfma_f32_16x16x32_f16 v[104:107], v[188:191], v[220:223], v[104:107]
	v_mfma_f32_16x16x32_f16 v[0:3], v[196:199], v[220:223], v[0:3]
	v_mfma_f32_16x16x32_f16 v[96:99], v[188:191], v[228:231], v[96:99]
	v_mfma_f32_16x16x32_f16 v[8:11], v[196:199], v[228:231], v[8:11]
	v_mfma_f32_16x16x32_f16 v[40:43], v[192:195], v[208:211], v[40:43]
	v_mfma_f32_16x16x32_f16 v[28:31], v[200:203], v[208:211], v[28:31]
	v_mfma_f32_16x16x32_f16 v[24:27], v[192:195], v[216:219], v[24:27]
	v_mfma_f32_16x16x32_f16 v[16:19], v[200:203], v[216:219], v[16:19]
	v_mfma_f32_16x16x32_f16 v[104:107], v[192:195], v[224:227], v[104:107]
	v_mfma_f32_16x16x32_f16 v[0:3], v[200:203], v[224:227], v[0:3]
	v_mfma_f32_16x16x32_f16 v[96:99], v[192:195], v[232:235], v[96:99]
	v_mfma_f32_16x16x32_f16 v[8:11], v[200:203], v[232:235], v[8:11]
	s_barrier
	s_add_i32 s16, s16, 2
	s_add_u32 s14, s14, 0x100
	s_addc_u32 s15, s15, 0
	s_cmp_gt_u32 s16, 13
	s_mov_b64 s[0:1], s[4:5]
	s_cbranch_scc0 .LBB0_188
	s_and_b64 vcc, exec, s[72:73]
	s_cbranch_vccz .LBB0_191
	s_barrier

.LBB0_642:
	s_add_u32 s16, s40, s14
	s_addc_u32 s17, s41, s15
	s_add_u32 s16, s16, 0x13d00100
	s_addc_u32 s17, s17, 0
	s_add_u32 s47, s42, s14
	s_addc_u32 s48, s43, s15
	s_cmpk_eq_i32 s14, 0x700
	s_cselect_b32 s19, s11, s17
	s_cselect_b32 s18, s10, s16
	v_add_u32_e32 v147, s67, v145
	s_cselect_b32 s17, s13, s48
	s_cselect_b32 s16, s12, s47
	s_add_i32 s47, 0, 0x14000
	ds_read_b128 v[148:151], v147
	ds_read_b128 v[152:155], v147 offset:1024
	ds_read_b128 v[156:159], v147 offset:2048
	ds_read_b128 v[160:163], v147 offset:3072
	v_add_u32_e32 v147, s47, v145
	ds_read_b128 v[164:167], v147
	ds_read_b128 v[168:171], v147 offset:1024
	ds_read_b128 v[172:175], v147 offset:2048
	ds_read_b128 v[176:179], v147 offset:3072
	v_lshl_add_u64 v[212:213], v[136:137], 0, s[14:15]
	s_add_i32 m0, s30, 0xc000
	ds_read_b128 v[180:183], v146
	ds_read_b128 v[184:187], v146 offset:1024
	ds_read_b128 v[188:191], v146 offset:2048
	ds_read_b128 v[192:195], v146 offset:3072
	ds_read_b128 v[196:199], v146 offset:4096
	ds_read_b128 v[200:203], v146 offset:5120
	ds_read_b128 v[204:207], v146 offset:6144
	ds_read_b128 v[208:211], v146 offset:7168
	global_load_lds_dwordx4 v[212:213], off
	v_lshl_add_u64 v[212:213], v[138:139], 0, s[14:15]
	s_add_i32 m0, s30, 0xe000
	s_nop 0
	global_load_lds_dwordx4 v[212:213], off
	s_waitcnt vmcnt(8)
	s_waitcnt lgkmcnt(0)
	s_barrier
	s_waitcnt lgkmcnt(0)
	v_mfma_f32_16x16x32_f16 v[124:127], v[148:151], v[180:183], v[124:127]
	v_mfma_f32_16x16x32_f16 v[120:123], v[156:159], v[180:183], v[120:123]
	v_mfma_f32_16x16x32_f16 v[108:111], v[148:151], v[188:191], v[108:111]
	v_mfma_f32_16x16x32_f16 v[104:107], v[156:159], v[188:191], v[104:107]
	v_mfma_f32_16x16x32_f16 v[92:95], v[148:151], v[196:199], v[92:95]
	v_mfma_f32_16x16x32_f16 v[88:91], v[156:159], v[196:199], v[88:91]
	v_mfma_f32_16x16x32_f16 v[76:79], v[148:151], v[204:207], v[76:79]
	v_mfma_f32_16x16x32_f16 v[72:75], v[156:159], v[204:207], v[72:75]
	v_mfma_f32_16x16x32_f16 v[124:127], v[152:155], v[184:187], v[124:127]
	v_mfma_f32_16x16x32_f16 v[120:123], v[160:163], v[184:187], v[120:123]
	v_mfma_f32_16x16x32_f16 v[108:111], v[152:155], v[192:195], v[108:111]
	v_mfma_f32_16x16x32_f16 v[104:107], v[160:163], v[192:195], v[104:107]
	v_mfma_f32_16x16x32_f16 v[92:95], v[152:155], v[200:203], v[92:95]
	v_mfma_f32_16x16x32_f16 v[88:91], v[160:163], v[200:203], v[88:91]
	v_mfma_f32_16x16x32_f16 v[76:79], v[152:155], v[208:211], v[76:79]
	v_mfma_f32_16x16x32_f16 v[72:75], v[160:163], v[208:211], v[72:75]
	v_mfma_f32_16x16x32_f16 v[116:119], v[164:167], v[180:183], v[116:119]
	v_mfma_f32_16x16x32_f16 v[112:115], v[172:175], v[180:183], v[112:115]
	v_mfma_f32_16x16x32_f16 v[100:103], v[164:167], v[188:191], v[100:103]
	v_mfma_f32_16x16x32_f16 v[96:99], v[172:175], v[188:191], v[96:99]
	v_mfma_f32_16x16x32_f16 v[84:87], v[164:167], v[196:199], v[84:87]
	v_mfma_f32_16x16x32_f16 v[80:83], v[172:175], v[196:199], v[80:83]
	v_mfma_f32_16x16x32_f16 v[68:71], v[164:167], v[204:207], v[68:71]
	v_mfma_f32_16x16x32_f16 v[64:67], v[172:175], v[204:207], v[64:67]
	v_mfma_f32_16x16x32_f16 v[116:119], v[168:171], v[184:187], v[116:119]
	v_mfma_f32_16x16x32_f16 v[112:115], v[176:179], v[184:187], v[112:115]
	v_mfma_f32_16x16x32_f16 v[100:103], v[168:171], v[192:195], v[100:103]
	v_mfma_f32_16x16x32_f16 v[96:99], v[176:179], v[192:195], v[96:99]
	v_mfma_f32_16x16x32_f16 v[84:87], v[168:171], v[200:203], v[84:87]
	v_mfma_f32_16x16x32_f16 v[80:83], v[176:179], v[200:203], v[80:83]
	v_mfma_f32_16x16x32_f16 v[68:71], v[168:171], v[208:211], v[68:71]
	v_mfma_f32_16x16x32_f16 v[64:67], v[176:179], v[208:211], v[64:67]
	s_barrier
	s_add_i32 s48, s67, s66
	v_lshl_add_u64 v[212:213], s[16:17], 0, v[128:129]
	s_mov_b32 m0, s48
	ds_read_b128 v[180:183], v146 offset:16384
	ds_read_b128 v[184:187], v146 offset:17408
	ds_read_b128 v[188:191], v146 offset:18432
	ds_read_b128 v[192:195], v146 offset:19456
	ds_read_b128 v[196:199], v146 offset:20480
	ds_read_b128 v[200:203], v146 offset:21504
	ds_read_b128 v[204:207], v146 offset:22528
	ds_read_b128 v[208:211], v146 offset:23552
	global_load_lds_dwordx4 v[212:213], off
	s_add_i32 m0, s48, 0x2000
	s_add_u32 s48, s16, 0x40000
	v_lshl_add_u64 v[214:215], s[16:17], 0, v[134:135]
	s_addc_u32 s49, s17, 0
	s_add_i32 s47, s47, s66
	global_load_lds_dwordx4 v[214:215], off
	v_lshl_add_u64 v[216:217], s[48:49], 0, v[128:129]
	s_mov_b32 m0, s47
	v_lshl_add_u64 v[218:219], s[18:19], 0, v[132:133]
	global_load_lds_dwordx4 v[216:217], off
	v_lshl_add_u64 v[216:217], s[48:49], 0, v[134:135]
	s_add_i32 m0, s47, 0x2000
	s_nop 0
	global_load_lds_dwordx4 v[216:217], off
	v_lshl_add_u64 v[216:217], s[18:19], 0, v[130:131]
	s_mov_b32 m0, s30
	s_nop 0
	global_load_lds_dwordx4 v[216:217], off
	s_mov_b32 m0, s31
	s_nop 0
	global_load_lds_dwordx4 v[218:219], off
	s_waitcnt vmcnt(8)
	s_waitcnt lgkmcnt(0)
	s_barrier
	s_waitcnt lgkmcnt(0)
	v_mfma_f32_16x16x32_f16 v[60:63], v[148:151], v[180:183], v[60:63]
	v_mfma_f32_16x16x32_f16 v[56:59], v[156:159], v[180:183], v[56:59]
	v_mfma_f32_16x16x32_f16 v[44:47], v[148:151], v[188:191], v[44:47]
	v_mfma_f32_16x16x32_f16 v[40:43], v[156:159], v[188:191], v[40:43]
	v_mfma_f32_16x16x32_f16 v[28:31], v[148:151], v[196:199], v[28:31]
	v_mfma_f32_16x16x32_f16 v[24:27], v[156:159], v[196:199], v[24:27]
	v_mfma_f32_16x16x32_f16 v[12:15], v[148:151], v[204:207], v[12:15]
	v_mfma_f32_16x16x32_f16 v[8:11], v[156:159], v[204:207], v[8:11]
	v_mfma_f32_16x16x32_f16 v[60:63], v[152:155], v[184:187], v[60:63]
	v_mfma_f32_16x16x32_f16 v[56:59], v[160:163], v[184:187], v[56:59]
	v_mfma_f32_16x16x32_f16 v[44:47], v[152:155], v[192:195], v[44:47]
	v_mfma_f32_16x16x32_f16 v[40:43], v[160:163], v[192:195], v[40:43]
	v_mfma_f32_16x16x32_f16 v[28:31], v[152:155], v[200:203], v[28:31]
	v_mfma_f32_16x16x32_f16 v[24:27], v[160:163], v[200:203], v[24:27]
	v_mfma_f32_16x16x32_f16 v[12:15], v[152:155], v[208:211], v[12:15]
	v_mfma_f32_16x16x32_f16 v[8:11], v[160:163], v[208:211], v[8:11]
	v_mfma_f32_16x16x32_f16 v[52:55], v[164:167], v[180:183], v[52:55]
	v_mfma_f32_16x16x32_f16 v[48:51], v[172:175], v[180:183], v[48:51]
	v_mfma_f32_16x16x32_f16 v[36:39], v[164:167], v[188:191], v[36:39]
	v_mfma_f32_16x16x32_f16 v[32:35], v[172:175], v[188:191], v[32:35]
	v_mfma_f32_16x16x32_f16 v[20:23], v[164:167], v[196:199], v[20:23]
	v_mfma_f32_16x16x32_f16 v[16:19], v[172:175], v[196:199], v[16:19]
	v_mfma_f32_16x16x32_f16 v[4:7], v[164:167], v[204:207], v[4:7]
	v_mfma_f32_16x16x32_f16 v[0:3], v[172:175], v[204:207], v[0:3]
	v_mfma_f32_16x16x32_f16 v[52:55], v[168:171], v[184:187], v[52:55]
	v_mfma_f32_16x16x32_f16 v[48:51], v[176:179], v[184:187], v[48:51]
	v_mfma_f32_16x16x32_f16 v[36:39], v[168:171], v[192:195], v[36:39]
	v_mfma_f32_16x16x32_f16 v[32:35], v[176:179], v[192:195], v[32:35]
	v_mfma_f32_16x16x32_f16 v[20:23], v[168:171], v[200:203], v[20:23]
	v_mfma_f32_16x16x32_f16 v[16:19], v[176:179], v[200:203], v[16:19]
	v_mfma_f32_16x16x32_f16 v[4:7], v[168:171], v[208:211], v[4:7]
	v_mfma_f32_16x16x32_f16 v[0:3], v[176:179], v[208:211], v[0:3]
	s_barrier
	s_add_i32 s47, 0, 0x18000
	v_add_u32_e32 v147, s47, v145
	s_add_i32 s48, 0, 0x1c000
	ds_read_b128 v[148:151], v147
	ds_read_b128 v[152:155], v147 offset:1024
	ds_read_b128 v[156:159], v147 offset:2048
	ds_read_b128 v[160:163], v147 offset:3072
	v_add_u32_e32 v147, s48, v145
	ds_read_b128 v[164:167], v147
	ds_read_b128 v[168:171], v147 offset:1024
	ds_read_b128 v[172:175], v147 offset:2048
	ds_read_b128 v[176:179], v147 offset:3072
	s_add_u32 s18, s18, 0x40000
	s_addc_u32 s19, s19, 0
	s_mov_b32 m0, s34
	v_lshl_add_u64 v[220:221], s[18:19], 0, v[130:131]
	ds_read_b128 v[180:183], v146 offset:32768
	ds_read_b128 v[184:187], v146 offset:33792
	ds_read_b128 v[188:191], v146 offset:34816
	ds_read_b128 v[192:195], v146 offset:35840
	ds_read_b128 v[196:199], v146 offset:36864
	ds_read_b128 v[200:203], v146 offset:37888
	ds_read_b128 v[204:207], v146 offset:38912
	ds_read_b128 v[208:211], v146 offset:39936
	global_load_lds_dwordx4 v[220:221], off
	v_lshl_add_u64 v[220:221], s[18:19], 0, v[132:133]
	s_mov_b32 m0, s35
	s_nop 0
	global_load_lds_dwordx4 v[220:221], off
	s_waitcnt vmcnt(8)
	s_waitcnt lgkmcnt(0)
	s_barrier
	s_waitcnt lgkmcnt(0)
	v_mfma_f32_16x16x32_f16 v[124:127], v[148:151], v[180:183], v[124:127]
	v_mfma_f32_16x16x32_f16 v[120:123], v[156:159], v[180:183], v[120:123]
	v_mfma_f32_16x16x32_f16 v[108:111], v[148:151], v[188:191], v[108:111]
	v_mfma_f32_16x16x32_f16 v[104:107], v[156:159], v[188:191], v[104:107]
	v_mfma_f32_16x16x32_f16 v[92:95], v[148:151], v[196:199], v[92:95]
	v_mfma_f32_16x16x32_f16 v[88:91], v[156:159], v[196:199], v[88:91]
	v_mfma_f32_16x16x32_f16 v[76:79], v[148:151], v[204:207], v[76:79]
	v_mfma_f32_16x16x32_f16 v[72:75], v[156:159], v[204:207], v[72:75]
	v_mfma_f32_16x16x32_f16 v[124:127], v[152:155], v[184:187], v[124:127]
	v_mfma_f32_16x16x32_f16 v[120:123], v[160:163], v[184:187], v[120:123]
	v_mfma_f32_16x16x32_f16 v[108:111], v[152:155], v[192:195], v[108:111]
	v_mfma_f32_16x16x32_f16 v[104:107], v[160:163], v[192:195], v[104:107]
	v_mfma_f32_16x16x32_f16 v[92:95], v[152:155], v[200:203], v[92:95]
	v_mfma_f32_16x16x32_f16 v[88:91], v[160:163], v[200:203], v[88:91]
	v_mfma_f32_16x16x32_f16 v[76:79], v[152:155], v[208:211], v[76:79]
	v_mfma_f32_16x16x32_f16 v[72:75], v[160:163], v[208:211], v[72:75]
	v_mfma_f32_16x16x32_f16 v[116:119], v[164:167], v[180:183], v[116:119]
	v_mfma_f32_16x16x32_f16 v[112:115], v[172:175], v[180:183], v[112:115]
	v_mfma_f32_16x16x32_f16 v[100:103], v[164:167], v[188:191], v[100:103]
	v_mfma_f32_16x16x32_f16 v[96:99], v[172:175], v[188:191], v[96:99]
	v_mfma_f32_16x16x32_f16 v[84:87], v[164:167], v[196:199], v[84:87]
	v_mfma_f32_16x16x32_f16 v[80:83], v[172:175], v[196:199], v[80:83]
	v_mfma_f32_16x16x32_f16 v[68:71], v[164:167], v[204:207], v[68:71]
	v_mfma_f32_16x16x32_f16 v[64:67], v[172:175], v[204:207], v[64:67]
	v_mfma_f32_16x16x32_f16 v[116:119], v[168:171], v[184:187], v[116:119]
	v_mfma_f32_16x16x32_f16 v[112:115], v[176:179], v[184:187], v[112:115]
	v_mfma_f32_16x16x32_f16 v[100:103], v[168:171], v[192:195], v[100:103]
	v_mfma_f32_16x16x32_f16 v[96:99], v[176:179], v[192:195], v[96:99]
	v_mfma_f32_16x16x32_f16 v[84:87], v[168:171], v[200:203], v[84:87]
	v_mfma_f32_16x16x32_f16 v[80:83], v[176:179], v[200:203], v[80:83]
	v_mfma_f32_16x16x32_f16 v[68:71], v[168:171], v[208:211], v[68:71]
	v_mfma_f32_16x16x32_f16 v[64:67], v[176:179], v[208:211], v[64:67]
	s_barrier
	s_add_i32 s18, s47, s66
	v_lshl_add_u64 v[212:213], v[212:213], 0, s[6:7]
	s_mov_b32 m0, s18
	ds_read_b128 v[180:183], v146 offset:49152
	ds_read_b128 v[184:187], v146 offset:50176
	ds_read_b128 v[188:191], v146 offset:51200
	ds_read_b128 v[192:195], v146 offset:52224
	ds_read_b128 v[196:199], v146 offset:53248
	ds_read_b128 v[200:203], v146 offset:54272
	ds_read_b128 v[204:207], v146 offset:55296
	ds_read_b128 v[208:211], v146 offset:56320
	global_load_lds_dwordx4 v[212:213], off
	s_add_i32 m0, s18, 0x2000
	s_add_u32 s16, s16, 0x40080
	v_lshl_add_u64 v[212:213], v[214:215], 0, s[6:7]
	s_addc_u32 s17, s17, 0
	s_add_i32 s18, s48, s66
	global_load_lds_dwordx4 v[212:213], off
	v_lshl_add_u64 v[212:213], s[16:17], 0, v[128:129]
	s_mov_b32 m0, s18
	s_nop 0
	global_load_lds_dwordx4 v[212:213], off
	v_lshl_add_u64 v[212:213], s[16:17], 0, v[134:135]
	s_add_i32 m0, s18, 0x2000
	s_nop 0
	global_load_lds_dwordx4 v[212:213], off
	v_lshl_add_u64 v[212:213], v[216:217], 0, s[6:7]
	s_mov_b32 m0, s38
	s_nop 0
	global_load_lds_dwordx4 v[212:213], off
	v_lshl_add_u64 v[212:213], v[218:219], 0, s[6:7]
	s_mov_b32 m0, s39
	s_nop 0
	global_load_lds_dwordx4 v[212:213], off
	s_waitcnt vmcnt(8)
	s_waitcnt lgkmcnt(0)
	s_barrier
	s_waitcnt lgkmcnt(0)
	v_mfma_f32_16x16x32_f16 v[60:63], v[148:151], v[180:183], v[60:63]
	v_mfma_f32_16x16x32_f16 v[56:59], v[156:159], v[180:183], v[56:59]
	v_mfma_f32_16x16x32_f16 v[44:47], v[148:151], v[188:191], v[44:47]
	v_mfma_f32_16x16x32_f16 v[40:43], v[156:159], v[188:191], v[40:43]
	v_mfma_f32_16x16x32_f16 v[28:31], v[148:151], v[196:199], v[28:31]
	v_mfma_f32_16x16x32_f16 v[24:27], v[156:159], v[196:199], v[24:27]
	v_mfma_f32_16x16x32_f16 v[12:15], v[148:151], v[204:207], v[12:15]
	v_mfma_f32_16x16x32_f16 v[8:11], v[156:159], v[204:207], v[8:11]
	v_mfma_f32_16x16x32_f16 v[60:63], v[152:155], v[184:187], v[60:63]
	v_mfma_f32_16x16x32_f16 v[56:59], v[160:163], v[184:187], v[56:59]
	v_mfma_f32_16x16x32_f16 v[44:47], v[152:155], v[192:195], v[44:47]
	v_mfma_f32_16x16x32_f16 v[40:43], v[160:163], v[192:195], v[40:43]
	v_mfma_f32_16x16x32_f16 v[28:31], v[152:155], v[200:203], v[28:31]
	v_mfma_f32_16x16x32_f16 v[24:27], v[160:163], v[200:203], v[24:27]
	v_mfma_f32_16x16x32_f16 v[12:15], v[152:155], v[208:211], v[12:15]
	v_mfma_f32_16x16x32_f16 v[8:11], v[160:163], v[208:211], v[8:11]
	v_mfma_f32_16x16x32_f16 v[52:55], v[164:167], v[180:183], v[52:55]
	v_mfma_f32_16x16x32_f16 v[48:51], v[172:175], v[180:183], v[48:51]
	v_mfma_f32_16x16x32_f16 v[36:39], v[164:167], v[188:191], v[36:39]
	v_mfma_f32_16x16x32_f16 v[32:35], v[172:175], v[188:191], v[32:35]
	v_mfma_f32_16x16x32_f16 v[20:23], v[164:167], v[196:199], v[20:23]
	v_mfma_f32_16x16x32_f16 v[16:19], v[172:175], v[196:199], v[16:19]
	v_mfma_f32_16x16x32_f16 v[4:7], v[164:167], v[204:207], v[4:7]
	v_mfma_f32_16x16x32_f16 v[0:3], v[172:175], v[204:207], v[0:3]
	v_mfma_f32_16x16x32_f16 v[52:55], v[168:171], v[184:187], v[52:55]
	v_mfma_f32_16x16x32_f16 v[48:51], v[176:179], v[184:187], v[48:51]
	v_mfma_f32_16x16x32_f16 v[36:39], v[168:171], v[192:195], v[36:39]
	v_mfma_f32_16x16x32_f16 v[32:35], v[176:179], v[192:195], v[32:35]
	v_mfma_f32_16x16x32_f16 v[20:23], v[168:171], v[200:203], v[20:23]
	v_mfma_f32_16x16x32_f16 v[16:19], v[176:179], v[200:203], v[16:19]
	v_mfma_f32_16x16x32_f16 v[4:7], v[168:171], v[208:211], v[4:7]
	v_mfma_f32_16x16x32_f16 v[0:3], v[176:179], v[208:211], v[0:3]
	s_barrier
	s_add_i32 s46, s46, 2
	s_add_u32 s14, s14, 0x100
	s_addc_u32 s15, s15, 0
	s_cmp_gt_u32 s46, 13
	s_cbranch_scc0 .LBB0_642
	s_and_b64 vcc, exec, s[26:27]
	s_cbranch_vccz .LBB0_645
	s_barrier

.LBB0_732:
	ds_read_b128 v[158:161], v156
	ds_read_b128 v[162:165], v156 offset:1024
	ds_read_b128 v[166:169], v156 offset:2048
	ds_read_b128 v[170:173], v156 offset:3072
	ds_read_b128 v[174:177], v153
	ds_read_b128 v[178:181], v153 offset:1024
	ds_read_b128 v[182:185], v153 offset:2048
	ds_read_b128 v[186:189], v153 offset:3072
	s_add_u32 s18, s4, 0xfffc0080
	s_addc_u32 s19, s5, -1
	s_cmp_eq_u32 s28, 12
	s_cselect_b32 s21, s15, s19
	s_cselect_b32 s20, s14, s18
	s_cselect_b32 s19, s17, s8
	s_cselect_b32 s18, s16, s3
	s_mov_b32 m0, s85
	v_lshl_add_u64 v[142:143], s[4:5], 0, v[138:139]
	ds_read_b128 v[190:193], v154
	ds_read_b128 v[194:197], v154 offset:1024
	ds_read_b128 v[198:201], v154 offset:2048
	ds_read_b128 v[202:205], v154 offset:3072
	ds_read_b128 v[206:209], v154 offset:4096
	ds_read_b128 v[210:213], v154 offset:5120
	ds_read_b128 v[214:217], v154 offset:6144
	ds_read_b128 v[218:221], v154 offset:7168
	global_load_lds_dwordx4 v[142:143], off
	v_lshl_add_u64 v[142:143], s[4:5], 0, v[140:141]
	s_mov_b32 m0, s84
	s_nop 0
	global_load_lds_dwordx4 v[142:143], off
	s_waitcnt vmcnt(8)
	s_waitcnt lgkmcnt(0)
	s_barrier
	s_waitcnt lgkmcnt(0)
	v_mfma_f32_16x16x32_f16 v[124:127], v[158:161], v[190:193], v[124:127]
	v_mfma_f32_16x16x32_f16 v[120:123], v[166:169], v[190:193], v[120:123]
	v_mfma_f32_16x16x32_f16 v[108:111], v[158:161], v[198:201], v[108:111]
	v_mfma_f32_16x16x32_f16 v[104:107], v[166:169], v[198:201], v[104:107]
	v_mfma_f32_16x16x32_f16 v[92:95], v[158:161], v[206:209], v[92:95]
	v_mfma_f32_16x16x32_f16 v[88:91], v[166:169], v[206:209], v[88:91]
	v_mfma_f32_16x16x32_f16 v[76:79], v[158:161], v[214:217], v[76:79]
	v_mfma_f32_16x16x32_f16 v[72:75], v[166:169], v[214:217], v[72:75]
	v_mfma_f32_16x16x32_f16 v[124:127], v[162:165], v[194:197], v[124:127]
	v_mfma_f32_16x16x32_f16 v[120:123], v[170:173], v[194:197], v[120:123]
	v_mfma_f32_16x16x32_f16 v[108:111], v[162:165], v[202:205], v[108:111]
	v_mfma_f32_16x16x32_f16 v[104:107], v[170:173], v[202:205], v[104:107]
	v_mfma_f32_16x16x32_f16 v[92:95], v[162:165], v[210:213], v[92:95]
	v_mfma_f32_16x16x32_f16 v[88:91], v[170:173], v[210:213], v[88:91]
	v_mfma_f32_16x16x32_f16 v[76:79], v[162:165], v[218:221], v[76:79]
	v_mfma_f32_16x16x32_f16 v[72:75], v[170:173], v[218:221], v[72:75]
	v_mfma_f32_16x16x32_f16 v[116:119], v[174:177], v[190:193], v[116:119]
	v_mfma_f32_16x16x32_f16 v[112:115], v[182:185], v[190:193], v[112:115]
	v_mfma_f32_16x16x32_f16 v[100:103], v[174:177], v[198:201], v[100:103]
	v_mfma_f32_16x16x32_f16 v[96:99], v[182:185], v[198:201], v[96:99]
	v_mfma_f32_16x16x32_f16 v[84:87], v[174:177], v[206:209], v[84:87]
	v_mfma_f32_16x16x32_f16 v[80:83], v[182:185], v[206:209], v[80:83]
	v_mfma_f32_16x16x32_f16 v[68:71], v[174:177], v[214:217], v[68:71]
	v_mfma_f32_16x16x32_f16 v[64:67], v[182:185], v[214:217], v[64:67]
	v_mfma_f32_16x16x32_f16 v[116:119], v[178:181], v[194:197], v[116:119]
	v_mfma_f32_16x16x32_f16 v[112:115], v[186:189], v[194:197], v[112:115]
	v_mfma_f32_16x16x32_f16 v[100:103], v[178:181], v[202:205], v[100:103]
	v_mfma_f32_16x16x32_f16 v[96:99], v[186:189], v[202:205], v[96:99]
	v_mfma_f32_16x16x32_f16 v[84:87], v[178:181], v[210:213], v[84:87]
	v_mfma_f32_16x16x32_f16 v[80:83], v[186:189], v[210:213], v[80:83]
	v_mfma_f32_16x16x32_f16 v[68:71], v[178:181], v[218:221], v[68:71]
	v_mfma_f32_16x16x32_f16 v[64:67], v[186:189], v[218:221], v[64:67]
	s_barrier
	s_mov_b32 m0, s83
	v_lshl_add_u64 v[142:143], s[18:19], 0, v[130:131]
	s_add_u32 vcc_lo, s18, 0x40000
	ds_read_b128 v[190:193], v154 offset:16384
	ds_read_b128 v[194:197], v154 offset:17408
	ds_read_b128 v[198:201], v154 offset:18432
	ds_read_b128 v[202:205], v154 offset:19456
	ds_read_b128 v[206:209], v154 offset:20480
	ds_read_b128 v[210:213], v154 offset:21504
	ds_read_b128 v[214:217], v154 offset:22528
	ds_read_b128 v[218:221], v154 offset:23552
	global_load_lds_dwordx4 v[142:143], off
	v_lshl_add_u64 v[222:223], s[18:19], 0, v[134:135]
	s_mov_b32 m0, s82
	s_addc_u32 vcc_hi, s19, 0
	global_load_lds_dwordx4 v[222:223], off
	v_lshl_add_u64 v[224:225], vcc, 0, v[130:131]
	s_mov_b32 m0, s81
	v_lshl_add_u64 v[226:227], s[20:21], 0, v[132:133]
	global_load_lds_dwordx4 v[224:225], off
	v_lshl_add_u64 v[224:225], vcc, 0, v[134:135]
	s_mov_b32 m0, s80
	s_nop 0
	global_load_lds_dwordx4 v[224:225], off
	v_lshl_add_u64 v[224:225], s[20:21], 0, v[128:129]
	s_mov_b32 m0, s61
	s_nop 0
	global_load_lds_dwordx4 v[224:225], off
	s_mov_b32 m0, s71
	s_nop 0
	global_load_lds_dwordx4 v[226:227], off
	s_waitcnt vmcnt(8)
	s_waitcnt lgkmcnt(0)
	s_barrier
	s_waitcnt lgkmcnt(0)
	v_mfma_f32_16x16x32_f16 v[60:63], v[158:161], v[190:193], v[60:63]
	v_mfma_f32_16x16x32_f16 v[56:59], v[166:169], v[190:193], v[56:59]
	v_mfma_f32_16x16x32_f16 v[44:47], v[158:161], v[198:201], v[44:47]
	v_mfma_f32_16x16x32_f16 v[40:43], v[166:169], v[198:201], v[40:43]
	v_mfma_f32_16x16x32_f16 v[28:31], v[158:161], v[206:209], v[28:31]
	v_mfma_f32_16x16x32_f16 v[24:27], v[166:169], v[206:209], v[24:27]
	v_mfma_f32_16x16x32_f16 v[12:15], v[158:161], v[214:217], v[12:15]
	v_mfma_f32_16x16x32_f16 v[8:11], v[166:169], v[214:217], v[8:11]
	v_mfma_f32_16x16x32_f16 v[60:63], v[162:165], v[194:197], v[60:63]
	v_mfma_f32_16x16x32_f16 v[56:59], v[170:173], v[194:197], v[56:59]
	v_mfma_f32_16x16x32_f16 v[44:47], v[162:165], v[202:205], v[44:47]
	v_mfma_f32_16x16x32_f16 v[40:43], v[170:173], v[202:205], v[40:43]
	v_mfma_f32_16x16x32_f16 v[28:31], v[162:165], v[210:213], v[28:31]
	v_mfma_f32_16x16x32_f16 v[24:27], v[170:173], v[210:213], v[24:27]
	v_mfma_f32_16x16x32_f16 v[12:15], v[162:165], v[218:221], v[12:15]
	v_mfma_f32_16x16x32_f16 v[8:11], v[170:173], v[218:221], v[8:11]
	v_mfma_f32_16x16x32_f16 v[52:55], v[174:177], v[190:193], v[52:55]
	v_mfma_f32_16x16x32_f16 v[48:51], v[182:185], v[190:193], v[48:51]
	v_mfma_f32_16x16x32_f16 v[36:39], v[174:177], v[198:201], v[36:39]
	v_mfma_f32_16x16x32_f16 v[32:35], v[182:185], v[198:201], v[32:35]
	v_mfma_f32_16x16x32_f16 v[20:23], v[174:177], v[206:209], v[20:23]
	v_mfma_f32_16x16x32_f16 v[16:19], v[182:185], v[206:209], v[16:19]
	v_mfma_f32_16x16x32_f16 v[4:7], v[174:177], v[214:217], v[4:7]
	v_mfma_f32_16x16x32_f16 v[0:3], v[182:185], v[214:217], v[0:3]
	v_mfma_f32_16x16x32_f16 v[52:55], v[178:181], v[194:197], v[52:55]
	v_mfma_f32_16x16x32_f16 v[48:51], v[186:189], v[194:197], v[48:51]
	v_mfma_f32_16x16x32_f16 v[36:39], v[178:181], v[202:205], v[36:39]
	v_mfma_f32_16x16x32_f16 v[32:35], v[186:189], v[202:205], v[32:35]
	v_mfma_f32_16x16x32_f16 v[20:23], v[178:181], v[210:213], v[20:23]
	v_mfma_f32_16x16x32_f16 v[16:19], v[186:189], v[210:213], v[16:19]
	v_mfma_f32_16x16x32_f16 v[4:7], v[178:181], v[218:221], v[4:7]
	v_mfma_f32_16x16x32_f16 v[0:3], v[186:189], v[218:221], v[0:3]
	s_barrier
	ds_read_b128 v[158:161], v157
	ds_read_b128 v[162:165], v157 offset:1024
	ds_read_b128 v[166:169], v157 offset:2048
	ds_read_b128 v[170:173], v157 offset:3072
	ds_read_b128 v[174:177], v155
	ds_read_b128 v[178:181], v155 offset:1024
	ds_read_b128 v[182:185], v155 offset:2048
	ds_read_b128 v[186:189], v155 offset:3072
	s_add_u32 s20, s20, 0x40000
	s_addc_u32 s21, s21, 0
	s_mov_b32 m0, s47
	v_lshl_add_u64 v[228:229], s[20:21], 0, v[128:129]
	ds_read_b128 v[190:193], v154 offset:32768
	ds_read_b128 v[194:197], v154 offset:33792
	ds_read_b128 v[198:201], v154 offset:34816
	ds_read_b128 v[202:205], v154 offset:35840
	ds_read_b128 v[206:209], v154 offset:36864
	ds_read_b128 v[210:213], v154 offset:37888
	ds_read_b128 v[214:217], v154 offset:38912
	ds_read_b128 v[218:221], v154 offset:39936
	global_load_lds_dwordx4 v[228:229], off
	v_lshl_add_u64 v[228:229], s[20:21], 0, v[132:133]
	s_mov_b32 m0, s58
	s_nop 0
	global_load_lds_dwordx4 v[228:229], off
	s_waitcnt vmcnt(8)
	s_waitcnt lgkmcnt(0)
	s_barrier
	s_waitcnt lgkmcnt(0)
	v_mfma_f32_16x16x32_f16 v[124:127], v[158:161], v[190:193], v[124:127]
	v_mfma_f32_16x16x32_f16 v[120:123], v[166:169], v[190:193], v[120:123]
	v_mfma_f32_16x16x32_f16 v[108:111], v[158:161], v[198:201], v[108:111]
	v_mfma_f32_16x16x32_f16 v[104:107], v[166:169], v[198:201], v[104:107]
	v_mfma_f32_16x16x32_f16 v[92:95], v[158:161], v[206:209], v[92:95]
	v_mfma_f32_16x16x32_f16 v[88:91], v[166:169], v[206:209], v[88:91]
	v_mfma_f32_16x16x32_f16 v[76:79], v[158:161], v[214:217], v[76:79]
	v_mfma_f32_16x16x32_f16 v[72:75], v[166:169], v[214:217], v[72:75]
	v_mfma_f32_16x16x32_f16 v[124:127], v[162:165], v[194:197], v[124:127]
	v_mfma_f32_16x16x32_f16 v[120:123], v[170:173], v[194:197], v[120:123]
	v_mfma_f32_16x16x32_f16 v[108:111], v[162:165], v[202:205], v[108:111]
	v_mfma_f32_16x16x32_f16 v[104:107], v[170:173], v[202:205], v[104:107]
	v_mfma_f32_16x16x32_f16 v[92:95], v[162:165], v[210:213], v[92:95]
	v_mfma_f32_16x16x32_f16 v[88:91], v[170:173], v[210:213], v[88:91]
	v_mfma_f32_16x16x32_f16 v[76:79], v[162:165], v[218:221], v[76:79]
	v_mfma_f32_16x16x32_f16 v[72:75], v[170:173], v[218:221], v[72:75]
	v_mfma_f32_16x16x32_f16 v[116:119], v[174:177], v[190:193], v[116:119]
	v_mfma_f32_16x16x32_f16 v[112:115], v[182:185], v[190:193], v[112:115]
	v_mfma_f32_16x16x32_f16 v[100:103], v[174:177], v[198:201], v[100:103]
	v_mfma_f32_16x16x32_f16 v[96:99], v[182:185], v[198:201], v[96:99]
	v_mfma_f32_16x16x32_f16 v[84:87], v[174:177], v[206:209], v[84:87]
	v_mfma_f32_16x16x32_f16 v[80:83], v[182:185], v[206:209], v[80:83]
	v_mfma_f32_16x16x32_f16 v[68:71], v[174:177], v[214:217], v[68:71]
	v_mfma_f32_16x16x32_f16 v[64:67], v[182:185], v[214:217], v[64:67]
	v_mfma_f32_16x16x32_f16 v[116:119], v[178:181], v[194:197], v[116:119]
	v_mfma_f32_16x16x32_f16 v[112:115], v[186:189], v[194:197], v[112:115]
	v_mfma_f32_16x16x32_f16 v[100:103], v[178:181], v[202:205], v[100:103]
	v_mfma_f32_16x16x32_f16 v[96:99], v[186:189], v[202:205], v[96:99]
	v_mfma_f32_16x16x32_f16 v[84:87], v[178:181], v[210:213], v[84:87]
	v_mfma_f32_16x16x32_f16 v[80:83], v[186:189], v[210:213], v[80:83]
	v_mfma_f32_16x16x32_f16 v[68:71], v[178:181], v[218:221], v[68:71]
	v_mfma_f32_16x16x32_f16 v[64:67], v[186:189], v[218:221], v[64:67]
	s_barrier
	s_mov_b32 m0, s70
	v_lshl_add_u64 v[142:143], v[142:143], 0, s[6:7]
	s_add_u32 s18, s18, 0x40080
	ds_read_b128 v[190:193], v154 offset:49152
	ds_read_b128 v[194:197], v154 offset:50176
	ds_read_b128 v[198:201], v154 offset:51200
	ds_read_b128 v[202:205], v154 offset:52224
	ds_read_b128 v[206:209], v154 offset:53248
	ds_read_b128 v[210:213], v154 offset:54272
	ds_read_b128 v[214:217], v154 offset:55296
	ds_read_b128 v[218:221], v154 offset:56320
	global_load_lds_dwordx4 v[142:143], off
	v_lshl_add_u64 v[142:143], v[222:223], 0, s[6:7]
	s_mov_b32 m0, s63
	s_addc_u32 s19, s19, 0
	global_load_lds_dwordx4 v[142:143], off
	v_lshl_add_u64 v[142:143], s[18:19], 0, v[130:131]
	s_mov_b32 m0, s62
	s_nop 0
	global_load_lds_dwordx4 v[142:143], off
	v_lshl_add_u64 v[142:143], s[18:19], 0, v[134:135]
	s_mov_b32 m0, s59
	s_nop 0
	global_load_lds_dwordx4 v[142:143], off
	v_lshl_add_u64 v[142:143], v[224:225], 0, s[6:7]
	s_mov_b32 m0, s34
	s_nop 0
	global_load_lds_dwordx4 v[142:143], off
	v_lshl_add_u64 v[142:143], v[226:227], 0, s[6:7]
	s_mov_b32 m0, s35
	s_nop 0
	global_load_lds_dwordx4 v[142:143], off
	s_waitcnt vmcnt(8)
	s_waitcnt lgkmcnt(0)
	s_barrier
	s_waitcnt lgkmcnt(0)
	v_mfma_f32_16x16x32_f16 v[60:63], v[158:161], v[190:193], v[60:63]
	v_mfma_f32_16x16x32_f16 v[56:59], v[166:169], v[190:193], v[56:59]
	v_mfma_f32_16x16x32_f16 v[44:47], v[158:161], v[198:201], v[44:47]
	v_mfma_f32_16x16x32_f16 v[40:43], v[166:169], v[198:201], v[40:43]
	v_mfma_f32_16x16x32_f16 v[28:31], v[158:161], v[206:209], v[28:31]
	v_mfma_f32_16x16x32_f16 v[24:27], v[166:169], v[206:209], v[24:27]
	v_mfma_f32_16x16x32_f16 v[12:15], v[158:161], v[214:217], v[12:15]
	v_mfma_f32_16x16x32_f16 v[8:11], v[166:169], v[214:217], v[8:11]
	v_mfma_f32_16x16x32_f16 v[60:63], v[162:165], v[194:197], v[60:63]
	v_mfma_f32_16x16x32_f16 v[56:59], v[170:173], v[194:197], v[56:59]
	v_mfma_f32_16x16x32_f16 v[44:47], v[162:165], v[202:205], v[44:47]
	v_mfma_f32_16x16x32_f16 v[40:43], v[170:173], v[202:205], v[40:43]
	v_mfma_f32_16x16x32_f16 v[28:31], v[162:165], v[210:213], v[28:31]
	v_mfma_f32_16x16x32_f16 v[24:27], v[170:173], v[210:213], v[24:27]
	v_mfma_f32_16x16x32_f16 v[12:15], v[162:165], v[218:221], v[12:15]
	v_mfma_f32_16x16x32_f16 v[8:11], v[170:173], v[218:221], v[8:11]
	v_mfma_f32_16x16x32_f16 v[52:55], v[174:177], v[190:193], v[52:55]
	v_mfma_f32_16x16x32_f16 v[48:51], v[182:185], v[190:193], v[48:51]
	v_mfma_f32_16x16x32_f16 v[36:39], v[174:177], v[198:201], v[36:39]
	v_mfma_f32_16x16x32_f16 v[32:35], v[182:185], v[198:201], v[32:35]
	v_mfma_f32_16x16x32_f16 v[20:23], v[174:177], v[206:209], v[20:23]
	v_mfma_f32_16x16x32_f16 v[16:19], v[182:185], v[206:209], v[16:19]
	v_mfma_f32_16x16x32_f16 v[4:7], v[174:177], v[214:217], v[4:7]
	v_mfma_f32_16x16x32_f16 v[0:3], v[182:185], v[214:217], v[0:3]
	v_mfma_f32_16x16x32_f16 v[52:55], v[178:181], v[194:197], v[52:55]
	v_mfma_f32_16x16x32_f16 v[48:51], v[186:189], v[194:197], v[48:51]
	v_mfma_f32_16x16x32_f16 v[36:39], v[178:181], v[202:205], v[36:39]
	v_mfma_f32_16x16x32_f16 v[32:35], v[186:189], v[202:205], v[32:35]
	v_mfma_f32_16x16x32_f16 v[20:23], v[178:181], v[210:213], v[20:23]
	v_mfma_f32_16x16x32_f16 v[16:19], v[186:189], v[210:213], v[16:19]
	v_mfma_f32_16x16x32_f16 v[4:7], v[178:181], v[218:221], v[4:7]
	v_mfma_f32_16x16x32_f16 v[0:3], v[186:189], v[218:221], v[0:3]
	s_barrier
	s_add_i32 s28, s28, 2
	s_add_u32 s4, s4, 0x100
	s_addc_u32 s5, s5, 0
	s_add_u32 s3, s3, 0x100
	s_addc_u32 s8, s8, 0
	s_cmp_gt_u32 s28, 13
	s_cbranch_scc0 .LBB0_732
	s_and_b64 vcc, exec, s[26:27]
	s_cbranch_vccz .LBB0_735
	s_barrier

.LBB0_886:
	ds_read_b128 v[84:87], v79
	ds_read_b128 v[88:91], v79 offset:1024
	ds_read_b128 v[92:95], v79 offset:2048
	ds_read_b128 v[96:99], v79 offset:3072
	ds_read_b128 v[100:103], v80
	ds_read_b128 v[104:107], v80 offset:1024
	ds_read_b128 v[108:111], v80 offset:2048
	ds_read_b128 v[112:115], v80 offset:3072
	s_add_u32 s14, s12, 0xba00100
	s_addc_u32 s15, s13, 0
	s_add_u32 s20, s12, s3
	s_addc_u32 s21, s13, s18
	s_cmp_eq_u32 s19, 12
	s_cselect_b32 s17, s7, s15
	s_cselect_b32 s16, s6, s14
	s_cselect_b32 s15, s5, s21
	s_cselect_b32 s14, s4, s20
	s_mov_b32 m0, s85
	v_lshl_add_u64 v[150:151], s[12:13], 0, v[72:73]
	ds_read_b128 v[116:119], v81
	ds_read_b128 v[120:123], v81 offset:1024
	ds_read_b128 v[124:127], v81 offset:2048
	ds_read_b128 v[128:131], v81 offset:3072
	ds_read_b128 v[132:135], v81 offset:4096
	ds_read_b128 v[136:139], v81 offset:5120
	ds_read_b128 v[140:143], v81 offset:6144
	ds_read_b128 v[146:149], v81 offset:7168
	global_load_lds_dwordx4 v[150:151], off
	v_lshl_add_u64 v[150:151], s[12:13], 0, v[74:75]
	s_mov_b32 m0, s84
	s_nop 0
	global_load_lds_dwordx4 v[150:151], off
	s_waitcnt vmcnt(8)
	s_waitcnt lgkmcnt(0)
	s_barrier
	s_waitcnt lgkmcnt(0)
	v_mfma_f32_16x16x32_f16 v[60:63], v[84:87], v[116:119], v[60:63]
	v_mfma_f32_16x16x32_f16 v[56:59], v[92:95], v[116:119], v[56:59]
	v_mfma_f32_16x16x32_f16 v[44:47], v[84:87], v[124:127], v[44:47]
	v_mfma_f32_16x16x32_f16 v[40:43], v[92:95], v[124:127], v[40:43]
	v_mfma_f32_16x16x32_f16 v[28:31], v[84:87], v[132:135], v[28:31]
	v_mfma_f32_16x16x32_f16 v[24:27], v[92:95], v[132:135], v[24:27]
	v_mfma_f32_16x16x32_f16 v[12:15], v[84:87], v[140:143], v[12:15]
	v_mfma_f32_16x16x32_f16 v[8:11], v[92:95], v[140:143], v[8:11]
	v_mfma_f32_16x16x32_f16 v[60:63], v[88:91], v[120:123], v[60:63]
	v_mfma_f32_16x16x32_f16 v[56:59], v[96:99], v[120:123], v[56:59]
	v_mfma_f32_16x16x32_f16 v[44:47], v[88:91], v[128:131], v[44:47]
	v_mfma_f32_16x16x32_f16 v[40:43], v[96:99], v[128:131], v[40:43]
	v_mfma_f32_16x16x32_f16 v[28:31], v[88:91], v[136:139], v[28:31]
	v_mfma_f32_16x16x32_f16 v[24:27], v[96:99], v[136:139], v[24:27]
	v_mfma_f32_16x16x32_f16 v[12:15], v[88:91], v[146:149], v[12:15]
	v_mfma_f32_16x16x32_f16 v[8:11], v[96:99], v[146:149], v[8:11]
	v_mfma_f32_16x16x32_f16 v[52:55], v[100:103], v[116:119], v[52:55]
	v_mfma_f32_16x16x32_f16 v[48:51], v[108:111], v[116:119], v[48:51]
	v_mfma_f32_16x16x32_f16 v[36:39], v[100:103], v[124:127], v[36:39]
	v_mfma_f32_16x16x32_f16 v[32:35], v[108:111], v[124:127], v[32:35]
	v_mfma_f32_16x16x32_f16 v[20:23], v[100:103], v[132:135], v[20:23]
	v_mfma_f32_16x16x32_f16 v[16:19], v[108:111], v[132:135], v[16:19]
	v_mfma_f32_16x16x32_f16 v[4:7], v[100:103], v[140:143], v[4:7]
	v_mfma_f32_16x16x32_f16 v[0:3], v[108:111], v[140:143], v[0:3]
	v_mfma_f32_16x16x32_f16 v[52:55], v[104:107], v[120:123], v[52:55]
	v_mfma_f32_16x16x32_f16 v[48:51], v[112:115], v[120:123], v[48:51]
	v_mfma_f32_16x16x32_f16 v[36:39], v[104:107], v[128:131], v[36:39]
	v_mfma_f32_16x16x32_f16 v[32:35], v[112:115], v[128:131], v[32:35]
	v_mfma_f32_16x16x32_f16 v[20:23], v[104:107], v[136:139], v[20:23]
	v_mfma_f32_16x16x32_f16 v[16:19], v[112:115], v[136:139], v[16:19]
	v_mfma_f32_16x16x32_f16 v[4:7], v[104:107], v[146:149], v[4:7]
	v_mfma_f32_16x16x32_f16 v[0:3], v[112:115], v[146:149], v[0:3]
	s_barrier
	s_mov_b32 m0, s83
	v_lshl_add_u64 v[150:151], s[14:15], 0, v[66:67]
	s_add_u32 s20, s14, 0x40000
	global_load_lds_dwordx4 v[150:151], off
	v_lshl_add_u64 v[152:153], s[14:15], 0, v[70:71]
	s_mov_b32 m0, s82
	s_addc_u32 s21, s15, 0
	global_load_lds_dwordx4 v[152:153], off
	v_lshl_add_u64 v[84:85], s[20:21], 0, v[66:67]
	s_mov_b32 m0, s81
	v_lshl_add_u64 v[154:155], s[16:17], 0, v[64:65]
	global_load_lds_dwordx4 v[84:85], off
	v_lshl_add_u64 v[84:85], s[20:21], 0, v[70:71]
	s_mov_b32 m0, s80
	v_lshl_add_u64 v[156:157], s[16:17], 0, v[68:69]
	global_load_lds_dwordx4 v[84:85], off
	s_mov_b32 m0, s61
	s_nop 0
	global_load_lds_dwordx4 v[154:155], off
	s_mov_b32 m0, s71
	s_nop 0
	global_load_lds_dwordx4 v[156:157], off
	s_waitcnt vmcnt(8)
	s_waitcnt lgkmcnt(0)
	s_barrier
	s_barrier
	ds_read_b128 v[84:87], v82
	ds_read_b128 v[88:91], v82 offset:1024
	ds_read_b128 v[92:95], v82 offset:2048
	ds_read_b128 v[96:99], v82 offset:3072
	ds_read_b128 v[100:103], v83
	ds_read_b128 v[104:107], v83 offset:1024
	ds_read_b128 v[108:111], v83 offset:2048
	ds_read_b128 v[112:115], v83 offset:3072
	s_add_u32 s16, s16, 0x40000
	s_addc_u32 s17, s17, 0
	s_mov_b32 m0, s47
	v_lshl_add_u64 v[158:159], s[16:17], 0, v[64:65]
	ds_read_b128 v[116:119], v81 offset:32768
	ds_read_b128 v[120:123], v81 offset:33792
	ds_read_b128 v[124:127], v81 offset:34816
	ds_read_b128 v[128:131], v81 offset:35840
	ds_read_b128 v[132:135], v81 offset:36864
	ds_read_b128 v[136:139], v81 offset:37888
	ds_read_b128 v[140:143], v81 offset:38912
	ds_read_b128 v[146:149], v81 offset:39936
	global_load_lds_dwordx4 v[158:159], off
	v_lshl_add_u64 v[158:159], s[16:17], 0, v[68:69]
	s_mov_b32 m0, s58
	s_nop 0
	global_load_lds_dwordx4 v[158:159], off
	s_waitcnt vmcnt(8)
	s_waitcnt lgkmcnt(0)
	s_barrier
	s_waitcnt lgkmcnt(0)
	v_mfma_f32_16x16x32_f16 v[60:63], v[84:87], v[116:119], v[60:63]
	v_mfma_f32_16x16x32_f16 v[56:59], v[92:95], v[116:119], v[56:59]
	v_mfma_f32_16x16x32_f16 v[44:47], v[84:87], v[124:127], v[44:47]
	v_mfma_f32_16x16x32_f16 v[40:43], v[92:95], v[124:127], v[40:43]
	v_mfma_f32_16x16x32_f16 v[28:31], v[84:87], v[132:135], v[28:31]
	v_mfma_f32_16x16x32_f16 v[24:27], v[92:95], v[132:135], v[24:27]
	v_mfma_f32_16x16x32_f16 v[12:15], v[84:87], v[140:143], v[12:15]
	v_mfma_f32_16x16x32_f16 v[8:11], v[92:95], v[140:143], v[8:11]
	v_mfma_f32_16x16x32_f16 v[60:63], v[88:91], v[120:123], v[60:63]
	v_mfma_f32_16x16x32_f16 v[56:59], v[96:99], v[120:123], v[56:59]
	v_mfma_f32_16x16x32_f16 v[44:47], v[88:91], v[128:131], v[44:47]
	v_mfma_f32_16x16x32_f16 v[40:43], v[96:99], v[128:131], v[40:43]
	v_mfma_f32_16x16x32_f16 v[28:31], v[88:91], v[136:139], v[28:31]
	v_mfma_f32_16x16x32_f16 v[24:27], v[96:99], v[136:139], v[24:27]
	v_mfma_f32_16x16x32_f16 v[12:15], v[88:91], v[146:149], v[12:15]
	v_mfma_f32_16x16x32_f16 v[8:11], v[96:99], v[146:149], v[8:11]
	v_mfma_f32_16x16x32_f16 v[52:55], v[100:103], v[116:119], v[52:55]
	v_mfma_f32_16x16x32_f16 v[48:51], v[108:111], v[116:119], v[48:51]
	v_mfma_f32_16x16x32_f16 v[36:39], v[100:103], v[124:127], v[36:39]
	v_mfma_f32_16x16x32_f16 v[32:35], v[108:111], v[124:127], v[32:35]
	v_mfma_f32_16x16x32_f16 v[20:23], v[100:103], v[132:135], v[20:23]
	v_mfma_f32_16x16x32_f16 v[16:19], v[108:111], v[132:135], v[16:19]
	v_mfma_f32_16x16x32_f16 v[4:7], v[100:103], v[140:143], v[4:7]
	v_mfma_f32_16x16x32_f16 v[0:3], v[108:111], v[140:143], v[0:3]
	v_mfma_f32_16x16x32_f16 v[52:55], v[104:107], v[120:123], v[52:55]
	v_mfma_f32_16x16x32_f16 v[48:51], v[112:115], v[120:123], v[48:51]
	v_mfma_f32_16x16x32_f16 v[36:39], v[104:107], v[128:131], v[36:39]
	v_mfma_f32_16x16x32_f16 v[32:35], v[112:115], v[128:131], v[32:35]
	v_mfma_f32_16x16x32_f16 v[20:23], v[104:107], v[136:139], v[20:23]
	v_mfma_f32_16x16x32_f16 v[16:19], v[112:115], v[136:139], v[16:19]
	v_mfma_f32_16x16x32_f16 v[4:7], v[104:107], v[146:149], v[4:7]
	v_mfma_f32_16x16x32_f16 v[0:3], v[112:115], v[146:149], v[0:3]
	s_barrier
	s_mov_b32 m0, s70
	v_lshl_add_u64 v[84:85], v[150:151], 0, s[8:9]
	s_add_u32 s14, s14, 0x40080
	global_load_lds_dwordx4 v[84:85], off
	v_lshl_add_u64 v[84:85], v[152:153], 0, s[8:9]
	s_mov_b32 m0, s63
	s_addc_u32 s15, s15, 0
	global_load_lds_dwordx4 v[84:85], off
	v_lshl_add_u64 v[84:85], s[14:15], 0, v[66:67]
	s_mov_b32 m0, s62
	s_nop 0
	global_load_lds_dwordx4 v[84:85], off
	v_lshl_add_u64 v[84:85], s[14:15], 0, v[70:71]
	s_mov_b32 m0, s59
	s_nop 0
	global_load_lds_dwordx4 v[84:85], off
	v_lshl_add_u64 v[84:85], v[154:155], 0, s[8:9]
	s_mov_b32 m0, s34
	s_nop 0
	global_load_lds_dwordx4 v[84:85], off
	v_lshl_add_u64 v[84:85], v[156:157], 0, s[8:9]
	s_mov_b32 m0, s35
	s_nop 0
	global_load_lds_dwordx4 v[84:85], off
	s_waitcnt vmcnt(8)
	s_waitcnt lgkmcnt(0)
	s_barrier
	s_barrier
	s_add_i32 s19, s19, 2
	s_add_u32 s12, s12, 0x100
	s_addc_u32 s13, s13, 0
	s_cmp_gt_u32 s19, 13
	s_cbranch_scc0 .LBB0_886
	s_and_b64 vcc, exec, s[26:27]
	s_cbranch_vccz .LBB0_889
	s_barrier

.LBB0_933:
	ds_read_b128 v[150:153], v129
	ds_read_b128 v[154:157], v129 offset:1024
	ds_read_b128 v[158:161], v129 offset:2048
	ds_read_b128 v[162:165], v129 offset:3072
	ds_read_b128 v[166:169], v145
	ds_read_b128 v[170:173], v145 offset:1024
	ds_read_b128 v[174:177], v145 offset:2048
	ds_read_b128 v[178:181], v145 offset:3072
	s_add_u32 s14, s10, 0xfb00100
	s_addc_u32 s15, s11, 0
	s_add_u32 s28, s10, s3
	s_addc_u32 s29, s11, s18
	s_cmp_eq_u32 s19, 12
	s_cselect_b32 s17, s7, s15
	s_cselect_b32 s16, s6, s14
	s_cselect_b32 s15, s5, s29
	s_cselect_b32 s14, s4, s28
	s_mov_b32 m0, s85
	v_lshl_add_u64 v[214:215], s[10:11], 0, v[138:139]
	ds_read_b128 v[182:185], v146
	ds_read_b128 v[186:189], v146 offset:1024
	ds_read_b128 v[190:193], v146 offset:2048
	ds_read_b128 v[194:197], v146 offset:3072
	ds_read_b128 v[198:201], v146 offset:4096
	ds_read_b128 v[202:205], v146 offset:5120
	ds_read_b128 v[206:209], v146 offset:6144
	ds_read_b128 v[210:213], v146 offset:7168
	global_load_lds_dwordx4 v[214:215], off
	v_lshl_add_u64 v[214:215], s[10:11], 0, v[140:141]
	s_mov_b32 m0, s84
	s_nop 0
	global_load_lds_dwordx4 v[214:215], off
	s_waitcnt vmcnt(8)
	s_waitcnt lgkmcnt(0)
	s_barrier
	s_waitcnt lgkmcnt(0)
	v_mfma_f32_16x16x32_f16 v[124:127], v[150:153], v[182:185], v[124:127]
	v_mfma_f32_16x16x32_f16 v[120:123], v[158:161], v[182:185], v[120:123]
	v_mfma_f32_16x16x32_f16 v[108:111], v[150:153], v[190:193], v[108:111]
	v_mfma_f32_16x16x32_f16 v[104:107], v[158:161], v[190:193], v[104:107]
	v_mfma_f32_16x16x32_f16 v[92:95], v[150:153], v[198:201], v[92:95]
	v_mfma_f32_16x16x32_f16 v[88:91], v[158:161], v[198:201], v[88:91]
	v_mfma_f32_16x16x32_f16 v[76:79], v[150:153], v[206:209], v[76:79]
	v_mfma_f32_16x16x32_f16 v[72:75], v[158:161], v[206:209], v[72:75]
	v_mfma_f32_16x16x32_f16 v[124:127], v[154:157], v[186:189], v[124:127]
	v_mfma_f32_16x16x32_f16 v[120:123], v[162:165], v[186:189], v[120:123]
	v_mfma_f32_16x16x32_f16 v[108:111], v[154:157], v[194:197], v[108:111]
	v_mfma_f32_16x16x32_f16 v[104:107], v[162:165], v[194:197], v[104:107]
	v_mfma_f32_16x16x32_f16 v[92:95], v[154:157], v[202:205], v[92:95]
	v_mfma_f32_16x16x32_f16 v[88:91], v[162:165], v[202:205], v[88:91]
	v_mfma_f32_16x16x32_f16 v[76:79], v[154:157], v[210:213], v[76:79]
	v_mfma_f32_16x16x32_f16 v[72:75], v[162:165], v[210:213], v[72:75]
	v_mfma_f32_16x16x32_f16 v[116:119], v[166:169], v[182:185], v[116:119]
	v_mfma_f32_16x16x32_f16 v[112:115], v[174:177], v[182:185], v[112:115]
	v_mfma_f32_16x16x32_f16 v[100:103], v[166:169], v[190:193], v[100:103]
	v_mfma_f32_16x16x32_f16 v[96:99], v[174:177], v[190:193], v[96:99]
	v_mfma_f32_16x16x32_f16 v[84:87], v[166:169], v[198:201], v[84:87]
	v_mfma_f32_16x16x32_f16 v[80:83], v[174:177], v[198:201], v[80:83]
	v_mfma_f32_16x16x32_f16 v[64:67], v[166:169], v[206:209], v[64:67]
	v_mfma_f32_16x16x32_f16 v[68:71], v[174:177], v[206:209], v[68:71]
	v_mfma_f32_16x16x32_f16 v[116:119], v[170:173], v[186:189], v[116:119]
	v_mfma_f32_16x16x32_f16 v[112:115], v[178:181], v[186:189], v[112:115]
	v_mfma_f32_16x16x32_f16 v[100:103], v[170:173], v[194:197], v[100:103]
	v_mfma_f32_16x16x32_f16 v[96:99], v[178:181], v[194:197], v[96:99]
	v_mfma_f32_16x16x32_f16 v[84:87], v[170:173], v[202:205], v[84:87]
	v_mfma_f32_16x16x32_f16 v[80:83], v[178:181], v[202:205], v[80:83]
	v_mfma_f32_16x16x32_f16 v[64:67], v[170:173], v[210:213], v[64:67]
	v_mfma_f32_16x16x32_f16 v[68:71], v[178:181], v[210:213], v[68:71]
	s_barrier
	s_mov_b32 m0, s83
	v_lshl_add_u64 v[214:215], s[14:15], 0, v[132:133]
	s_add_u32 s28, s14, 0x40000
	ds_read_b128 v[182:185], v146 offset:16384
	ds_read_b128 v[186:189], v146 offset:17408
	ds_read_b128 v[190:193], v146 offset:18432
	ds_read_b128 v[194:197], v146 offset:19456
	ds_read_b128 v[198:201], v146 offset:20480
	ds_read_b128 v[202:205], v146 offset:21504
	ds_read_b128 v[206:209], v146 offset:22528
	ds_read_b128 v[210:213], v146 offset:23552
	global_load_lds_dwordx4 v[214:215], off
	v_lshl_add_u64 v[216:217], s[14:15], 0, v[136:137]
	s_mov_b32 m0, s82
	s_addc_u32 s29, s15, 0
	global_load_lds_dwordx4 v[216:217], off
	v_lshl_add_u64 v[218:219], s[28:29], 0, v[132:133]
	s_mov_b32 m0, s81
	v_lshl_add_u64 v[220:221], s[16:17], 0, v[134:135]
	global_load_lds_dwordx4 v[218:219], off
	v_lshl_add_u64 v[218:219], s[28:29], 0, v[136:137]
	s_mov_b32 m0, s80
	s_nop 0
	global_load_lds_dwordx4 v[218:219], off
	v_lshl_add_u64 v[218:219], s[16:17], 0, v[130:131]
	s_mov_b32 m0, s61
	s_nop 0
	global_load_lds_dwordx4 v[218:219], off
	s_mov_b32 m0, s71
	s_nop 0
	global_load_lds_dwordx4 v[220:221], off
	s_waitcnt vmcnt(8)
	s_waitcnt lgkmcnt(0)
	s_barrier
	s_waitcnt lgkmcnt(0)
	v_mfma_f32_16x16x32_f16 v[60:63], v[150:153], v[182:185], v[60:63]
	v_mfma_f32_16x16x32_f16 v[56:59], v[158:161], v[182:185], v[56:59]
	v_mfma_f32_16x16x32_f16 v[44:47], v[150:153], v[190:193], v[44:47]
	v_mfma_f32_16x16x32_f16 v[40:43], v[158:161], v[190:193], v[40:43]
	v_mfma_f32_16x16x32_f16 v[28:31], v[150:153], v[198:201], v[28:31]
	v_mfma_f32_16x16x32_f16 v[24:27], v[158:161], v[198:201], v[24:27]
	v_mfma_f32_16x16x32_f16 v[12:15], v[150:153], v[206:209], v[12:15]
	v_mfma_f32_16x16x32_f16 v[8:11], v[158:161], v[206:209], v[8:11]
	v_mfma_f32_16x16x32_f16 v[60:63], v[154:157], v[186:189], v[60:63]
	v_mfma_f32_16x16x32_f16 v[56:59], v[162:165], v[186:189], v[56:59]
	v_mfma_f32_16x16x32_f16 v[44:47], v[154:157], v[194:197], v[44:47]
	v_mfma_f32_16x16x32_f16 v[40:43], v[162:165], v[194:197], v[40:43]
	v_mfma_f32_16x16x32_f16 v[28:31], v[154:157], v[202:205], v[28:31]
	v_mfma_f32_16x16x32_f16 v[24:27], v[162:165], v[202:205], v[24:27]
	v_mfma_f32_16x16x32_f16 v[12:15], v[154:157], v[210:213], v[12:15]
	v_mfma_f32_16x16x32_f16 v[8:11], v[162:165], v[210:213], v[8:11]
	v_mfma_f32_16x16x32_f16 v[52:55], v[166:169], v[182:185], v[52:55]
	v_mfma_f32_16x16x32_f16 v[48:51], v[174:177], v[182:185], v[48:51]
	v_mfma_f32_16x16x32_f16 v[36:39], v[166:169], v[190:193], v[36:39]
	v_mfma_f32_16x16x32_f16 v[32:35], v[174:177], v[190:193], v[32:35]
	v_mfma_f32_16x16x32_f16 v[20:23], v[166:169], v[198:201], v[20:23]
	v_mfma_f32_16x16x32_f16 v[16:19], v[174:177], v[198:201], v[16:19]
	v_mfma_f32_16x16x32_f16 v[4:7], v[166:169], v[206:209], v[4:7]
	v_mfma_f32_16x16x32_f16 v[0:3], v[174:177], v[206:209], v[0:3]
	v_mfma_f32_16x16x32_f16 v[52:55], v[170:173], v[186:189], v[52:55]
	v_mfma_f32_16x16x32_f16 v[48:51], v[178:181], v[186:189], v[48:51]
	v_mfma_f32_16x16x32_f16 v[36:39], v[170:173], v[194:197], v[36:39]
	v_mfma_f32_16x16x32_f16 v[32:35], v[178:181], v[194:197], v[32:35]
	v_mfma_f32_16x16x32_f16 v[20:23], v[170:173], v[202:205], v[20:23]
	v_mfma_f32_16x16x32_f16 v[16:19], v[178:181], v[202:205], v[16:19]
	v_mfma_f32_16x16x32_f16 v[4:7], v[170:173], v[210:213], v[4:7]
	v_mfma_f32_16x16x32_f16 v[0:3], v[178:181], v[210:213], v[0:3]
	s_barrier
	ds_read_b128 v[150:153], v147
	ds_read_b128 v[154:157], v147 offset:1024
	ds_read_b128 v[158:161], v147 offset:2048
	ds_read_b128 v[162:165], v147 offset:3072
	ds_read_b128 v[166:169], v148
	ds_read_b128 v[170:173], v148 offset:1024
	ds_read_b128 v[174:177], v148 offset:2048
	ds_read_b128 v[178:181], v148 offset:3072
	s_add_u32 s16, s16, 0x40000
	s_addc_u32 s17, s17, 0
	s_mov_b32 m0, s47
	v_lshl_add_u64 v[222:223], s[16:17], 0, v[130:131]
	ds_read_b128 v[182:185], v146 offset:32768
	ds_read_b128 v[186:189], v146 offset:33792
	ds_read_b128 v[190:193], v146 offset:34816
	ds_read_b128 v[194:197], v146 offset:35840
	ds_read_b128 v[198:201], v146 offset:36864
	ds_read_b128 v[202:205], v146 offset:37888
	ds_read_b128 v[206:209], v146 offset:38912
	ds_read_b128 v[210:213], v146 offset:39936
	global_load_lds_dwordx4 v[222:223], off
	v_lshl_add_u64 v[222:223], s[16:17], 0, v[134:135]
	s_mov_b32 m0, s58
	s_nop 0
	global_load_lds_dwordx4 v[222:223], off
	s_waitcnt vmcnt(8)
	s_waitcnt lgkmcnt(0)
	s_barrier
	s_waitcnt lgkmcnt(0)
	v_mfma_f32_16x16x32_f16 v[124:127], v[150:153], v[182:185], v[124:127]
	v_mfma_f32_16x16x32_f16 v[120:123], v[158:161], v[182:185], v[120:123]
	v_mfma_f32_16x16x32_f16 v[108:111], v[150:153], v[190:193], v[108:111]
	v_mfma_f32_16x16x32_f16 v[104:107], v[158:161], v[190:193], v[104:107]
	v_mfma_f32_16x16x32_f16 v[92:95], v[150:153], v[198:201], v[92:95]
	v_mfma_f32_16x16x32_f16 v[88:91], v[158:161], v[198:201], v[88:91]
	v_mfma_f32_16x16x32_f16 v[76:79], v[150:153], v[206:209], v[76:79]
	v_mfma_f32_16x16x32_f16 v[72:75], v[158:161], v[206:209], v[72:75]
	v_mfma_f32_16x16x32_f16 v[124:127], v[154:157], v[186:189], v[124:127]
	v_mfma_f32_16x16x32_f16 v[120:123], v[162:165], v[186:189], v[120:123]
	v_mfma_f32_16x16x32_f16 v[108:111], v[154:157], v[194:197], v[108:111]
	v_mfma_f32_16x16x32_f16 v[104:107], v[162:165], v[194:197], v[104:107]
	v_mfma_f32_16x16x32_f16 v[92:95], v[154:157], v[202:205], v[92:95]
	v_mfma_f32_16x16x32_f16 v[88:91], v[162:165], v[202:205], v[88:91]
	v_mfma_f32_16x16x32_f16 v[76:79], v[154:157], v[210:213], v[76:79]
	v_mfma_f32_16x16x32_f16 v[72:75], v[162:165], v[210:213], v[72:75]
	v_mfma_f32_16x16x32_f16 v[116:119], v[166:169], v[182:185], v[116:119]
	v_mfma_f32_16x16x32_f16 v[112:115], v[174:177], v[182:185], v[112:115]
	v_mfma_f32_16x16x32_f16 v[100:103], v[166:169], v[190:193], v[100:103]
	v_mfma_f32_16x16x32_f16 v[96:99], v[174:177], v[190:193], v[96:99]
	v_mfma_f32_16x16x32_f16 v[84:87], v[166:169], v[198:201], v[84:87]
	v_mfma_f32_16x16x32_f16 v[80:83], v[174:177], v[198:201], v[80:83]
	v_mfma_f32_16x16x32_f16 v[64:67], v[166:169], v[206:209], v[64:67]
	v_mfma_f32_16x16x32_f16 v[68:71], v[174:177], v[206:209], v[68:71]
	v_mfma_f32_16x16x32_f16 v[116:119], v[170:173], v[186:189], v[116:119]
	v_mfma_f32_16x16x32_f16 v[112:115], v[178:181], v[186:189], v[112:115]
	v_mfma_f32_16x16x32_f16 v[100:103], v[170:173], v[194:197], v[100:103]
	v_mfma_f32_16x16x32_f16 v[96:99], v[178:181], v[194:197], v[96:99]
	v_mfma_f32_16x16x32_f16 v[84:87], v[170:173], v[202:205], v[84:87]
	v_mfma_f32_16x16x32_f16 v[80:83], v[178:181], v[202:205], v[80:83]
	v_mfma_f32_16x16x32_f16 v[64:67], v[170:173], v[210:213], v[64:67]
	v_mfma_f32_16x16x32_f16 v[68:71], v[178:181], v[210:213], v[68:71]
	s_barrier
	s_mov_b32 m0, s70
	v_lshl_add_u64 v[214:215], v[214:215], 0, s[8:9]
	s_add_u32 s14, s14, 0x40080
	ds_read_b128 v[182:185], v146 offset:49152
	ds_read_b128 v[186:189], v146 offset:50176
	ds_read_b128 v[190:193], v146 offset:51200
	ds_read_b128 v[194:197], v146 offset:52224
	ds_read_b128 v[198:201], v146 offset:53248
	ds_read_b128 v[202:205], v146 offset:54272
	ds_read_b128 v[206:209], v146 offset:55296
	ds_read_b128 v[210:213], v146 offset:56320
	global_load_lds_dwordx4 v[214:215], off
	v_lshl_add_u64 v[214:215], v[216:217], 0, s[8:9]
	s_mov_b32 m0, s63
	s_addc_u32 s15, s15, 0
	global_load_lds_dwordx4 v[214:215], off
	v_lshl_add_u64 v[214:215], s[14:15], 0, v[132:133]
	s_mov_b32 m0, s62
	s_nop 0
	global_load_lds_dwordx4 v[214:215], off
	v_lshl_add_u64 v[214:215], s[14:15], 0, v[136:137]
	s_mov_b32 m0, s59
	s_nop 0
	global_load_lds_dwordx4 v[214:215], off
	v_lshl_add_u64 v[214:215], v[218:219], 0, s[8:9]
	s_mov_b32 m0, s34
	s_nop 0
	global_load_lds_dwordx4 v[214:215], off
	v_lshl_add_u64 v[214:215], v[220:221], 0, s[8:9]
	s_mov_b32 m0, s35
	s_nop 0
	global_load_lds_dwordx4 v[214:215], off
	s_waitcnt vmcnt(8)
	s_waitcnt lgkmcnt(0)
	s_barrier
	s_waitcnt lgkmcnt(0)
	v_mfma_f32_16x16x32_f16 v[60:63], v[150:153], v[182:185], v[60:63]
	v_mfma_f32_16x16x32_f16 v[56:59], v[158:161], v[182:185], v[56:59]
	v_mfma_f32_16x16x32_f16 v[44:47], v[150:153], v[190:193], v[44:47]
	v_mfma_f32_16x16x32_f16 v[40:43], v[158:161], v[190:193], v[40:43]
	v_mfma_f32_16x16x32_f16 v[28:31], v[150:153], v[198:201], v[28:31]
	v_mfma_f32_16x16x32_f16 v[24:27], v[158:161], v[198:201], v[24:27]
	v_mfma_f32_16x16x32_f16 v[12:15], v[150:153], v[206:209], v[12:15]
	v_mfma_f32_16x16x32_f16 v[8:11], v[158:161], v[206:209], v[8:11]
	v_mfma_f32_16x16x32_f16 v[60:63], v[154:157], v[186:189], v[60:63]
	v_mfma_f32_16x16x32_f16 v[56:59], v[162:165], v[186:189], v[56:59]
	v_mfma_f32_16x16x32_f16 v[44:47], v[154:157], v[194:197], v[44:47]
	v_mfma_f32_16x16x32_f16 v[40:43], v[162:165], v[194:197], v[40:43]
	v_mfma_f32_16x16x32_f16 v[28:31], v[154:157], v[202:205], v[28:31]
	v_mfma_f32_16x16x32_f16 v[24:27], v[162:165], v[202:205], v[24:27]
	v_mfma_f32_16x16x32_f16 v[12:15], v[154:157], v[210:213], v[12:15]
	v_mfma_f32_16x16x32_f16 v[8:11], v[162:165], v[210:213], v[8:11]
	v_mfma_f32_16x16x32_f16 v[52:55], v[166:169], v[182:185], v[52:55]
	v_mfma_f32_16x16x32_f16 v[48:51], v[174:177], v[182:185], v[48:51]
	v_mfma_f32_16x16x32_f16 v[36:39], v[166:169], v[190:193], v[36:39]
	v_mfma_f32_16x16x32_f16 v[32:35], v[174:177], v[190:193], v[32:35]
	v_mfma_f32_16x16x32_f16 v[20:23], v[166:169], v[198:201], v[20:23]
	v_mfma_f32_16x16x32_f16 v[16:19], v[174:177], v[198:201], v[16:19]
	v_mfma_f32_16x16x32_f16 v[4:7], v[166:169], v[206:209], v[4:7]
	v_mfma_f32_16x16x32_f16 v[0:3], v[174:177], v[206:209], v[0:3]
	v_mfma_f32_16x16x32_f16 v[52:55], v[170:173], v[186:189], v[52:55]
	v_mfma_f32_16x16x32_f16 v[48:51], v[178:181], v[186:189], v[48:51]
	v_mfma_f32_16x16x32_f16 v[36:39], v[170:173], v[194:197], v[36:39]
	v_mfma_f32_16x16x32_f16 v[32:35], v[178:181], v[194:197], v[32:35]
	v_mfma_f32_16x16x32_f16 v[20:23], v[170:173], v[202:205], v[20:23]
	v_mfma_f32_16x16x32_f16 v[16:19], v[178:181], v[202:205], v[16:19]
	v_mfma_f32_16x16x32_f16 v[4:7], v[170:173], v[210:213], v[4:7]
	v_mfma_f32_16x16x32_f16 v[0:3], v[178:181], v[210:213], v[0:3]
	s_barrier
	s_add_i32 s19, s19, 2
	s_add_u32 s10, s10, 0x100
	s_addc_u32 s11, s11, 0
	s_cmp_gt_u32 s19, 13
	s_cbranch_scc0 .LBB0_933
	s_and_b64 vcc, exec, s[26:27]
	s_cbranch_vccz .LBB0_936
	s_barrier

.LBB0_938:
	v_and_b32_e32 v133, 15, v34
	v_bfe_u32 v132, v34, 4, 2
	v_or_b32_e32 v35, s69, v133
	v_lshlrev_b32_e32 v36, 4, v132
	v_lshlrev_b32_e32 v37, 6, v35
	s_movk_i32 s3, 0x3c0
	v_lshlrev_b32_e32 v35, 2, v35
	v_and_or_b32 v37, v37, s3, v36
	v_and_b32_e32 v35, 32, v35
	v_lshlrev_b32_e32 v34, 2, v34
	v_bitop3_b32 v66, v37, s52, v35 bitop3:0xde
	v_lshl_or_b32 v35, v133, 6, v36
	v_and_b32_e32 v34, 32, v34
	v_bitop3_b32 v67, v35, s53, v34 bitop3:0xde
	s_add_u32 s12, s76, 0x7900100
	s_addc_u32 s13, s77, 0
	v_add_u32_e32 v131, s67, v67
	s_add_u32 s6, s76, 0x7900180
	s_waitcnt vmcnt(8)
	s_barrier
	s_waitcnt vmcnt(6)
	s_barrier
	v_add_u32_e32 v130, s88, v67
	ds_read_b128 v[34:37], v131
	ds_read_b128 v[38:41], v131 offset:1024
	ds_read_b128 v[42:45], v131 offset:2048
	ds_read_b128 v[46:49], v131 offset:3072
	ds_read_b128 v[50:53], v130
	ds_read_b128 v[54:57], v130 offset:1024
	ds_read_b128 v[58:61], v130 offset:2048
	ds_read_b128 v[62:65], v130 offset:3072
	s_addc_u32 s7, s77, 0
	s_add_u32 s16, s76, 0x7910080
	s_addc_u32 s17, s77, 0
	s_add_u32 s14, s4, 0x10100
	s_addc_u32 s15, s5, 0
	s_add_u32 s10, s76, 0x7910100
	s_addc_u32 s11, s77, 0
	s_add_u32 s8, s4, 0x10180
	s_addc_u32 s9, s5, 0
	s_add_u32 s4, s76, 0x7910180
	s_addc_u32 s5, s77, 0
	v_add_u32_e32 v244, 0, v66
	v_add_u32_e32 v240, s86, v67
	v_add_u32_e32 v241, s87, v67
	s_mov_b32 m0, s85
	v_lshl_add_u64 v[98:99], s[16:17], 0, v[20:21]
	ds_read_b128 v[66:69], v244
	ds_read_b128 v[70:73], v244 offset:1024
	ds_read_b128 v[74:77], v244 offset:2048
	ds_read_b128 v[78:81], v244 offset:3072
	ds_read_b128 v[82:85], v244 offset:4096
	ds_read_b128 v[86:89], v244 offset:5120
	ds_read_b128 v[90:93], v244 offset:6144
	ds_read_b128 v[94:97], v244 offset:7168
	global_load_lds_dwordx4 v[98:99], off
	v_lshl_add_u64 v[98:99], s[16:17], 0, v[30:31]
	s_mov_b32 m0, s84
	s_nop 0
	global_load_lds_dwordx4 v[98:99], off
	s_waitcnt vmcnt(8)
	s_waitcnt lgkmcnt(0)
	s_barrier
	s_waitcnt lgkmcnt(0)
	v_mfma_f32_16x16x32_f16 v[98:101], v[34:37], v[66:69], 0
	v_mfma_f32_16x16x32_f16 v[102:105], v[42:45], v[66:69], 0
	v_mfma_f32_16x16x32_f16 v[106:109], v[34:37], v[74:77], 0
	v_mfma_f32_16x16x32_f16 v[110:113], v[42:45], v[74:77], 0
	v_mfma_f32_16x16x32_f16 v[114:117], v[34:37], v[82:85], 0
	v_mfma_f32_16x16x32_f16 v[118:121], v[42:45], v[82:85], 0
	v_mfma_f32_16x16x32_f16 v[122:125], v[34:37], v[90:93], 0
	v_mfma_f32_16x16x32_f16 v[98:101], v[38:41], v[70:73], v[98:101]
	v_mfma_f32_16x16x32_f16 v[102:105], v[46:49], v[70:73], v[102:105]
	v_mfma_f32_16x16x32_f16 v[106:109], v[38:41], v[78:81], v[106:109]
	v_mfma_f32_16x16x32_f16 v[110:113], v[46:49], v[78:81], v[110:113]
	v_mfma_f32_16x16x32_f16 v[114:117], v[38:41], v[86:89], v[114:117]
	v_mfma_f32_16x16x32_f16 v[118:121], v[46:49], v[86:89], v[118:121]
	v_mfma_f32_16x16x32_f16 v[122:125], v[38:41], v[94:97], v[122:125]
	v_mfma_f32_16x16x32_f16 v[134:137], v[42:45], v[90:93], 0
	v_mfma_f32_16x16x32_f16 v[134:137], v[46:49], v[94:97], v[134:137]
	v_mfma_f32_16x16x32_f16 v[138:141], v[50:53], v[66:69], 0
	v_mfma_f32_16x16x32_f16 v[66:69], v[58:61], v[66:69], 0
	v_mfma_f32_16x16x32_f16 v[138:141], v[54:57], v[70:73], v[138:141]
	v_mfma_f32_16x16x32_f16 v[66:69], v[62:65], v[70:73], v[66:69]
	v_mfma_f32_16x16x32_f16 v[70:73], v[50:53], v[74:77], 0
	v_mfma_f32_16x16x32_f16 v[74:77], v[58:61], v[74:77], 0
	v_mfma_f32_16x16x32_f16 v[70:73], v[54:57], v[78:81], v[70:73]
	v_mfma_f32_16x16x32_f16 v[74:77], v[62:65], v[78:81], v[74:77]
	v_mfma_f32_16x16x32_f16 v[78:81], v[50:53], v[82:85], 0
	v_mfma_f32_16x16x32_f16 v[82:85], v[58:61], v[82:85], 0
	v_mfma_f32_16x16x32_f16 v[78:81], v[54:57], v[86:89], v[78:81]
	v_mfma_f32_16x16x32_f16 v[82:85], v[62:65], v[86:89], v[82:85]
	v_mfma_f32_16x16x32_f16 v[86:89], v[50:53], v[90:93], 0
	v_mfma_f32_16x16x32_f16 v[90:93], v[58:61], v[90:93], 0
	v_mfma_f32_16x16x32_f16 v[86:89], v[54:57], v[94:97], v[86:89]
	v_mfma_f32_16x16x32_f16 v[90:93], v[62:65], v[94:97], v[90:93]
	s_barrier
	s_mov_b64 s[16:17], 0x100
	s_mov_b32 m0, s83
	v_lshl_add_u64 v[126:127], v[16:17], 0, s[16:17]
	ds_read_b128 v[94:97], v244 offset:16384
	ds_read_b128 v[144:147], v244 offset:17408
	ds_read_b128 v[148:151], v244 offset:18432
	ds_read_b128 v[152:155], v244 offset:19456
	ds_read_b128 v[156:159], v244 offset:20480
	ds_read_b128 v[160:163], v244 offset:21504
	ds_read_b128 v[164:167], v244 offset:22528
	ds_read_b128 v[168:171], v244 offset:23552
	global_load_lds_dwordx4 v[126:127], off
	v_lshl_add_u64 v[126:127], v[18:19], 0, s[16:17]
	s_mov_b32 m0, s82
	s_nop 0
	global_load_lds_dwordx4 v[126:127], off
	v_lshl_add_u64 v[126:127], s[14:15], 0, v[128:129]
	s_mov_b32 m0, s81
	s_nop 0
	global_load_lds_dwordx4 v[126:127], off
	v_lshl_add_u64 v[126:127], s[14:15], 0, v[32:33]
	s_mov_b32 m0, s80
	s_nop 0
	global_load_lds_dwordx4 v[126:127], off
	v_lshl_add_u64 v[126:127], s[12:13], 0, v[20:21]
	s_mov_b32 m0, s61
	s_nop 0
	global_load_lds_dwordx4 v[126:127], off
	v_lshl_add_u64 v[126:127], s[12:13], 0, v[30:31]
	s_mov_b32 m0, s71
	s_nop 0
	global_load_lds_dwordx4 v[126:127], off
	s_waitcnt vmcnt(8)
	s_waitcnt lgkmcnt(0)
	s_barrier
	s_waitcnt lgkmcnt(0)
	v_mfma_f32_16x16x32_f16 v[172:175], v[34:37], v[94:97], 0
	v_mfma_f32_16x16x32_f16 v[180:183], v[34:37], v[148:151], 0
	v_mfma_f32_16x16x32_f16 v[188:191], v[34:37], v[156:159], 0
	v_mfma_f32_16x16x32_f16 v[34:37], v[34:37], v[164:167], 0
	v_mfma_f32_16x16x32_f16 v[172:175], v[38:41], v[144:147], v[172:175]
	v_mfma_f32_16x16x32_f16 v[180:183], v[38:41], v[152:155], v[180:183]
	v_mfma_f32_16x16x32_f16 v[188:191], v[38:41], v[160:163], v[188:191]
	v_mfma_f32_16x16x32_f16 v[34:37], v[38:41], v[168:171], v[34:37]
	v_mfma_f32_16x16x32_f16 v[38:41], v[42:45], v[164:167], 0
	v_mfma_f32_16x16x32_f16 v[176:179], v[42:45], v[94:97], 0
	v_mfma_f32_16x16x32_f16 v[184:187], v[42:45], v[148:151], 0
	v_mfma_f32_16x16x32_f16 v[192:195], v[42:45], v[156:159], 0
	v_mfma_f32_16x16x32_f16 v[38:41], v[46:49], v[168:171], v[38:41]
	v_mfma_f32_16x16x32_f16 v[176:179], v[46:49], v[144:147], v[176:179]
	v_mfma_f32_16x16x32_f16 v[184:187], v[46:49], v[152:155], v[184:187]
	v_mfma_f32_16x16x32_f16 v[192:195], v[46:49], v[160:163], v[192:195]
	v_mfma_f32_16x16x32_f16 v[42:45], v[50:53], v[94:97], 0
	v_mfma_f32_16x16x32_f16 v[46:49], v[58:61], v[94:97], 0
	v_mfma_f32_16x16x32_f16 v[42:45], v[54:57], v[144:147], v[42:45]
	v_mfma_f32_16x16x32_f16 v[46:49], v[62:65], v[144:147], v[46:49]
	v_mfma_f32_16x16x32_f16 v[94:97], v[50:53], v[148:151], 0
	v_mfma_f32_16x16x32_f16 v[144:147], v[58:61], v[148:151], 0
	v_mfma_f32_16x16x32_f16 v[148:151], v[50:53], v[156:159], 0
	v_mfma_f32_16x16x32_f16 v[50:53], v[50:53], v[164:167], 0
	v_mfma_f32_16x16x32_f16 v[94:97], v[54:57], v[152:155], v[94:97]
	v_mfma_f32_16x16x32_f16 v[148:151], v[54:57], v[160:163], v[148:151]
	v_mfma_f32_16x16x32_f16 v[50:53], v[54:57], v[168:171], v[50:53]
	v_mfma_f32_16x16x32_f16 v[54:57], v[58:61], v[164:167], 0
	v_mfma_f32_16x16x32_f16 v[144:147], v[62:65], v[152:155], v[144:147]
	v_mfma_f32_16x16x32_f16 v[152:155], v[58:61], v[156:159], 0
	v_mfma_f32_16x16x32_f16 v[54:57], v[62:65], v[168:171], v[54:57]
	v_mfma_f32_16x16x32_f16 v[152:155], v[62:65], v[160:163], v[152:155]
	s_barrier
	ds_read_b128 v[58:61], v241
	ds_read_b128 v[62:65], v241 offset:1024
	ds_read_b128 v[156:159], v241 offset:2048
	ds_read_b128 v[160:163], v241 offset:3072
	ds_read_b128 v[164:167], v240
	ds_read_b128 v[168:171], v240 offset:1024
	ds_read_b128 v[196:199], v240 offset:2048
	ds_read_b128 v[200:203], v240 offset:3072
	s_mov_b32 m0, s47
	v_lshl_add_u64 v[126:127], s[10:11], 0, v[20:21]
	ds_read_b128 v[204:207], v244 offset:32768
	ds_read_b128 v[208:211], v244 offset:33792
	ds_read_b128 v[212:215], v244 offset:34816
	ds_read_b128 v[216:219], v244 offset:35840
	ds_read_b128 v[220:223], v244 offset:36864
	ds_read_b128 v[224:227], v244 offset:37888
	ds_read_b128 v[228:231], v244 offset:38912
	ds_read_b128 v[232:235], v244 offset:39936
	global_load_lds_dwordx4 v[126:127], off
	v_lshl_add_u64 v[126:127], s[10:11], 0, v[30:31]
	s_mov_b32 m0, s58
	s_nop 0
	global_load_lds_dwordx4 v[126:127], off
	s_waitcnt vmcnt(8)
	s_waitcnt lgkmcnt(0)
	s_barrier
	s_waitcnt lgkmcnt(0)
	v_mfma_f32_16x16x32_f16 v[98:101], v[58:61], v[204:207], v[98:101]
	v_mfma_f32_16x16x32_f16 v[102:105], v[156:159], v[204:207], v[102:105]
	v_mfma_f32_16x16x32_f16 v[106:109], v[58:61], v[212:215], v[106:109]
	v_mfma_f32_16x16x32_f16 v[110:113], v[156:159], v[212:215], v[110:113]
	v_mfma_f32_16x16x32_f16 v[114:117], v[58:61], v[220:223], v[114:117]
	v_mfma_f32_16x16x32_f16 v[118:121], v[156:159], v[220:223], v[118:121]
	v_mfma_f32_16x16x32_f16 v[122:125], v[58:61], v[228:231], v[122:125]
	v_mfma_f32_16x16x32_f16 v[98:101], v[62:65], v[208:211], v[98:101]
	v_mfma_f32_16x16x32_f16 v[102:105], v[160:163], v[208:211], v[102:105]
	v_mfma_f32_16x16x32_f16 v[106:109], v[62:65], v[216:219], v[106:109]
	v_mfma_f32_16x16x32_f16 v[110:113], v[160:163], v[216:219], v[110:113]
	v_mfma_f32_16x16x32_f16 v[114:117], v[62:65], v[224:227], v[114:117]
	v_mfma_f32_16x16x32_f16 v[118:121], v[160:163], v[224:227], v[118:121]
	v_mfma_f32_16x16x32_f16 v[122:125], v[62:65], v[232:235], v[122:125]
	v_mfma_f32_16x16x32_f16 v[134:137], v[156:159], v[228:231], v[134:137]
	v_mfma_f32_16x16x32_f16 v[134:137], v[160:163], v[232:235], v[134:137]
	v_mfma_f32_16x16x32_f16 v[66:69], v[196:199], v[204:207], v[66:69]
	v_mfma_f32_16x16x32_f16 v[70:73], v[164:167], v[212:215], v[70:73]
	v_mfma_f32_16x16x32_f16 v[74:77], v[196:199], v[212:215], v[74:77]
	v_mfma_f32_16x16x32_f16 v[78:81], v[164:167], v[220:223], v[78:81]
	v_mfma_f32_16x16x32_f16 v[82:85], v[196:199], v[220:223], v[82:85]
	v_mfma_f32_16x16x32_f16 v[86:89], v[164:167], v[228:231], v[86:89]
	v_mfma_f32_16x16x32_f16 v[90:93], v[196:199], v[228:231], v[90:93]
	v_mfma_f32_16x16x32_f16 v[138:141], v[164:167], v[204:207], v[138:141]
	v_mfma_f32_16x16x32_f16 v[66:69], v[200:203], v[208:211], v[66:69]
	v_mfma_f32_16x16x32_f16 v[70:73], v[168:171], v[216:219], v[70:73]
	v_mfma_f32_16x16x32_f16 v[74:77], v[200:203], v[216:219], v[74:77]
	v_mfma_f32_16x16x32_f16 v[78:81], v[168:171], v[224:227], v[78:81]
	v_mfma_f32_16x16x32_f16 v[82:85], v[200:203], v[224:227], v[82:85]
	v_mfma_f32_16x16x32_f16 v[86:89], v[168:171], v[232:235], v[86:89]
	v_mfma_f32_16x16x32_f16 v[90:93], v[200:203], v[232:235], v[90:93]
	v_mfma_f32_16x16x32_f16 v[138:141], v[168:171], v[208:211], v[138:141]
	s_barrier
	s_mov_b64 s[10:11], 0x180
	s_mov_b32 m0, s70
	v_lshl_add_u64 v[126:127], v[16:17], 0, s[10:11]
	ds_read_b128 v[204:207], v244 offset:49152
	ds_read_b128 v[208:211], v244 offset:50176
	ds_read_b128 v[212:215], v244 offset:51200
	ds_read_b128 v[216:219], v244 offset:52224
	ds_read_b128 v[220:223], v244 offset:53248
	ds_read_b128 v[224:227], v244 offset:54272
	ds_read_b128 v[228:231], v244 offset:55296
	ds_read_b128 v[232:235], v244 offset:56320
	global_load_lds_dwordx4 v[126:127], off
	v_lshl_add_u64 v[126:127], v[18:19], 0, s[10:11]
	s_mov_b32 m0, s63
	v_lshl_add_u64 v[32:33], s[8:9], 0, v[32:33]
	global_load_lds_dwordx4 v[126:127], off
	v_lshl_add_u64 v[126:127], s[8:9], 0, v[128:129]
	s_mov_b32 m0, s62
	s_nop 0
	global_load_lds_dwordx4 v[126:127], off
	s_mov_b32 m0, s59
	s_nop 0
	global_load_lds_dwordx4 v[32:33], off
	v_lshl_add_u64 v[32:33], s[6:7], 0, v[20:21]
	s_mov_b32 m0, s34
	s_nop 0
	global_load_lds_dwordx4 v[32:33], off
	v_lshl_add_u64 v[32:33], s[6:7], 0, v[30:31]
	s_mov_b32 m0, s35
	s_nop 0
	global_load_lds_dwordx4 v[32:33], off
	s_waitcnt vmcnt(8)
	s_waitcnt lgkmcnt(0)
	s_barrier
	s_waitcnt lgkmcnt(0)
	v_mfma_f32_16x16x32_f16 v[126:129], v[58:61], v[204:207], v[172:175]
	v_mfma_f32_16x16x32_f16 v[32:35], v[58:61], v[228:231], v[34:37]
	v_mfma_f32_16x16x32_f16 v[36:39], v[156:159], v[228:231], v[38:41]
	v_mfma_f32_16x16x32_f16 v[126:129], v[62:65], v[208:211], v[126:129]
	v_mfma_f32_16x16x32_f16 v[172:175], v[156:159], v[204:207], v[176:179]
	v_mfma_f32_16x16x32_f16 v[176:179], v[58:61], v[212:215], v[180:183]
	v_mfma_f32_16x16x32_f16 v[180:183], v[156:159], v[212:215], v[184:187]
	v_mfma_f32_16x16x32_f16 v[184:187], v[58:61], v[220:223], v[188:191]
	v_mfma_f32_16x16x32_f16 v[188:191], v[156:159], v[220:223], v[192:195]
	v_mfma_f32_16x16x32_f16 v[32:35], v[62:65], v[232:235], v[32:35]
	v_mfma_f32_16x16x32_f16 v[36:39], v[160:163], v[232:235], v[36:39]
	v_mfma_f32_16x16x32_f16 v[172:175], v[160:163], v[208:211], v[172:175]
	v_mfma_f32_16x16x32_f16 v[176:179], v[62:65], v[216:219], v[176:179]
	v_mfma_f32_16x16x32_f16 v[180:183], v[160:163], v[216:219], v[180:183]
	v_mfma_f32_16x16x32_f16 v[184:187], v[62:65], v[224:227], v[184:187]
	v_mfma_f32_16x16x32_f16 v[188:191], v[160:163], v[224:227], v[188:191]
	v_mfma_f32_16x16x32_f16 v[40:43], v[164:167], v[204:207], v[42:45]
	v_mfma_f32_16x16x32_f16 v[44:47], v[196:199], v[204:207], v[46:49]
	v_mfma_f32_16x16x32_f16 v[58:61], v[164:167], v[212:215], v[94:97]
	v_mfma_f32_16x16x32_f16 v[62:65], v[196:199], v[212:215], v[144:147]
	v_mfma_f32_16x16x32_f16 v[94:97], v[164:167], v[220:223], v[148:151]
	v_mfma_f32_16x16x32_f16 v[48:51], v[164:167], v[228:231], v[50:53]
	v_mfma_f32_16x16x32_f16 v[52:55], v[196:199], v[228:231], v[54:57]
	v_mfma_f32_16x16x32_f16 v[40:43], v[168:171], v[208:211], v[40:43]
	v_mfma_f32_16x16x32_f16 v[44:47], v[200:203], v[208:211], v[44:47]
	v_mfma_f32_16x16x32_f16 v[58:61], v[168:171], v[216:219], v[58:61]
	v_mfma_f32_16x16x32_f16 v[62:65], v[200:203], v[216:219], v[62:65]
	v_mfma_f32_16x16x32_f16 v[94:97], v[168:171], v[224:227], v[94:97]
	v_mfma_f32_16x16x32_f16 v[144:147], v[196:199], v[220:223], v[152:155]
	v_mfma_f32_16x16x32_f16 v[48:51], v[168:171], v[232:235], v[48:51]
	v_mfma_f32_16x16x32_f16 v[52:55], v[200:203], v[232:235], v[52:55]
	v_mfma_f32_16x16x32_f16 v[144:147], v[200:203], v[224:227], v[144:147]
	s_barrier
	ds_read_b128 v[148:151], v131
	ds_read_b128 v[152:155], v131 offset:1024
	ds_read_b128 v[156:159], v131 offset:2048
	ds_read_b128 v[160:163], v131 offset:3072
	ds_read_b128 v[164:167], v130
	ds_read_b128 v[168:171], v130 offset:1024
	ds_read_b128 v[192:195], v130 offset:2048
	ds_read_b128 v[196:199], v130 offset:3072
	s_mov_b32 m0, s85
	v_lshl_add_u64 v[20:21], s[4:5], 0, v[20:21]
	ds_read_b128 v[200:203], v244
	ds_read_b128 v[204:207], v244 offset:1024
	ds_read_b128 v[208:211], v244 offset:2048
	ds_read_b128 v[212:215], v244 offset:3072
	ds_read_b128 v[216:219], v244 offset:4096
	ds_read_b128 v[220:223], v244 offset:5120
	ds_read_b128 v[224:227], v244 offset:6144
	ds_read_b128 v[228:231], v244 offset:7168
	global_load_lds_dwordx4 v[20:21], off
	v_lshl_add_u64 v[20:21], s[4:5], 0, v[30:31]
	s_mov_b32 m0, s84
	s_nop 0
	global_load_lds_dwordx4 v[20:21], off
	s_waitcnt vmcnt(8)
	s_waitcnt lgkmcnt(0)
	s_barrier
	s_waitcnt lgkmcnt(0)
	v_mfma_f32_16x16x32_f16 v[110:113], v[156:159], v[208:211], v[110:113]
	v_mfma_f32_16x16x32_f16 v[232:235], v[160:163], v[212:215], v[110:113]
	v_mfma_f32_16x16x32_f16 v[110:113], v[148:151], v[216:219], v[114:117]
	v_mfma_f32_16x16x32_f16 v[116:119], v[156:159], v[216:219], v[118:121]
	v_mfma_f32_16x16x32_f16 v[98:101], v[148:151], v[200:203], v[98:101]
	v_mfma_f32_16x16x32_f16 v[102:105], v[156:159], v[200:203], v[102:105]
	v_mfma_f32_16x16x32_f16 v[106:109], v[148:151], v[208:211], v[106:109]
	v_mfma_f32_16x16x32_f16 v[236:239], v[160:163], v[220:223], v[116:119]
	v_mfma_f32_16x16x32_f16 v[116:119], v[148:151], v[224:227], v[122:125]
	v_mfma_f32_16x16x32_f16 v[98:101], v[152:155], v[204:207], v[98:101]
	v_mfma_f32_16x16x32_f16 v[102:105], v[160:163], v[204:207], v[102:105]
	v_mfma_f32_16x16x32_f16 v[106:109], v[152:155], v[212:215], v[106:109]
	v_mfma_f32_16x16x32_f16 v[112:115], v[152:155], v[220:223], v[110:113]
	v_mfma_f32_16x16x32_f16 v[120:123], v[152:155], v[228:231], v[116:119]
	v_mfma_f32_16x16x32_f16 v[116:119], v[156:159], v[224:227], v[134:137]
	v_mfma_f32_16x16x32_f16 v[134:137], v[160:163], v[228:231], v[116:119]
	v_mfma_f32_16x16x32_f16 v[66:69], v[192:195], v[200:203], v[66:69]
	v_mfma_f32_16x16x32_f16 v[116:119], v[164:167], v[200:203], v[138:141]
	v_mfma_f32_16x16x32_f16 v[200:203], v[196:199], v[204:207], v[66:69]
	v_mfma_f32_16x16x32_f16 v[66:69], v[164:167], v[208:211], v[70:73]
	v_mfma_f32_16x16x32_f16 v[138:141], v[168:171], v[204:207], v[116:119]
	v_mfma_f32_16x16x32_f16 v[204:207], v[168:171], v[212:215], v[66:69]
	v_mfma_f32_16x16x32_f16 v[66:69], v[192:195], v[208:211], v[74:77]
	v_mfma_f32_16x16x32_f16 v[72:75], v[196:199], v[212:215], v[66:69]
	v_mfma_f32_16x16x32_f16 v[66:69], v[164:167], v[216:219], v[78:81]
	v_mfma_f32_16x16x32_f16 v[208:211], v[168:171], v[220:223], v[66:69]
	v_mfma_f32_16x16x32_f16 v[66:69], v[192:195], v[216:219], v[82:85]
	v_mfma_f32_16x16x32_f16 v[80:83], v[196:199], v[220:223], v[66:69]
	v_mfma_f32_16x16x32_f16 v[66:69], v[164:167], v[224:227], v[86:89]
	v_mfma_f32_16x16x32_f16 v[212:215], v[168:171], v[228:231], v[66:69]
	v_mfma_f32_16x16x32_f16 v[66:69], v[192:195], v[224:227], v[90:93]
	v_mfma_f32_16x16x32_f16 v[216:219], v[196:199], v[228:231], v[66:69]
	s_barrier
	s_mov_b32 m0, s83
	s_nop 3
	ds_read_b128 v[66:69], v244 offset:16384
	ds_read_b128 v[76:79], v244 offset:17408
	ds_read_b128 v[84:87], v244 offset:18432
	ds_read_b128 v[88:91], v244 offset:19456
	ds_read_b128 v[116:119], v244 offset:20480
	ds_read_b128 v[220:223], v244 offset:21504
	ds_read_b128 v[224:227], v244 offset:22528
	ds_read_b128 v[228:231], v244 offset:23552
	global_load_lds_dwordx4 v[16:17], off
	s_mov_b32 m0, s82
	s_nop 0
	global_load_lds_dwordx4 v[18:19], off
	s_mov_b32 m0, s81
	s_nop 0
	global_load_lds_dwordx4 v[28:29], off
	s_mov_b32 m0, s80
	s_nop 0
	global_load_lds_dwordx4 v[22:23], off
	s_mov_b32 m0, s61
	s_nop 0
	global_load_lds_dwordx4 v[24:25], off
	s_mov_b32 m0, s71
	s_nop 0
	global_load_lds_dwordx4 v[26:27], off
	s_waitcnt vmcnt(8)
	s_waitcnt lgkmcnt(0)
	s_barrier
	s_waitcnt lgkmcnt(0)
	v_mfma_f32_16x16x32_f16 v[16:19], v[148:151], v[66:69], v[126:129]
	v_mfma_f32_16x16x32_f16 v[20:23], v[156:159], v[66:69], v[172:175]
	v_mfma_f32_16x16x32_f16 v[24:27], v[148:151], v[84:87], v[176:179]
	v_mfma_f32_16x16x32_f16 v[28:31], v[156:159], v[84:87], v[180:183]
	v_mfma_f32_16x16x32_f16 v[124:127], v[148:151], v[116:119], v[184:187]
	v_mfma_f32_16x16x32_f16 v[32:35], v[148:151], v[224:227], v[32:35]
	v_mfma_f32_16x16x32_f16 v[16:19], v[152:155], v[76:79], v[16:19]
	v_mfma_f32_16x16x32_f16 v[20:23], v[160:163], v[76:79], v[20:23]
	v_mfma_f32_16x16x32_f16 v[24:27], v[152:155], v[88:91], v[24:27]
	v_mfma_f32_16x16x32_f16 v[28:31], v[160:163], v[88:91], v[28:31]
	v_mfma_f32_16x16x32_f16 v[128:131], v[152:155], v[220:223], v[124:127]
	v_mfma_f32_16x16x32_f16 v[124:127], v[156:159], v[116:119], v[188:191]
	v_mfma_f32_16x16x32_f16 v[32:35], v[152:155], v[228:231], v[32:35]
	v_mfma_f32_16x16x32_f16 v[36:39], v[156:159], v[224:227], v[36:39]
	v_mfma_f32_16x16x32_f16 v[172:175], v[160:163], v[220:223], v[124:127]
	v_mfma_f32_16x16x32_f16 v[148:151], v[160:163], v[228:231], v[36:39]
	v_mfma_f32_16x16x32_f16 v[36:39], v[164:167], v[66:69], v[40:43]
	v_mfma_f32_16x16x32_f16 v[40:43], v[168:171], v[76:79], v[36:39]
	v_mfma_f32_16x16x32_f16 v[36:39], v[192:195], v[66:69], v[44:47]
	v_mfma_f32_16x16x32_f16 v[152:155], v[196:199], v[76:79], v[36:39]
	v_mfma_f32_16x16x32_f16 v[36:39], v[164:167], v[84:87], v[58:61]
	v_mfma_f32_16x16x32_f16 v[156:159], v[168:171], v[88:91], v[36:39]
	v_mfma_f32_16x16x32_f16 v[36:39], v[192:195], v[84:87], v[62:65]
	v_mfma_f32_16x16x32_f16 v[160:163], v[196:199], v[88:91], v[36:39]
	v_mfma_f32_16x16x32_f16 v[36:39], v[164:167], v[116:119], v[94:97]
	v_mfma_f32_16x16x32_f16 v[176:179], v[168:171], v[220:223], v[36:39]
	v_mfma_f32_16x16x32_f16 v[36:39], v[192:195], v[116:119], v[144:147]
	v_mfma_f32_16x16x32_f16 v[144:147], v[196:199], v[220:223], v[36:39]
	v_mfma_f32_16x16x32_f16 v[36:39], v[164:167], v[224:227], v[48:51]
	v_mfma_f32_16x16x32_f16 v[164:167], v[168:171], v[228:231], v[36:39]
	v_mfma_f32_16x16x32_f16 v[36:39], v[192:195], v[224:227], v[52:55]
	v_mfma_f32_16x16x32_f16 v[168:171], v[196:199], v[228:231], v[36:39]
	s_barrier
	ds_read_b128 v[48:51], v241
	ds_read_b128 v[56:59], v241 offset:1024
	ds_read_b128 v[180:183], v241 offset:2048
	ds_read_b128 v[184:187], v241 offset:3072
	ds_read_b128 v[188:191], v240
	ds_read_b128 v[192:195], v240 offset:1024
	ds_read_b128 v[196:199], v240 offset:2048
	ds_read_b128 v[220:223], v240 offset:3072
	s_mov_b32 m0, s47
	ds_read_b128 v[36:39], v244 offset:32768
	ds_read_b128 v[44:47], v244 offset:33792
	ds_read_b128 v[52:55], v244 offset:34816
	ds_read_b128 v[60:63], v244 offset:35840
	ds_read_b128 v[64:67], v244 offset:36864
	ds_read_b128 v[224:227], v244 offset:37888
	ds_read_b128 v[228:231], v244 offset:38912
	ds_read_b128 v[240:243], v244 offset:39936
	global_load_lds_dwordx4 v[14:15], off
	s_mov_b32 m0, s58
	s_nop 0
	global_load_lds_dwordx4 v[12:13], off
	s_waitcnt vmcnt(8)
	s_waitcnt lgkmcnt(0)
	s_barrier
	s_waitcnt lgkmcnt(0)
	v_mfma_f32_16x16x32_f16 v[12:15], v[48:51], v[36:39], v[98:101]
	v_mfma_f32_16x16x32_f16 v[124:127], v[56:59], v[44:47], v[12:15]
	v_mfma_f32_16x16x32_f16 v[12:15], v[180:183], v[36:39], v[102:105]
	v_mfma_f32_16x16x32_f16 v[116:119], v[184:187], v[44:47], v[12:15]
	v_mfma_f32_16x16x32_f16 v[12:15], v[48:51], v[52:55], v[106:109]
	v_mfma_f32_16x16x32_f16 v[108:111], v[56:59], v[60:63], v[12:15]
	v_mfma_f32_16x16x32_f16 v[12:15], v[180:183], v[52:55], v[232:235]
	v_mfma_f32_16x16x32_f16 v[100:103], v[184:187], v[60:63], v[12:15]
	v_mfma_f32_16x16x32_f16 v[12:15], v[48:51], v[64:67], v[112:115]
	v_mfma_f32_16x16x32_f16 v[92:95], v[56:59], v[224:227], v[12:15]
	v_mfma_f32_16x16x32_f16 v[12:15], v[180:183], v[64:67], v[236:239]
	v_mfma_f32_16x16x32_f16 v[84:87], v[184:187], v[224:227], v[12:15]
	v_mfma_f32_16x16x32_f16 v[12:15], v[48:51], v[228:231], v[120:123]
	v_mfma_f32_16x16x32_f16 v[76:79], v[56:59], v[240:243], v[12:15]
	v_mfma_f32_16x16x32_f16 v[12:15], v[180:183], v[228:231], v[134:137]
	v_mfma_f32_16x16x32_f16 v[68:71], v[184:187], v[240:243], v[12:15]
	v_mfma_f32_16x16x32_f16 v[12:15], v[188:191], v[36:39], v[138:141]
	v_mfma_f32_16x16x32_f16 v[120:123], v[192:195], v[44:47], v[12:15]
	v_mfma_f32_16x16x32_f16 v[12:15], v[196:199], v[36:39], v[200:203]
	v_mfma_f32_16x16x32_f16 v[112:115], v[220:223], v[44:47], v[12:15]
	v_mfma_f32_16x16x32_f16 v[12:15], v[188:191], v[52:55], v[204:207]
	v_mfma_f32_16x16x32_f16 v[104:107], v[192:195], v[60:63], v[12:15]
	v_mfma_f32_16x16x32_f16 v[12:15], v[196:199], v[52:55], v[72:75]
	v_mfma_f32_16x16x32_f16 v[96:99], v[220:223], v[60:63], v[12:15]
	v_mfma_f32_16x16x32_f16 v[12:15], v[188:191], v[64:67], v[208:211]
	v_mfma_f32_16x16x32_f16 v[88:91], v[192:195], v[224:227], v[12:15]
	v_mfma_f32_16x16x32_f16 v[12:15], v[196:199], v[64:67], v[80:83]
	v_mfma_f32_16x16x32_f16 v[80:83], v[220:223], v[224:227], v[12:15]
	v_mfma_f32_16x16x32_f16 v[12:15], v[188:191], v[228:231], v[212:215]
	v_mfma_f32_16x16x32_f16 v[72:75], v[192:195], v[240:243], v[12:15]
	v_mfma_f32_16x16x32_f16 v[12:15], v[196:199], v[228:231], v[216:219]
	v_mfma_f32_16x16x32_f16 v[64:67], v[220:223], v[240:243], v[12:15]
	s_barrier
	s_mov_b32 m0, s70
	ds_read_b128 v[134:137], v244 offset:49152
	ds_read_b128 v[138:141], v244 offset:50176
	ds_read_b128 v[200:203], v244 offset:51200
	ds_read_b128 v[204:207], v244 offset:52224
	ds_read_b128 v[208:211], v244 offset:53248
	ds_read_b128 v[212:215], v244 offset:54272
	ds_read_b128 v[216:219], v244 offset:55296
	ds_read_b128 v[224:227], v244 offset:56320
	global_load_lds_dwordx4 v[0:1], off
	s_mov_b32 m0, s63
	s_nop 0
	global_load_lds_dwordx4 v[2:3], off
	s_mov_b32 m0, s62
	s_nop 0
	global_load_lds_dwordx4 v[8:9], off
	s_mov_b32 m0, s59
	s_nop 0
	global_load_lds_dwordx4 v[10:11], off
	s_mov_b32 m0, s34
	s_nop 0
	global_load_lds_dwordx4 v[6:7], off
	s_mov_b32 m0, s35
	s_nop 0
	global_load_lds_dwordx4 v[4:5], off
	s_waitcnt vmcnt(8)
	s_waitcnt lgkmcnt(0)
	s_barrier
	s_waitcnt lgkmcnt(0)
	v_mfma_f32_16x16x32_f16 v[0:3], v[48:51], v[134:137], v[16:19]
	v_mfma_f32_16x16x32_f16 v[60:63], v[56:59], v[138:141], v[0:3]
	v_mfma_f32_16x16x32_f16 v[0:3], v[180:183], v[134:137], v[20:23]
	v_mfma_f32_16x16x32_f16 v[52:55], v[184:187], v[138:141], v[0:3]
	v_mfma_f32_16x16x32_f16 v[0:3], v[48:51], v[200:203], v[24:27]
	v_mfma_f32_16x16x32_f16 v[44:47], v[56:59], v[204:207], v[0:3]
	v_mfma_f32_16x16x32_f16 v[0:3], v[180:183], v[200:203], v[28:31]
	v_mfma_f32_16x16x32_f16 v[36:39], v[184:187], v[204:207], v[0:3]
	v_mfma_f32_16x16x32_f16 v[0:3], v[48:51], v[208:211], v[128:131]
	v_mfma_f32_16x16x32_f16 v[28:31], v[56:59], v[212:215], v[0:3]
	v_mfma_f32_16x16x32_f16 v[0:3], v[180:183], v[208:211], v[172:175]
	v_mfma_f32_16x16x32_f16 v[20:23], v[184:187], v[212:215], v[0:3]
	v_mfma_f32_16x16x32_f16 v[0:3], v[48:51], v[216:219], v[32:35]
	v_mfma_f32_16x16x32_f16 v[12:15], v[56:59], v[224:227], v[0:3]
	v_mfma_f32_16x16x32_f16 v[0:3], v[180:183], v[216:219], v[148:151]
	v_mfma_f32_16x16x32_f16 v[4:7], v[184:187], v[224:227], v[0:3]
	v_mfma_f32_16x16x32_f16 v[0:3], v[188:191], v[134:137], v[40:43]
	v_mfma_f32_16x16x32_f16 v[56:59], v[192:195], v[138:141], v[0:3]
	v_mfma_f32_16x16x32_f16 v[0:3], v[196:199], v[134:137], v[152:155]
	v_mfma_f32_16x16x32_f16 v[48:51], v[220:223], v[138:141], v[0:3]
	v_mfma_f32_16x16x32_f16 v[0:3], v[188:191], v[200:203], v[156:159]
	v_mfma_f32_16x16x32_f16 v[40:43], v[192:195], v[204:207], v[0:3]
	v_mfma_f32_16x16x32_f16 v[0:3], v[196:199], v[200:203], v[160:163]
	v_mfma_f32_16x16x32_f16 v[32:35], v[220:223], v[204:207], v[0:3]
	v_mfma_f32_16x16x32_f16 v[0:3], v[188:191], v[208:211], v[176:179]
	v_mfma_f32_16x16x32_f16 v[24:27], v[192:195], v[212:215], v[0:3]
	v_mfma_f32_16x16x32_f16 v[0:3], v[196:199], v[208:211], v[144:147]
	v_mfma_f32_16x16x32_f16 v[16:19], v[220:223], v[212:215], v[0:3]
	v_mfma_f32_16x16x32_f16 v[0:3], v[188:191], v[216:219], v[164:167]
	v_mfma_f32_16x16x32_f16 v[8:11], v[192:195], v[224:227], v[0:3]
	v_mfma_f32_16x16x32_f16 v[0:3], v[196:199], v[216:219], v[168:171]
	v_mfma_f32_16x16x32_f16 v[0:3], v[220:223], v[224:227], v[0:3]
	s_barrier
	v_readlane_b32 s72, v255, 34
	s_andn2_b64 vcc, exec, s[26:27]
	v_readlane_b32 s73, v255, 35
	s_cbranch_vccnz .LBB0_940
	s_barrier

.LBB0_1044:
	v_add_u32_e32 v136, s67, v144
	ds_read_b128 v[156:159], v136
	ds_read_b128 v[160:163], v136 offset:1024
	ds_read_b128 v[164:167], v136 offset:2048
	ds_read_b128 v[168:171], v136 offset:3072
	ds_read_b128 v[172:175], v153
	ds_read_b128 v[176:179], v153 offset:1024
	ds_read_b128 v[180:183], v153 offset:2048
	ds_read_b128 v[184:187], v153 offset:3072
	s_add_u32 s42, s34, 0xfffc0080
	s_addc_u32 s43, s35, -1
	s_cmp_eq_u32 s85, 12
	s_cselect_b32 s45, s5, s43
	s_cselect_b32 s44, s29, s42
	s_cselect_b32 s43, s33, s84
	s_cselect_b32 s42, s82, s83
	v_lshl_add_u64 v[142:143], s[34:35], 0, v[138:139]
	s_add_i32 m0, s3, 0xc000
	ds_read_b128 v[188:191], v154
	ds_read_b128 v[192:195], v154 offset:1024
	ds_read_b128 v[196:199], v154 offset:2048
	ds_read_b128 v[200:203], v154 offset:3072
	ds_read_b128 v[204:207], v154 offset:4096
	ds_read_b128 v[208:211], v154 offset:5120
	ds_read_b128 v[212:215], v154 offset:6144
	ds_read_b128 v[216:219], v154 offset:7168
	global_load_lds_dwordx4 v[142:143], off
	v_lshl_add_u64 v[142:143], s[34:35], 0, v[140:141]
	s_add_i32 m0, s3, 0xe000
	s_nop 0
	global_load_lds_dwordx4 v[142:143], off
	s_waitcnt vmcnt(8)
	s_waitcnt lgkmcnt(0)
	s_barrier
	s_waitcnt lgkmcnt(0)
	v_mfma_f32_16x16x32_f16 v[124:127], v[156:159], v[188:191], v[124:127]
	v_mfma_f32_16x16x32_f16 v[120:123], v[164:167], v[188:191], v[120:123]
	v_mfma_f32_16x16x32_f16 v[108:111], v[156:159], v[196:199], v[108:111]
	v_mfma_f32_16x16x32_f16 v[104:107], v[164:167], v[196:199], v[104:107]
	v_mfma_f32_16x16x32_f16 v[92:95], v[156:159], v[204:207], v[92:95]
	v_mfma_f32_16x16x32_f16 v[88:91], v[164:167], v[204:207], v[88:91]
	v_mfma_f32_16x16x32_f16 v[76:79], v[156:159], v[212:215], v[76:79]
	v_mfma_f32_16x16x32_f16 v[72:75], v[164:167], v[212:215], v[72:75]
	v_mfma_f32_16x16x32_f16 v[124:127], v[160:163], v[192:195], v[124:127]
	v_mfma_f32_16x16x32_f16 v[120:123], v[168:171], v[192:195], v[120:123]
	v_mfma_f32_16x16x32_f16 v[108:111], v[160:163], v[200:203], v[108:111]
	v_mfma_f32_16x16x32_f16 v[104:107], v[168:171], v[200:203], v[104:107]
	v_mfma_f32_16x16x32_f16 v[92:95], v[160:163], v[208:211], v[92:95]
	v_mfma_f32_16x16x32_f16 v[88:91], v[168:171], v[208:211], v[88:91]
	v_mfma_f32_16x16x32_f16 v[76:79], v[160:163], v[216:219], v[76:79]
	v_mfma_f32_16x16x32_f16 v[72:75], v[168:171], v[216:219], v[72:75]
	v_mfma_f32_16x16x32_f16 v[116:119], v[172:175], v[188:191], v[116:119]
	v_mfma_f32_16x16x32_f16 v[112:115], v[180:183], v[188:191], v[112:115]
	v_mfma_f32_16x16x32_f16 v[100:103], v[172:175], v[196:199], v[100:103]
	v_mfma_f32_16x16x32_f16 v[96:99], v[180:183], v[196:199], v[96:99]
	v_mfma_f32_16x16x32_f16 v[84:87], v[172:175], v[204:207], v[84:87]
	v_mfma_f32_16x16x32_f16 v[80:83], v[180:183], v[204:207], v[80:83]
	v_mfma_f32_16x16x32_f16 v[68:71], v[172:175], v[212:215], v[68:71]
	v_mfma_f32_16x16x32_f16 v[64:67], v[180:183], v[212:215], v[64:67]
	v_mfma_f32_16x16x32_f16 v[116:119], v[176:179], v[192:195], v[116:119]
	v_mfma_f32_16x16x32_f16 v[112:115], v[184:187], v[192:195], v[112:115]
	v_mfma_f32_16x16x32_f16 v[100:103], v[176:179], v[200:203], v[100:103]
	v_mfma_f32_16x16x32_f16 v[96:99], v[184:187], v[200:203], v[96:99]
	v_mfma_f32_16x16x32_f16 v[84:87], v[176:179], v[208:211], v[84:87]
	v_mfma_f32_16x16x32_f16 v[80:83], v[184:187], v[208:211], v[80:83]
	v_mfma_f32_16x16x32_f16 v[68:71], v[176:179], v[216:219], v[68:71]
	v_mfma_f32_16x16x32_f16 v[64:67], v[184:187], v[216:219], v[64:67]
	s_barrier
	s_add_i32 s86, s67, s66
	v_lshl_add_u64 v[142:143], s[42:43], 0, v[130:131]
	s_mov_b32 m0, s86
	ds_read_b128 v[188:191], v154 offset:16384
	ds_read_b128 v[192:195], v154 offset:17408
	ds_read_b128 v[196:199], v154 offset:18432
	ds_read_b128 v[200:203], v154 offset:19456
	ds_read_b128 v[204:207], v154 offset:20480
	ds_read_b128 v[208:211], v154 offset:21504
	ds_read_b128 v[212:215], v154 offset:22528
	ds_read_b128 v[216:219], v154 offset:23552
	global_load_lds_dwordx4 v[142:143], off
	s_add_i32 m0, s86, 0x2000
	s_add_u32 s86, s42, 0x40000
	v_lshl_add_u64 v[220:221], s[42:43], 0, v[134:135]
	s_addc_u32 s87, s43, 0
	s_add_i32 s88, s70, s66
	global_load_lds_dwordx4 v[220:221], off
	v_lshl_add_u64 v[222:223], s[86:87], 0, v[130:131]
	s_mov_b32 m0, s88
	v_lshl_add_u64 v[224:225], s[44:45], 0, v[132:133]
	global_load_lds_dwordx4 v[222:223], off
	v_lshl_add_u64 v[222:223], s[86:87], 0, v[134:135]
	s_add_i32 m0, s88, 0x2000
	s_nop 0
	global_load_lds_dwordx4 v[222:223], off
	v_lshl_add_u64 v[222:223], s[44:45], 0, v[128:129]
	s_mov_b32 m0, s3
	s_nop 0
	global_load_lds_dwordx4 v[222:223], off
	s_mov_b32 m0, s31
	s_nop 0
	global_load_lds_dwordx4 v[224:225], off
	s_waitcnt vmcnt(8)
	s_waitcnt lgkmcnt(0)
	s_barrier
	s_waitcnt lgkmcnt(0)
	v_mfma_f32_16x16x32_f16 v[60:63], v[156:159], v[188:191], v[60:63]
	v_mfma_f32_16x16x32_f16 v[56:59], v[164:167], v[188:191], v[56:59]
	v_mfma_f32_16x16x32_f16 v[44:47], v[156:159], v[196:199], v[44:47]
	v_mfma_f32_16x16x32_f16 v[40:43], v[164:167], v[196:199], v[40:43]
	v_mfma_f32_16x16x32_f16 v[28:31], v[156:159], v[204:207], v[28:31]
	v_mfma_f32_16x16x32_f16 v[24:27], v[164:167], v[204:207], v[24:27]
	v_mfma_f32_16x16x32_f16 v[12:15], v[156:159], v[212:215], v[12:15]
	v_mfma_f32_16x16x32_f16 v[8:11], v[164:167], v[212:215], v[8:11]
	v_mfma_f32_16x16x32_f16 v[60:63], v[160:163], v[192:195], v[60:63]
	v_mfma_f32_16x16x32_f16 v[56:59], v[168:171], v[192:195], v[56:59]
	v_mfma_f32_16x16x32_f16 v[44:47], v[160:163], v[200:203], v[44:47]
	v_mfma_f32_16x16x32_f16 v[40:43], v[168:171], v[200:203], v[40:43]
	v_mfma_f32_16x16x32_f16 v[28:31], v[160:163], v[208:211], v[28:31]
	v_mfma_f32_16x16x32_f16 v[24:27], v[168:171], v[208:211], v[24:27]
	v_mfma_f32_16x16x32_f16 v[12:15], v[160:163], v[216:219], v[12:15]
	v_mfma_f32_16x16x32_f16 v[8:11], v[168:171], v[216:219], v[8:11]
	v_mfma_f32_16x16x32_f16 v[52:55], v[172:175], v[188:191], v[52:55]
	v_mfma_f32_16x16x32_f16 v[48:51], v[180:183], v[188:191], v[48:51]
	v_mfma_f32_16x16x32_f16 v[36:39], v[172:175], v[196:199], v[36:39]
	v_mfma_f32_16x16x32_f16 v[32:35], v[180:183], v[196:199], v[32:35]
	v_mfma_f32_16x16x32_f16 v[20:23], v[172:175], v[204:207], v[20:23]
	v_mfma_f32_16x16x32_f16 v[16:19], v[180:183], v[204:207], v[16:19]
	v_mfma_f32_16x16x32_f16 v[4:7], v[172:175], v[212:215], v[4:7]
	v_mfma_f32_16x16x32_f16 v[0:3], v[180:183], v[212:215], v[0:3]
	v_mfma_f32_16x16x32_f16 v[52:55], v[176:179], v[192:195], v[52:55]
	v_mfma_f32_16x16x32_f16 v[48:51], v[184:187], v[192:195], v[48:51]
	v_mfma_f32_16x16x32_f16 v[36:39], v[176:179], v[200:203], v[36:39]
	v_mfma_f32_16x16x32_f16 v[32:35], v[184:187], v[200:203], v[32:35]
	v_mfma_f32_16x16x32_f16 v[20:23], v[176:179], v[208:211], v[20:23]
	v_mfma_f32_16x16x32_f16 v[16:19], v[184:187], v[208:211], v[16:19]
	v_mfma_f32_16x16x32_f16 v[4:7], v[176:179], v[216:219], v[4:7]
	v_mfma_f32_16x16x32_f16 v[0:3], v[184:187], v[216:219], v[0:3]
	s_barrier
	s_add_i32 s86, 0, 0x18000
	v_add_u32_e32 v136, s86, v144
	ds_read_b128 v[156:159], v136
	ds_read_b128 v[160:163], v136 offset:1024
	ds_read_b128 v[164:167], v136 offset:2048
	ds_read_b128 v[168:171], v136 offset:3072
	ds_read_b128 v[172:175], v155
	ds_read_b128 v[176:179], v155 offset:1024
	ds_read_b128 v[180:183], v155 offset:2048
	ds_read_b128 v[184:187], v155 offset:3072
	s_add_u32 s44, s44, 0x40000
	s_addc_u32 s45, s45, 0
	s_mov_b32 m0, s46
	v_lshl_add_u64 v[226:227], s[44:45], 0, v[128:129]
	ds_read_b128 v[188:191], v154 offset:32768
	ds_read_b128 v[192:195], v154 offset:33792
	ds_read_b128 v[196:199], v154 offset:34816
	ds_read_b128 v[200:203], v154 offset:35840
	ds_read_b128 v[204:207], v154 offset:36864
	ds_read_b128 v[208:211], v154 offset:37888
	ds_read_b128 v[212:215], v154 offset:38912
	ds_read_b128 v[216:219], v154 offset:39936
	global_load_lds_dwordx4 v[226:227], off
	v_lshl_add_u64 v[226:227], s[44:45], 0, v[132:133]
	s_mov_b32 m0, s47
	s_nop 0
	global_load_lds_dwordx4 v[226:227], off
	s_waitcnt vmcnt(8)
	s_waitcnt lgkmcnt(0)
	s_barrier
	s_waitcnt lgkmcnt(0)
	v_mfma_f32_16x16x32_f16 v[124:127], v[156:159], v[188:191], v[124:127]
	v_mfma_f32_16x16x32_f16 v[120:123], v[164:167], v[188:191], v[120:123]
	v_mfma_f32_16x16x32_f16 v[108:111], v[156:159], v[196:199], v[108:111]
	v_mfma_f32_16x16x32_f16 v[104:107], v[164:167], v[196:199], v[104:107]
	v_mfma_f32_16x16x32_f16 v[92:95], v[156:159], v[204:207], v[92:95]
	v_mfma_f32_16x16x32_f16 v[88:91], v[164:167], v[204:207], v[88:91]
	v_mfma_f32_16x16x32_f16 v[76:79], v[156:159], v[212:215], v[76:79]
	v_mfma_f32_16x16x32_f16 v[72:75], v[164:167], v[212:215], v[72:75]
	v_mfma_f32_16x16x32_f16 v[124:127], v[160:163], v[192:195], v[124:127]
	v_mfma_f32_16x16x32_f16 v[120:123], v[168:171], v[192:195], v[120:123]
	v_mfma_f32_16x16x32_f16 v[108:111], v[160:163], v[200:203], v[108:111]
	v_mfma_f32_16x16x32_f16 v[104:107], v[168:171], v[200:203], v[104:107]
	v_mfma_f32_16x16x32_f16 v[92:95], v[160:163], v[208:211], v[92:95]
	v_mfma_f32_16x16x32_f16 v[88:91], v[168:171], v[208:211], v[88:91]
	v_mfma_f32_16x16x32_f16 v[76:79], v[160:163], v[216:219], v[76:79]
	v_mfma_f32_16x16x32_f16 v[72:75], v[168:171], v[216:219], v[72:75]
	v_mfma_f32_16x16x32_f16 v[116:119], v[172:175], v[188:191], v[116:119]
	v_mfma_f32_16x16x32_f16 v[112:115], v[180:183], v[188:191], v[112:115]
	v_mfma_f32_16x16x32_f16 v[100:103], v[172:175], v[196:199], v[100:103]
	v_mfma_f32_16x16x32_f16 v[96:99], v[180:183], v[196:199], v[96:99]
	v_mfma_f32_16x16x32_f16 v[84:87], v[172:175], v[204:207], v[84:87]
	v_mfma_f32_16x16x32_f16 v[80:83], v[180:183], v[204:207], v[80:83]
	v_mfma_f32_16x16x32_f16 v[68:71], v[172:175], v[212:215], v[68:71]
	v_mfma_f32_16x16x32_f16 v[64:67], v[180:183], v[212:215], v[64:67]
	v_mfma_f32_16x16x32_f16 v[116:119], v[176:179], v[192:195], v[116:119]
	v_mfma_f32_16x16x32_f16 v[112:115], v[184:187], v[192:195], v[112:115]
	v_mfma_f32_16x16x32_f16 v[100:103], v[176:179], v[200:203], v[100:103]
	v_mfma_f32_16x16x32_f16 v[96:99], v[184:187], v[200:203], v[96:99]
	v_mfma_f32_16x16x32_f16 v[84:87], v[176:179], v[208:211], v[84:87]
	v_mfma_f32_16x16x32_f16 v[80:83], v[184:187], v[208:211], v[80:83]
	v_mfma_f32_16x16x32_f16 v[68:71], v[176:179], v[216:219], v[68:71]
	v_mfma_f32_16x16x32_f16 v[64:67], v[184:187], v[216:219], v[64:67]
	s_barrier
	s_add_i32 s44, s86, s66
	v_lshl_add_u64 v[142:143], v[142:143], 0, s[6:7]
	s_mov_b32 m0, s44
	ds_read_b128 v[188:191], v154 offset:49152
	ds_read_b128 v[192:195], v154 offset:50176
	ds_read_b128 v[196:199], v154 offset:51200
	ds_read_b128 v[200:203], v154 offset:52224
	ds_read_b128 v[204:207], v154 offset:53248
	ds_read_b128 v[208:211], v154 offset:54272
	ds_read_b128 v[212:215], v154 offset:55296
	ds_read_b128 v[216:219], v154 offset:56320
	global_load_lds_dwordx4 v[142:143], off
	s_add_i32 m0, s44, 0x2000
	s_add_u32 s42, s42, 0x40080
	v_lshl_add_u64 v[142:143], v[220:221], 0, s[6:7]
	s_addc_u32 s43, s43, 0
	s_add_i32 s44, s71, s66
	global_load_lds_dwordx4 v[142:143], off
	v_lshl_add_u64 v[142:143], s[42:43], 0, v[130:131]
	s_mov_b32 m0, s44
	s_nop 0
	global_load_lds_dwordx4 v[142:143], off
	v_lshl_add_u64 v[142:143], s[42:43], 0, v[134:135]
	s_add_i32 m0, s44, 0x2000
	s_nop 0
	global_load_lds_dwordx4 v[142:143], off
	v_lshl_add_u64 v[142:143], v[222:223], 0, s[6:7]
	s_mov_b32 m0, s48
	s_nop 0
	global_load_lds_dwordx4 v[142:143], off
	v_lshl_add_u64 v[142:143], v[224:225], 0, s[6:7]
	s_mov_b32 m0, s49
	s_nop 0
	global_load_lds_dwordx4 v[142:143], off
	s_waitcnt vmcnt(8)
	s_waitcnt lgkmcnt(0)
	s_barrier
	s_waitcnt lgkmcnt(0)
	v_mfma_f32_16x16x32_f16 v[60:63], v[156:159], v[188:191], v[60:63]
	v_mfma_f32_16x16x32_f16 v[56:59], v[164:167], v[188:191], v[56:59]
	v_mfma_f32_16x16x32_f16 v[44:47], v[156:159], v[196:199], v[44:47]
	v_mfma_f32_16x16x32_f16 v[40:43], v[164:167], v[196:199], v[40:43]
	v_mfma_f32_16x16x32_f16 v[28:31], v[156:159], v[204:207], v[28:31]
	v_mfma_f32_16x16x32_f16 v[24:27], v[164:167], v[204:207], v[24:27]
	v_mfma_f32_16x16x32_f16 v[12:15], v[156:159], v[212:215], v[12:15]
	v_mfma_f32_16x16x32_f16 v[8:11], v[164:167], v[212:215], v[8:11]
	v_mfma_f32_16x16x32_f16 v[60:63], v[160:163], v[192:195], v[60:63]
	v_mfma_f32_16x16x32_f16 v[56:59], v[168:171], v[192:195], v[56:59]
	v_mfma_f32_16x16x32_f16 v[44:47], v[160:163], v[200:203], v[44:47]
	v_mfma_f32_16x16x32_f16 v[40:43], v[168:171], v[200:203], v[40:43]
	v_mfma_f32_16x16x32_f16 v[28:31], v[160:163], v[208:211], v[28:31]
	v_mfma_f32_16x16x32_f16 v[24:27], v[168:171], v[208:211], v[24:27]
	v_mfma_f32_16x16x32_f16 v[12:15], v[160:163], v[216:219], v[12:15]
	v_mfma_f32_16x16x32_f16 v[8:11], v[168:171], v[216:219], v[8:11]
	v_mfma_f32_16x16x32_f16 v[52:55], v[172:175], v[188:191], v[52:55]
	v_mfma_f32_16x16x32_f16 v[48:51], v[180:183], v[188:191], v[48:51]
	v_mfma_f32_16x16x32_f16 v[36:39], v[172:175], v[196:199], v[36:39]
	v_mfma_f32_16x16x32_f16 v[32:35], v[180:183], v[196:199], v[32:35]
	v_mfma_f32_16x16x32_f16 v[20:23], v[172:175], v[204:207], v[20:23]
	v_mfma_f32_16x16x32_f16 v[16:19], v[180:183], v[204:207], v[16:19]
	v_mfma_f32_16x16x32_f16 v[4:7], v[172:175], v[212:215], v[4:7]
	v_mfma_f32_16x16x32_f16 v[0:3], v[180:183], v[212:215], v[0:3]
	v_mfma_f32_16x16x32_f16 v[52:55], v[176:179], v[192:195], v[52:55]
	v_mfma_f32_16x16x32_f16 v[48:51], v[184:187], v[192:195], v[48:51]
	v_mfma_f32_16x16x32_f16 v[36:39], v[176:179], v[200:203], v[36:39]
	v_mfma_f32_16x16x32_f16 v[32:35], v[184:187], v[200:203], v[32:35]
	v_mfma_f32_16x16x32_f16 v[20:23], v[176:179], v[208:211], v[20:23]
	v_mfma_f32_16x16x32_f16 v[16:19], v[184:187], v[208:211], v[16:19]
	v_mfma_f32_16x16x32_f16 v[4:7], v[176:179], v[216:219], v[4:7]
	v_mfma_f32_16x16x32_f16 v[0:3], v[184:187], v[216:219], v[0:3]
	s_barrier
	s_add_i32 s85, s85, 2
	s_add_u32 s34, s34, 0x100
	s_addc_u32 s35, s35, 0
	s_add_u32 s83, s83, 0x100
	s_addc_u32 s84, s84, 0
	s_cmp_gt_u32 s85, 13
	s_cbranch_scc0 .LBB0_1044
	s_and_b64 vcc, exec, s[26:27]
	s_cbranch_vccz .LBB0_1047
	s_barrier

.LBB0_1232:
	s_add_u32 s16, s38, s14
	s_addc_u32 s17, s39, s15
	s_add_u32 s16, s16, 0x13d00100
	s_addc_u32 s17, s17, 0
	s_add_u32 s43, s40, s14
	s_addc_u32 s44, s41, s15
	s_cmpk_eq_i32 s14, 0x700
	s_cselect_b32 s19, s11, s17
	s_cselect_b32 s18, s10, s16
	s_cselect_b32 s17, s13, s44
	s_cselect_b32 s16, s12, s43
	s_add_i32 s43, 0, 0x14000
	v_add_u32_e32 v158, s67, v144
	v_add_u32_e32 v174, s43, v144
	ds_read_b128 v[146:149], v158
	ds_read_b128 v[150:153], v158 offset:1024
	ds_read_b128 v[154:157], v158 offset:2048
	ds_read_b128 v[158:161], v158 offset:3072
	ds_read_b128 v[162:165], v174
	ds_read_b128 v[166:169], v174 offset:1024
	ds_read_b128 v[170:173], v174 offset:2048
	ds_read_b128 v[174:177], v174 offset:3072
	v_lshl_add_u64 v[210:211], v[136:137], 0, s[14:15]
	s_add_i32 m0, s30, 0xc000
	ds_read_b128 v[178:181], v145
	ds_read_b128 v[182:185], v145 offset:1024
	ds_read_b128 v[186:189], v145 offset:2048
	ds_read_b128 v[190:193], v145 offset:3072
	ds_read_b128 v[194:197], v145 offset:4096
	ds_read_b128 v[198:201], v145 offset:5120
	ds_read_b128 v[202:205], v145 offset:6144
	ds_read_b128 v[206:209], v145 offset:7168
	global_load_lds_dwordx4 v[210:211], off
	v_lshl_add_u64 v[210:211], v[138:139], 0, s[14:15]
	s_add_i32 m0, s30, 0xe000
	s_nop 0
	global_load_lds_dwordx4 v[210:211], off
	s_waitcnt vmcnt(8)
	s_waitcnt lgkmcnt(0)
	s_barrier
	s_waitcnt lgkmcnt(0)
	v_mfma_f32_16x16x32_f16 v[124:127], v[146:149], v[178:181], v[124:127]
	v_mfma_f32_16x16x32_f16 v[120:123], v[154:157], v[178:181], v[120:123]
	v_mfma_f32_16x16x32_f16 v[108:111], v[146:149], v[186:189], v[108:111]
	v_mfma_f32_16x16x32_f16 v[104:107], v[154:157], v[186:189], v[104:107]
	v_mfma_f32_16x16x32_f16 v[92:95], v[146:149], v[194:197], v[92:95]
	v_mfma_f32_16x16x32_f16 v[88:91], v[154:157], v[194:197], v[88:91]
	v_mfma_f32_16x16x32_f16 v[76:79], v[146:149], v[202:205], v[76:79]
	v_mfma_f32_16x16x32_f16 v[72:75], v[154:157], v[202:205], v[72:75]
	v_mfma_f32_16x16x32_f16 v[124:127], v[150:153], v[182:185], v[124:127]
	v_mfma_f32_16x16x32_f16 v[120:123], v[158:161], v[182:185], v[120:123]
	v_mfma_f32_16x16x32_f16 v[108:111], v[150:153], v[190:193], v[108:111]
	v_mfma_f32_16x16x32_f16 v[104:107], v[158:161], v[190:193], v[104:107]
	v_mfma_f32_16x16x32_f16 v[92:95], v[150:153], v[198:201], v[92:95]
	v_mfma_f32_16x16x32_f16 v[88:91], v[158:161], v[198:201], v[88:91]
	v_mfma_f32_16x16x32_f16 v[76:79], v[150:153], v[206:209], v[76:79]
	v_mfma_f32_16x16x32_f16 v[72:75], v[158:161], v[206:209], v[72:75]
	v_mfma_f32_16x16x32_f16 v[116:119], v[162:165], v[178:181], v[116:119]
	v_mfma_f32_16x16x32_f16 v[112:115], v[170:173], v[178:181], v[112:115]
	v_mfma_f32_16x16x32_f16 v[100:103], v[162:165], v[186:189], v[100:103]
	v_mfma_f32_16x16x32_f16 v[96:99], v[170:173], v[186:189], v[96:99]
	v_mfma_f32_16x16x32_f16 v[84:87], v[162:165], v[194:197], v[84:87]
	v_mfma_f32_16x16x32_f16 v[80:83], v[170:173], v[194:197], v[80:83]
	v_mfma_f32_16x16x32_f16 v[68:71], v[162:165], v[202:205], v[68:71]
	v_mfma_f32_16x16x32_f16 v[64:67], v[170:173], v[202:205], v[64:67]
	v_mfma_f32_16x16x32_f16 v[116:119], v[166:169], v[182:185], v[116:119]
	v_mfma_f32_16x16x32_f16 v[112:115], v[174:177], v[182:185], v[112:115]
	v_mfma_f32_16x16x32_f16 v[100:103], v[166:169], v[190:193], v[100:103]
	v_mfma_f32_16x16x32_f16 v[96:99], v[174:177], v[190:193], v[96:99]
	v_mfma_f32_16x16x32_f16 v[84:87], v[166:169], v[198:201], v[84:87]
	v_mfma_f32_16x16x32_f16 v[80:83], v[174:177], v[198:201], v[80:83]
	v_mfma_f32_16x16x32_f16 v[68:71], v[166:169], v[206:209], v[68:71]
	v_mfma_f32_16x16x32_f16 v[64:67], v[174:177], v[206:209], v[64:67]
	s_barrier
	s_add_i32 s44, s67, s66
	v_lshl_add_u64 v[210:211], s[16:17], 0, v[128:129]
	s_mov_b32 m0, s44
	ds_read_b128 v[178:181], v145 offset:16384
	ds_read_b128 v[182:185], v145 offset:17408
	ds_read_b128 v[186:189], v145 offset:18432
	ds_read_b128 v[190:193], v145 offset:19456
	ds_read_b128 v[194:197], v145 offset:20480
	ds_read_b128 v[198:201], v145 offset:21504
	ds_read_b128 v[202:205], v145 offset:22528
	ds_read_b128 v[206:209], v145 offset:23552
	global_load_lds_dwordx4 v[210:211], off
	s_add_i32 m0, s44, 0x2000
	s_add_u32 s44, s16, 0x40000
	v_lshl_add_u64 v[212:213], s[16:17], 0, v[134:135]
	s_addc_u32 s45, s17, 0
	s_add_i32 s43, s43, s66
	global_load_lds_dwordx4 v[212:213], off
	v_lshl_add_u64 v[214:215], s[44:45], 0, v[128:129]
	s_mov_b32 m0, s43
	v_lshl_add_u64 v[216:217], s[18:19], 0, v[132:133]
	global_load_lds_dwordx4 v[214:215], off
	v_lshl_add_u64 v[214:215], s[44:45], 0, v[134:135]
	s_add_i32 m0, s43, 0x2000
	s_nop 0
	global_load_lds_dwordx4 v[214:215], off
	v_lshl_add_u64 v[214:215], s[18:19], 0, v[130:131]
	s_mov_b32 m0, s30
	s_nop 0
	global_load_lds_dwordx4 v[214:215], off
	s_mov_b32 m0, s31
	s_nop 0
	global_load_lds_dwordx4 v[216:217], off
	s_waitcnt vmcnt(8)
	s_waitcnt lgkmcnt(0)
	s_barrier
	s_waitcnt lgkmcnt(0)
	v_mfma_f32_16x16x32_f16 v[60:63], v[146:149], v[178:181], v[60:63]
	v_mfma_f32_16x16x32_f16 v[56:59], v[154:157], v[178:181], v[56:59]
	v_mfma_f32_16x16x32_f16 v[44:47], v[146:149], v[186:189], v[44:47]
	v_mfma_f32_16x16x32_f16 v[40:43], v[154:157], v[186:189], v[40:43]
	v_mfma_f32_16x16x32_f16 v[28:31], v[146:149], v[194:197], v[28:31]
	v_mfma_f32_16x16x32_f16 v[24:27], v[154:157], v[194:197], v[24:27]
	v_mfma_f32_16x16x32_f16 v[12:15], v[146:149], v[202:205], v[12:15]
	v_mfma_f32_16x16x32_f16 v[8:11], v[154:157], v[202:205], v[8:11]
	v_mfma_f32_16x16x32_f16 v[60:63], v[150:153], v[182:185], v[60:63]
	v_mfma_f32_16x16x32_f16 v[56:59], v[158:161], v[182:185], v[56:59]
	v_mfma_f32_16x16x32_f16 v[44:47], v[150:153], v[190:193], v[44:47]
	v_mfma_f32_16x16x32_f16 v[40:43], v[158:161], v[190:193], v[40:43]
	v_mfma_f32_16x16x32_f16 v[28:31], v[150:153], v[198:201], v[28:31]
	v_mfma_f32_16x16x32_f16 v[24:27], v[158:161], v[198:201], v[24:27]
	v_mfma_f32_16x16x32_f16 v[12:15], v[150:153], v[206:209], v[12:15]
	v_mfma_f32_16x16x32_f16 v[8:11], v[158:161], v[206:209], v[8:11]
	v_mfma_f32_16x16x32_f16 v[52:55], v[162:165], v[178:181], v[52:55]
	v_mfma_f32_16x16x32_f16 v[48:51], v[170:173], v[178:181], v[48:51]
	v_mfma_f32_16x16x32_f16 v[36:39], v[162:165], v[186:189], v[36:39]
	v_mfma_f32_16x16x32_f16 v[32:35], v[170:173], v[186:189], v[32:35]
	v_mfma_f32_16x16x32_f16 v[20:23], v[162:165], v[194:197], v[20:23]
	v_mfma_f32_16x16x32_f16 v[16:19], v[170:173], v[194:197], v[16:19]
	v_mfma_f32_16x16x32_f16 v[4:7], v[162:165], v[202:205], v[4:7]
	v_mfma_f32_16x16x32_f16 v[0:3], v[170:173], v[202:205], v[0:3]
	v_mfma_f32_16x16x32_f16 v[52:55], v[166:169], v[182:185], v[52:55]
	v_mfma_f32_16x16x32_f16 v[48:51], v[174:177], v[182:185], v[48:51]
	v_mfma_f32_16x16x32_f16 v[36:39], v[166:169], v[190:193], v[36:39]
	v_mfma_f32_16x16x32_f16 v[32:35], v[174:177], v[190:193], v[32:35]
	v_mfma_f32_16x16x32_f16 v[20:23], v[166:169], v[198:201], v[20:23]
	v_mfma_f32_16x16x32_f16 v[16:19], v[174:177], v[198:201], v[16:19]
	v_mfma_f32_16x16x32_f16 v[4:7], v[166:169], v[206:209], v[4:7]
	v_mfma_f32_16x16x32_f16 v[0:3], v[174:177], v[206:209], v[0:3]
	s_barrier
	s_add_i32 s43, 0, 0x18000
	s_add_i32 s44, 0, 0x1c000
	v_add_u32_e32 v158, s43, v144
	v_add_u32_e32 v174, s44, v144
	ds_read_b128 v[146:149], v158
	ds_read_b128 v[150:153], v158 offset:1024
	ds_read_b128 v[154:157], v158 offset:2048
	ds_read_b128 v[158:161], v158 offset:3072
	ds_read_b128 v[162:165], v174
	ds_read_b128 v[166:169], v174 offset:1024
	ds_read_b128 v[170:173], v174 offset:2048
	ds_read_b128 v[174:177], v174 offset:3072
	s_add_u32 s18, s18, 0x40000
	s_addc_u32 s19, s19, 0
	s_mov_b32 m0, s34
	v_lshl_add_u64 v[218:219], s[18:19], 0, v[130:131]
	ds_read_b128 v[178:181], v145 offset:32768
	ds_read_b128 v[182:185], v145 offset:33792
	ds_read_b128 v[186:189], v145 offset:34816
	ds_read_b128 v[190:193], v145 offset:35840
	ds_read_b128 v[194:197], v145 offset:36864
	ds_read_b128 v[198:201], v145 offset:37888
	ds_read_b128 v[202:205], v145 offset:38912
	ds_read_b128 v[206:209], v145 offset:39936
	global_load_lds_dwordx4 v[218:219], off
	v_lshl_add_u64 v[218:219], s[18:19], 0, v[132:133]
	s_mov_b32 m0, s35
	s_nop 0
	global_load_lds_dwordx4 v[218:219], off
	s_waitcnt vmcnt(8)
	s_waitcnt lgkmcnt(0)
	s_barrier
	s_waitcnt lgkmcnt(0)
	v_mfma_f32_16x16x32_f16 v[124:127], v[146:149], v[178:181], v[124:127]
	v_mfma_f32_16x16x32_f16 v[120:123], v[154:157], v[178:181], v[120:123]
	v_mfma_f32_16x16x32_f16 v[108:111], v[146:149], v[186:189], v[108:111]
	v_mfma_f32_16x16x32_f16 v[104:107], v[154:157], v[186:189], v[104:107]
	v_mfma_f32_16x16x32_f16 v[92:95], v[146:149], v[194:197], v[92:95]
	v_mfma_f32_16x16x32_f16 v[88:91], v[154:157], v[194:197], v[88:91]
	v_mfma_f32_16x16x32_f16 v[76:79], v[146:149], v[202:205], v[76:79]
	v_mfma_f32_16x16x32_f16 v[72:75], v[154:157], v[202:205], v[72:75]
	v_mfma_f32_16x16x32_f16 v[124:127], v[150:153], v[182:185], v[124:127]
	v_mfma_f32_16x16x32_f16 v[120:123], v[158:161], v[182:185], v[120:123]
	v_mfma_f32_16x16x32_f16 v[108:111], v[150:153], v[190:193], v[108:111]
	v_mfma_f32_16x16x32_f16 v[104:107], v[158:161], v[190:193], v[104:107]
	v_mfma_f32_16x16x32_f16 v[92:95], v[150:153], v[198:201], v[92:95]
	v_mfma_f32_16x16x32_f16 v[88:91], v[158:161], v[198:201], v[88:91]
	v_mfma_f32_16x16x32_f16 v[76:79], v[150:153], v[206:209], v[76:79]
	v_mfma_f32_16x16x32_f16 v[72:75], v[158:161], v[206:209], v[72:75]
	v_mfma_f32_16x16x32_f16 v[116:119], v[162:165], v[178:181], v[116:119]
	v_mfma_f32_16x16x32_f16 v[112:115], v[170:173], v[178:181], v[112:115]
	v_mfma_f32_16x16x32_f16 v[100:103], v[162:165], v[186:189], v[100:103]
	v_mfma_f32_16x16x32_f16 v[96:99], v[170:173], v[186:189], v[96:99]
	v_mfma_f32_16x16x32_f16 v[84:87], v[162:165], v[194:197], v[84:87]
	v_mfma_f32_16x16x32_f16 v[80:83], v[170:173], v[194:197], v[80:83]
	v_mfma_f32_16x16x32_f16 v[68:71], v[162:165], v[202:205], v[68:71]
	v_mfma_f32_16x16x32_f16 v[64:67], v[170:173], v[202:205], v[64:67]
	v_mfma_f32_16x16x32_f16 v[116:119], v[166:169], v[182:185], v[116:119]
	v_mfma_f32_16x16x32_f16 v[112:115], v[174:177], v[182:185], v[112:115]
	v_mfma_f32_16x16x32_f16 v[100:103], v[166:169], v[190:193], v[100:103]
	v_mfma_f32_16x16x32_f16 v[96:99], v[174:177], v[190:193], v[96:99]
	v_mfma_f32_16x16x32_f16 v[84:87], v[166:169], v[198:201], v[84:87]
	v_mfma_f32_16x16x32_f16 v[80:83], v[174:177], v[198:201], v[80:83]
	v_mfma_f32_16x16x32_f16 v[68:71], v[166:169], v[206:209], v[68:71]
	v_mfma_f32_16x16x32_f16 v[64:67], v[174:177], v[206:209], v[64:67]
	s_barrier
	s_add_i32 s18, s43, s66
	v_lshl_add_u64 v[210:211], v[210:211], 0, s[6:7]
	s_mov_b32 m0, s18
	ds_read_b128 v[178:181], v145 offset:49152
	ds_read_b128 v[182:185], v145 offset:50176
	ds_read_b128 v[186:189], v145 offset:51200
	ds_read_b128 v[190:193], v145 offset:52224
	ds_read_b128 v[194:197], v145 offset:53248
	ds_read_b128 v[198:201], v145 offset:54272
	ds_read_b128 v[202:205], v145 offset:55296
	ds_read_b128 v[206:209], v145 offset:56320
	global_load_lds_dwordx4 v[210:211], off
	s_add_i32 m0, s18, 0x2000
	s_add_u32 s16, s16, 0x40080
	v_lshl_add_u64 v[210:211], v[212:213], 0, s[6:7]
	s_addc_u32 s17, s17, 0
	s_add_i32 s18, s44, s66
	global_load_lds_dwordx4 v[210:211], off
	v_lshl_add_u64 v[210:211], s[16:17], 0, v[128:129]
	s_mov_b32 m0, s18
	s_nop 0
	global_load_lds_dwordx4 v[210:211], off
	v_lshl_add_u64 v[210:211], s[16:17], 0, v[134:135]
	s_add_i32 m0, s18, 0x2000
	s_nop 0
	global_load_lds_dwordx4 v[210:211], off
	v_lshl_add_u64 v[210:211], v[214:215], 0, s[6:7]
	s_mov_b32 m0, s36
	s_nop 0
	global_load_lds_dwordx4 v[210:211], off
	v_lshl_add_u64 v[210:211], v[216:217], 0, s[6:7]
	s_mov_b32 m0, s37
	s_nop 0
	global_load_lds_dwordx4 v[210:211], off
	s_waitcnt vmcnt(8)
	s_waitcnt lgkmcnt(0)
	s_barrier
	s_waitcnt lgkmcnt(0)
	v_mfma_f32_16x16x32_f16 v[60:63], v[146:149], v[178:181], v[60:63]
	v_mfma_f32_16x16x32_f16 v[56:59], v[154:157], v[178:181], v[56:59]
	v_mfma_f32_16x16x32_f16 v[44:47], v[146:149], v[186:189], v[44:47]
	v_mfma_f32_16x16x32_f16 v[40:43], v[154:157], v[186:189], v[40:43]
	v_mfma_f32_16x16x32_f16 v[28:31], v[146:149], v[194:197], v[28:31]
	v_mfma_f32_16x16x32_f16 v[24:27], v[154:157], v[194:197], v[24:27]
	v_mfma_f32_16x16x32_f16 v[12:15], v[146:149], v[202:205], v[12:15]
	v_mfma_f32_16x16x32_f16 v[8:11], v[154:157], v[202:205], v[8:11]
	v_mfma_f32_16x16x32_f16 v[60:63], v[150:153], v[182:185], v[60:63]
	v_mfma_f32_16x16x32_f16 v[56:59], v[158:161], v[182:185], v[56:59]
	v_mfma_f32_16x16x32_f16 v[44:47], v[150:153], v[190:193], v[44:47]
	v_mfma_f32_16x16x32_f16 v[40:43], v[158:161], v[190:193], v[40:43]
	v_mfma_f32_16x16x32_f16 v[28:31], v[150:153], v[198:201], v[28:31]
	v_mfma_f32_16x16x32_f16 v[24:27], v[158:161], v[198:201], v[24:27]
	v_mfma_f32_16x16x32_f16 v[12:15], v[150:153], v[206:209], v[12:15]
	v_mfma_f32_16x16x32_f16 v[8:11], v[158:161], v[206:209], v[8:11]
	v_mfma_f32_16x16x32_f16 v[52:55], v[162:165], v[178:181], v[52:55]
	v_mfma_f32_16x16x32_f16 v[48:51], v[170:173], v[178:181], v[48:51]
	v_mfma_f32_16x16x32_f16 v[36:39], v[162:165], v[186:189], v[36:39]
	v_mfma_f32_16x16x32_f16 v[32:35], v[170:173], v[186:189], v[32:35]
	v_mfma_f32_16x16x32_f16 v[20:23], v[162:165], v[194:197], v[20:23]
	v_mfma_f32_16x16x32_f16 v[16:19], v[170:173], v[194:197], v[16:19]
	v_mfma_f32_16x16x32_f16 v[4:7], v[162:165], v[202:205], v[4:7]
	v_mfma_f32_16x16x32_f16 v[0:3], v[170:173], v[202:205], v[0:3]
	v_mfma_f32_16x16x32_f16 v[52:55], v[166:169], v[182:185], v[52:55]
	v_mfma_f32_16x16x32_f16 v[48:51], v[174:177], v[182:185], v[48:51]
	v_mfma_f32_16x16x32_f16 v[36:39], v[166:169], v[190:193], v[36:39]
	v_mfma_f32_16x16x32_f16 v[32:35], v[174:177], v[190:193], v[32:35]
	v_mfma_f32_16x16x32_f16 v[20:23], v[166:169], v[198:201], v[20:23]
	v_mfma_f32_16x16x32_f16 v[16:19], v[174:177], v[198:201], v[16:19]
	v_mfma_f32_16x16x32_f16 v[4:7], v[166:169], v[206:209], v[4:7]
	v_mfma_f32_16x16x32_f16 v[0:3], v[174:177], v[206:209], v[0:3]
	s_barrier
	s_add_i32 s42, s42, 2
	s_add_u32 s14, s14, 0x100
	s_addc_u32 s15, s15, 0
	s_cmp_gt_u32 s42, 13
	s_cbranch_scc0 .LBB0_1232
	s_and_b64 vcc, exec, s[26:27]
	s_cbranch_vccz .LBB0_1235
	s_barrier

.LBB0_1329:
	s_add_u32 s28, s41, s26
	s_addc_u32 s29, s42, s27
	s_add_u32 s28, s28, 0x7a00100
	s_addc_u32 s29, s29, 0
	s_add_u32 s46, s43, s26
	s_addc_u32 s47, s44, s27
	s_add_i32 s48, 0, 0x10000
	s_cmpk_eq_i32 s26, 0x700
	s_cselect_b32 s31, s25, s29
	s_cselect_b32 s30, s24, s28
	v_add_u32_e32 v149, s48, v147
	s_cselect_b32 s29, s1, s47
	s_cselect_b32 s28, s0, s46
	s_add_i32 s49, 0, 0x14000
	ds_read_b128 v[150:153], v149
	ds_read_b128 v[154:157], v149 offset:1024
	ds_read_b128 v[158:161], v149 offset:2048
	ds_read_b128 v[162:165], v149 offset:3072
	v_add_u32_e32 v149, s49, v147
	ds_read_b128 v[166:169], v149
	ds_read_b128 v[170:173], v149 offset:1024
	ds_read_b128 v[174:177], v149 offset:2048
	ds_read_b128 v[178:181], v149 offset:3072
	v_lshl_add_u64 v[214:215], v[136:137], 0, s[26:27]
	s_add_i32 m0, s35, 0xc000
	ds_read_b128 v[182:185], v148
	ds_read_b128 v[186:189], v148 offset:1024
	ds_read_b128 v[190:193], v148 offset:2048
	ds_read_b128 v[194:197], v148 offset:3072
	ds_read_b128 v[198:201], v148 offset:4096
	ds_read_b128 v[202:205], v148 offset:5120
	ds_read_b128 v[206:209], v148 offset:6144
	ds_read_b128 v[210:213], v148 offset:7168
	global_load_lds_dwordx4 v[214:215], off
	v_lshl_add_u64 v[214:215], v[138:139], 0, s[26:27]
	s_add_i32 m0, s35, 0xe000
	s_nop 0
	global_load_lds_dwordx4 v[214:215], off
	s_waitcnt vmcnt(8)
	s_waitcnt lgkmcnt(0)
	s_barrier
	s_waitcnt lgkmcnt(0)
	v_mfma_f32_16x16x32_f16 v[124:127], v[150:153], v[182:185], v[124:127]
	v_mfma_f32_16x16x32_f16 v[120:123], v[158:161], v[182:185], v[120:123]
	v_mfma_f32_16x16x32_f16 v[108:111], v[150:153], v[190:193], v[108:111]
	v_mfma_f32_16x16x32_f16 v[104:107], v[158:161], v[190:193], v[104:107]
	v_mfma_f32_16x16x32_f16 v[92:95], v[150:153], v[198:201], v[92:95]
	v_mfma_f32_16x16x32_f16 v[88:91], v[158:161], v[198:201], v[88:91]
	v_mfma_f32_16x16x32_f16 v[76:79], v[150:153], v[206:209], v[76:79]
	v_mfma_f32_16x16x32_f16 v[72:75], v[158:161], v[206:209], v[72:75]
	v_mfma_f32_16x16x32_f16 v[124:127], v[154:157], v[186:189], v[124:127]
	v_mfma_f32_16x16x32_f16 v[120:123], v[162:165], v[186:189], v[120:123]
	v_mfma_f32_16x16x32_f16 v[108:111], v[154:157], v[194:197], v[108:111]
	v_mfma_f32_16x16x32_f16 v[104:107], v[162:165], v[194:197], v[104:107]
	v_mfma_f32_16x16x32_f16 v[92:95], v[154:157], v[202:205], v[92:95]
	v_mfma_f32_16x16x32_f16 v[88:91], v[162:165], v[202:205], v[88:91]
	v_mfma_f32_16x16x32_f16 v[76:79], v[154:157], v[210:213], v[76:79]
	v_mfma_f32_16x16x32_f16 v[72:75], v[162:165], v[210:213], v[72:75]
	v_mfma_f32_16x16x32_f16 v[116:119], v[166:169], v[182:185], v[116:119]
	v_mfma_f32_16x16x32_f16 v[112:115], v[174:177], v[182:185], v[112:115]
	v_mfma_f32_16x16x32_f16 v[100:103], v[166:169], v[190:193], v[100:103]
	v_mfma_f32_16x16x32_f16 v[96:99], v[174:177], v[190:193], v[96:99]
	v_mfma_f32_16x16x32_f16 v[84:87], v[166:169], v[198:201], v[84:87]
	v_mfma_f32_16x16x32_f16 v[80:83], v[174:177], v[198:201], v[80:83]
	v_mfma_f32_16x16x32_f16 v[68:71], v[166:169], v[206:209], v[68:71]
	v_mfma_f32_16x16x32_f16 v[64:67], v[174:177], v[206:209], v[64:67]
	v_mfma_f32_16x16x32_f16 v[116:119], v[170:173], v[186:189], v[116:119]
	v_mfma_f32_16x16x32_f16 v[112:115], v[178:181], v[186:189], v[112:115]
	v_mfma_f32_16x16x32_f16 v[100:103], v[170:173], v[194:197], v[100:103]
	v_mfma_f32_16x16x32_f16 v[96:99], v[178:181], v[194:197], v[96:99]
	v_mfma_f32_16x16x32_f16 v[84:87], v[170:173], v[202:205], v[84:87]
	v_mfma_f32_16x16x32_f16 v[80:83], v[178:181], v[202:205], v[80:83]
	v_mfma_f32_16x16x32_f16 v[68:71], v[170:173], v[210:213], v[68:71]
	v_mfma_f32_16x16x32_f16 v[64:67], v[178:181], v[210:213], v[64:67]
	s_barrier
	s_add_i32 s46, s48, s53
	v_lshl_add_u64 v[214:215], s[28:29], 0, v[128:129]
	s_mov_b32 m0, s46
	ds_read_b128 v[182:185], v148 offset:16384
	ds_read_b128 v[186:189], v148 offset:17408
	ds_read_b128 v[190:193], v148 offset:18432
	ds_read_b128 v[194:197], v148 offset:19456
	ds_read_b128 v[198:201], v148 offset:20480
	ds_read_b128 v[202:205], v148 offset:21504
	ds_read_b128 v[206:209], v148 offset:22528
	ds_read_b128 v[210:213], v148 offset:23552
	global_load_lds_dwordx4 v[214:215], off
	s_add_i32 m0, s46, 0x2000
	s_add_u32 s46, s28, 0x40000
	v_lshl_add_u64 v[216:217], s[28:29], 0, v[134:135]
	s_addc_u32 s47, s29, 0
	s_add_i32 s48, s49, s53
	global_load_lds_dwordx4 v[216:217], off
	v_lshl_add_u64 v[218:219], s[46:47], 0, v[128:129]
	s_mov_b32 m0, s48
	v_lshl_add_u64 v[220:221], s[30:31], 0, v[132:133]
	global_load_lds_dwordx4 v[218:219], off
	v_lshl_add_u64 v[218:219], s[46:47], 0, v[134:135]
	s_add_i32 m0, s48, 0x2000
	s_nop 0
	global_load_lds_dwordx4 v[218:219], off
	v_lshl_add_u64 v[218:219], s[30:31], 0, v[130:131]
	s_mov_b32 m0, s35
	s_nop 0
	global_load_lds_dwordx4 v[218:219], off
	s_mov_b32 m0, s36
	s_nop 0
	global_load_lds_dwordx4 v[220:221], off
	s_waitcnt vmcnt(8)
	s_waitcnt lgkmcnt(0)
	s_barrier
	s_waitcnt lgkmcnt(0)
	v_mfma_f32_16x16x32_f16 v[60:63], v[150:153], v[182:185], v[60:63]
	v_mfma_f32_16x16x32_f16 v[56:59], v[158:161], v[182:185], v[56:59]
	v_mfma_f32_16x16x32_f16 v[44:47], v[150:153], v[190:193], v[44:47]
	v_mfma_f32_16x16x32_f16 v[40:43], v[158:161], v[190:193], v[40:43]
	v_mfma_f32_16x16x32_f16 v[28:31], v[150:153], v[198:201], v[28:31]
	v_mfma_f32_16x16x32_f16 v[24:27], v[158:161], v[198:201], v[24:27]
	v_mfma_f32_16x16x32_f16 v[12:15], v[150:153], v[206:209], v[12:15]
	v_mfma_f32_16x16x32_f16 v[8:11], v[158:161], v[206:209], v[8:11]
	v_mfma_f32_16x16x32_f16 v[60:63], v[154:157], v[186:189], v[60:63]
	v_mfma_f32_16x16x32_f16 v[56:59], v[162:165], v[186:189], v[56:59]
	v_mfma_f32_16x16x32_f16 v[44:47], v[154:157], v[194:197], v[44:47]
	v_mfma_f32_16x16x32_f16 v[40:43], v[162:165], v[194:197], v[40:43]
	v_mfma_f32_16x16x32_f16 v[28:31], v[154:157], v[202:205], v[28:31]
	v_mfma_f32_16x16x32_f16 v[24:27], v[162:165], v[202:205], v[24:27]
	v_mfma_f32_16x16x32_f16 v[12:15], v[154:157], v[210:213], v[12:15]
	v_mfma_f32_16x16x32_f16 v[8:11], v[162:165], v[210:213], v[8:11]
	v_mfma_f32_16x16x32_f16 v[52:55], v[166:169], v[182:185], v[52:55]
	v_mfma_f32_16x16x32_f16 v[48:51], v[174:177], v[182:185], v[48:51]
	v_mfma_f32_16x16x32_f16 v[36:39], v[166:169], v[190:193], v[36:39]
	v_mfma_f32_16x16x32_f16 v[32:35], v[174:177], v[190:193], v[32:35]
	v_mfma_f32_16x16x32_f16 v[20:23], v[166:169], v[198:201], v[20:23]
	v_mfma_f32_16x16x32_f16 v[16:19], v[174:177], v[198:201], v[16:19]
	v_mfma_f32_16x16x32_f16 v[4:7], v[166:169], v[206:209], v[4:7]
	v_mfma_f32_16x16x32_f16 v[0:3], v[174:177], v[206:209], v[0:3]
	v_mfma_f32_16x16x32_f16 v[52:55], v[170:173], v[186:189], v[52:55]
	v_mfma_f32_16x16x32_f16 v[48:51], v[178:181], v[186:189], v[48:51]
	v_mfma_f32_16x16x32_f16 v[36:39], v[170:173], v[194:197], v[36:39]
	v_mfma_f32_16x16x32_f16 v[32:35], v[178:181], v[194:197], v[32:35]
	v_mfma_f32_16x16x32_f16 v[20:23], v[170:173], v[202:205], v[20:23]
	v_mfma_f32_16x16x32_f16 v[16:19], v[178:181], v[202:205], v[16:19]
	v_mfma_f32_16x16x32_f16 v[4:7], v[170:173], v[210:213], v[4:7]
	v_mfma_f32_16x16x32_f16 v[0:3], v[178:181], v[210:213], v[0:3]
	s_barrier
	s_add_i32 s46, 0, 0x18000
	v_add_u32_e32 v149, s46, v147
	s_add_i32 s47, 0, 0x1c000
	ds_read_b128 v[150:153], v149
	ds_read_b128 v[154:157], v149 offset:1024
	ds_read_b128 v[158:161], v149 offset:2048
	ds_read_b128 v[162:165], v149 offset:3072
	v_add_u32_e32 v149, s47, v147
	ds_read_b128 v[166:169], v149
	ds_read_b128 v[170:173], v149 offset:1024
	ds_read_b128 v[174:177], v149 offset:2048
	ds_read_b128 v[178:181], v149 offset:3072
	s_add_u32 s30, s30, 0x40000
	s_addc_u32 s31, s31, 0
	s_mov_b32 m0, s37
	v_lshl_add_u64 v[222:223], s[30:31], 0, v[130:131]
	ds_read_b128 v[182:185], v148 offset:32768
	ds_read_b128 v[186:189], v148 offset:33792
	ds_read_b128 v[190:193], v148 offset:34816
	ds_read_b128 v[194:197], v148 offset:35840
	ds_read_b128 v[198:201], v148 offset:36864
	ds_read_b128 v[202:205], v148 offset:37888
	ds_read_b128 v[206:209], v148 offset:38912
	ds_read_b128 v[210:213], v148 offset:39936
	global_load_lds_dwordx4 v[222:223], off
	v_lshl_add_u64 v[222:223], s[30:31], 0, v[132:133]
	s_mov_b32 m0, s38
	s_nop 0
	global_load_lds_dwordx4 v[222:223], off
	s_waitcnt vmcnt(8)
	s_waitcnt lgkmcnt(0)
	s_barrier
	s_waitcnt lgkmcnt(0)
	v_mfma_f32_16x16x32_f16 v[124:127], v[150:153], v[182:185], v[124:127]
	v_mfma_f32_16x16x32_f16 v[120:123], v[158:161], v[182:185], v[120:123]
	v_mfma_f32_16x16x32_f16 v[108:111], v[150:153], v[190:193], v[108:111]
	v_mfma_f32_16x16x32_f16 v[104:107], v[158:161], v[190:193], v[104:107]
	v_mfma_f32_16x16x32_f16 v[92:95], v[150:153], v[198:201], v[92:95]
	v_mfma_f32_16x16x32_f16 v[88:91], v[158:161], v[198:201], v[88:91]
	v_mfma_f32_16x16x32_f16 v[76:79], v[150:153], v[206:209], v[76:79]
	v_mfma_f32_16x16x32_f16 v[72:75], v[158:161], v[206:209], v[72:75]
	v_mfma_f32_16x16x32_f16 v[124:127], v[154:157], v[186:189], v[124:127]
	v_mfma_f32_16x16x32_f16 v[120:123], v[162:165], v[186:189], v[120:123]
	v_mfma_f32_16x16x32_f16 v[108:111], v[154:157], v[194:197], v[108:111]
	v_mfma_f32_16x16x32_f16 v[104:107], v[162:165], v[194:197], v[104:107]
	v_mfma_f32_16x16x32_f16 v[92:95], v[154:157], v[202:205], v[92:95]
	v_mfma_f32_16x16x32_f16 v[88:91], v[162:165], v[202:205], v[88:91]
	v_mfma_f32_16x16x32_f16 v[76:79], v[154:157], v[210:213], v[76:79]
	v_mfma_f32_16x16x32_f16 v[72:75], v[162:165], v[210:213], v[72:75]
	v_mfma_f32_16x16x32_f16 v[116:119], v[166:169], v[182:185], v[116:119]
	v_mfma_f32_16x16x32_f16 v[112:115], v[174:177], v[182:185], v[112:115]
	v_mfma_f32_16x16x32_f16 v[100:103], v[166:169], v[190:193], v[100:103]
	v_mfma_f32_16x16x32_f16 v[96:99], v[174:177], v[190:193], v[96:99]
	v_mfma_f32_16x16x32_f16 v[84:87], v[166:169], v[198:201], v[84:87]
	v_mfma_f32_16x16x32_f16 v[80:83], v[174:177], v[198:201], v[80:83]
	v_mfma_f32_16x16x32_f16 v[68:71], v[166:169], v[206:209], v[68:71]
	v_mfma_f32_16x16x32_f16 v[64:67], v[174:177], v[206:209], v[64:67]
	v_mfma_f32_16x16x32_f16 v[116:119], v[170:173], v[186:189], v[116:119]
	v_mfma_f32_16x16x32_f16 v[112:115], v[178:181], v[186:189], v[112:115]
	v_mfma_f32_16x16x32_f16 v[100:103], v[170:173], v[194:197], v[100:103]
	v_mfma_f32_16x16x32_f16 v[96:99], v[178:181], v[194:197], v[96:99]
	v_mfma_f32_16x16x32_f16 v[84:87], v[170:173], v[202:205], v[84:87]
	v_mfma_f32_16x16x32_f16 v[80:83], v[178:181], v[202:205], v[80:83]
	v_mfma_f32_16x16x32_f16 v[68:71], v[170:173], v[210:213], v[68:71]
	v_mfma_f32_16x16x32_f16 v[64:67], v[178:181], v[210:213], v[64:67]
	s_barrier
	s_add_i32 s30, s46, s53
	v_lshl_add_u64 v[214:215], v[214:215], 0, s[20:21]
	s_mov_b32 m0, s30
	ds_read_b128 v[182:185], v148 offset:49152
	ds_read_b128 v[186:189], v148 offset:50176
	ds_read_b128 v[190:193], v148 offset:51200
	ds_read_b128 v[194:197], v148 offset:52224
	ds_read_b128 v[198:201], v148 offset:53248
	ds_read_b128 v[202:205], v148 offset:54272
	ds_read_b128 v[206:209], v148 offset:55296
	ds_read_b128 v[210:213], v148 offset:56320
	global_load_lds_dwordx4 v[214:215], off
	s_add_i32 m0, s30, 0x2000
	s_add_u32 s28, s28, 0x40080
	v_lshl_add_u64 v[214:215], v[216:217], 0, s[20:21]
	s_addc_u32 s29, s29, 0
	s_add_i32 s30, s47, s53
	global_load_lds_dwordx4 v[214:215], off
	v_lshl_add_u64 v[214:215], s[28:29], 0, v[128:129]
	s_mov_b32 m0, s30
	s_nop 0
	global_load_lds_dwordx4 v[214:215], off
	v_lshl_add_u64 v[214:215], s[28:29], 0, v[134:135]
	s_add_i32 m0, s30, 0x2000
	s_nop 0
	global_load_lds_dwordx4 v[214:215], off
	v_lshl_add_u64 v[214:215], v[218:219], 0, s[20:21]
	s_mov_b32 m0, s39
	s_nop 0
	global_load_lds_dwordx4 v[214:215], off
	v_lshl_add_u64 v[214:215], v[220:221], 0, s[20:21]
	s_mov_b32 m0, s40
	s_nop 0
	global_load_lds_dwordx4 v[214:215], off
	s_waitcnt vmcnt(8)
	s_waitcnt lgkmcnt(0)
	s_barrier
	s_waitcnt lgkmcnt(0)
	v_mfma_f32_16x16x32_f16 v[60:63], v[150:153], v[182:185], v[60:63]
	v_mfma_f32_16x16x32_f16 v[56:59], v[158:161], v[182:185], v[56:59]
	v_mfma_f32_16x16x32_f16 v[44:47], v[150:153], v[190:193], v[44:47]
	v_mfma_f32_16x16x32_f16 v[40:43], v[158:161], v[190:193], v[40:43]
	v_mfma_f32_16x16x32_f16 v[28:31], v[150:153], v[198:201], v[28:31]
	v_mfma_f32_16x16x32_f16 v[24:27], v[158:161], v[198:201], v[24:27]
	v_mfma_f32_16x16x32_f16 v[12:15], v[150:153], v[206:209], v[12:15]
	v_mfma_f32_16x16x32_f16 v[8:11], v[158:161], v[206:209], v[8:11]
	v_mfma_f32_16x16x32_f16 v[60:63], v[154:157], v[186:189], v[60:63]
	v_mfma_f32_16x16x32_f16 v[56:59], v[162:165], v[186:189], v[56:59]
	v_mfma_f32_16x16x32_f16 v[44:47], v[154:157], v[194:197], v[44:47]
	v_mfma_f32_16x16x32_f16 v[40:43], v[162:165], v[194:197], v[40:43]
	v_mfma_f32_16x16x32_f16 v[28:31], v[154:157], v[202:205], v[28:31]
	v_mfma_f32_16x16x32_f16 v[24:27], v[162:165], v[202:205], v[24:27]
	v_mfma_f32_16x16x32_f16 v[12:15], v[154:157], v[210:213], v[12:15]
	v_mfma_f32_16x16x32_f16 v[8:11], v[162:165], v[210:213], v[8:11]
	v_mfma_f32_16x16x32_f16 v[52:55], v[166:169], v[182:185], v[52:55]
	v_mfma_f32_16x16x32_f16 v[48:51], v[174:177], v[182:185], v[48:51]
	v_mfma_f32_16x16x32_f16 v[36:39], v[166:169], v[190:193], v[36:39]
	v_mfma_f32_16x16x32_f16 v[32:35], v[174:177], v[190:193], v[32:35]
	v_mfma_f32_16x16x32_f16 v[20:23], v[166:169], v[198:201], v[20:23]
	v_mfma_f32_16x16x32_f16 v[16:19], v[174:177], v[198:201], v[16:19]
	v_mfma_f32_16x16x32_f16 v[4:7], v[166:169], v[206:209], v[4:7]
	v_mfma_f32_16x16x32_f16 v[0:3], v[174:177], v[206:209], v[0:3]
	v_mfma_f32_16x16x32_f16 v[52:55], v[170:173], v[186:189], v[52:55]
	v_mfma_f32_16x16x32_f16 v[48:51], v[178:181], v[186:189], v[48:51]
	v_mfma_f32_16x16x32_f16 v[36:39], v[170:173], v[194:197], v[36:39]
	v_mfma_f32_16x16x32_f16 v[32:35], v[178:181], v[194:197], v[32:35]
	v_mfma_f32_16x16x32_f16 v[20:23], v[170:173], v[202:205], v[20:23]
	v_mfma_f32_16x16x32_f16 v[16:19], v[178:181], v[202:205], v[16:19]
	v_mfma_f32_16x16x32_f16 v[4:7], v[170:173], v[210:213], v[4:7]
	v_mfma_f32_16x16x32_f16 v[0:3], v[178:181], v[210:213], v[0:3]
	s_barrier
	s_add_i32 s45, s45, 2
	s_add_u32 s26, s26, 0x100
	s_addc_u32 s27, s27, 0
	s_cmp_gt_u32 s45, 13
	s_cbranch_scc0 .LBB0_1329
	s_and_b64 vcc, exec, s[16:17]
	s_cbranch_vccz .LBB0_1332
	s_barrier

.LBB0_1429:
	ds_read_b128 v[158:161], v151
	ds_read_b128 v[162:165], v151 offset:1024
	ds_read_b128 v[166:169], v151 offset:2048
	ds_read_b128 v[170:173], v151 offset:3072
	ds_read_b128 v[174:177], v152
	ds_read_b128 v[178:181], v152 offset:1024
	ds_read_b128 v[182:185], v152 offset:2048
	ds_read_b128 v[186:189], v152 offset:3072
	s_add_u32 s30, s22, 0xfffc0080
	s_addc_u32 s31, s23, -1
	s_cmp_eq_u32 s51, 12
	s_cselect_b32 s35, s17, s31
	s_cselect_b32 s34, s16, s30
	s_cselect_b32 s31, s19, s15
	s_cselect_b32 s30, s18, s13
	v_lshl_add_u64 v[222:223], s[22:23], 0, v[138:139]
	s_add_i32 m0, s21, 0xc000
	ds_read_b128 v[190:193], v153
	ds_read_b128 v[194:197], v153 offset:1024
	ds_read_b128 v[198:201], v153 offset:2048
	ds_read_b128 v[202:205], v153 offset:3072
	ds_read_b128 v[206:209], v153 offset:4096
	ds_read_b128 v[210:213], v153 offset:5120
	ds_read_b128 v[214:217], v153 offset:6144
	ds_read_b128 v[218:221], v153 offset:7168
	global_load_lds_dwordx4 v[222:223], off
	v_lshl_add_u64 v[222:223], s[22:23], 0, v[140:141]
	s_add_i32 m0, s21, 0xe000
	s_nop 0
	global_load_lds_dwordx4 v[222:223], off
	s_waitcnt vmcnt(8)
	s_waitcnt lgkmcnt(0)
	s_barrier
	s_waitcnt lgkmcnt(0)
	v_mfma_f32_16x16x32_f16 v[124:127], v[158:161], v[190:193], v[124:127]
	v_mfma_f32_16x16x32_f16 v[120:123], v[166:169], v[190:193], v[120:123]
	v_mfma_f32_16x16x32_f16 v[108:111], v[158:161], v[198:201], v[108:111]
	v_mfma_f32_16x16x32_f16 v[104:107], v[166:169], v[198:201], v[104:107]
	v_mfma_f32_16x16x32_f16 v[92:95], v[158:161], v[206:209], v[92:95]
	v_mfma_f32_16x16x32_f16 v[88:91], v[166:169], v[206:209], v[88:91]
	v_mfma_f32_16x16x32_f16 v[76:79], v[158:161], v[214:217], v[76:79]
	v_mfma_f32_16x16x32_f16 v[72:75], v[166:169], v[214:217], v[72:75]
	v_mfma_f32_16x16x32_f16 v[124:127], v[162:165], v[194:197], v[124:127]
	v_mfma_f32_16x16x32_f16 v[120:123], v[170:173], v[194:197], v[120:123]
	v_mfma_f32_16x16x32_f16 v[108:111], v[162:165], v[202:205], v[108:111]
	v_mfma_f32_16x16x32_f16 v[104:107], v[170:173], v[202:205], v[104:107]
	v_mfma_f32_16x16x32_f16 v[92:95], v[162:165], v[210:213], v[92:95]
	v_mfma_f32_16x16x32_f16 v[88:91], v[170:173], v[210:213], v[88:91]
	v_mfma_f32_16x16x32_f16 v[76:79], v[162:165], v[218:221], v[76:79]
	v_mfma_f32_16x16x32_f16 v[72:75], v[170:173], v[218:221], v[72:75]
	v_mfma_f32_16x16x32_f16 v[116:119], v[174:177], v[190:193], v[116:119]
	v_mfma_f32_16x16x32_f16 v[112:115], v[182:185], v[190:193], v[112:115]
	v_mfma_f32_16x16x32_f16 v[100:103], v[174:177], v[198:201], v[100:103]
	v_mfma_f32_16x16x32_f16 v[96:99], v[182:185], v[198:201], v[96:99]
	v_mfma_f32_16x16x32_f16 v[84:87], v[174:177], v[206:209], v[84:87]
	v_mfma_f32_16x16x32_f16 v[80:83], v[182:185], v[206:209], v[80:83]
	v_mfma_f32_16x16x32_f16 v[68:71], v[174:177], v[214:217], v[68:71]
	v_mfma_f32_16x16x32_f16 v[64:67], v[182:185], v[214:217], v[64:67]
	v_mfma_f32_16x16x32_f16 v[116:119], v[178:181], v[194:197], v[116:119]
	v_mfma_f32_16x16x32_f16 v[112:115], v[186:189], v[194:197], v[112:115]
	v_mfma_f32_16x16x32_f16 v[100:103], v[178:181], v[202:205], v[100:103]
	v_mfma_f32_16x16x32_f16 v[96:99], v[186:189], v[202:205], v[96:99]
	v_mfma_f32_16x16x32_f16 v[84:87], v[178:181], v[210:213], v[84:87]
	v_mfma_f32_16x16x32_f16 v[80:83], v[186:189], v[210:213], v[80:83]
	v_mfma_f32_16x16x32_f16 v[68:71], v[178:181], v[218:221], v[68:71]
	v_mfma_f32_16x16x32_f16 v[64:67], v[186:189], v[218:221], v[64:67]
	s_barrier
	s_add_i32 s52, s46, s3
	v_lshl_add_u64 v[222:223], s[30:31], 0, v[132:133]
	s_mov_b32 m0, s52
	ds_read_b128 v[190:193], v153 offset:16384
	ds_read_b128 v[194:197], v153 offset:17408
	ds_read_b128 v[198:201], v153 offset:18432
	ds_read_b128 v[202:205], v153 offset:19456
	ds_read_b128 v[206:209], v153 offset:20480
	ds_read_b128 v[210:213], v153 offset:21504
	ds_read_b128 v[214:217], v153 offset:22528
	ds_read_b128 v[218:221], v153 offset:23552
	global_load_lds_dwordx4 v[222:223], off
	s_add_i32 m0, s52, 0x2000
	s_add_u32 s52, s30, 0x40000
	v_lshl_add_u64 v[224:225], s[30:31], 0, v[128:129]
	s_addc_u32 s53, s31, 0
	s_add_i32 s54, s47, s3
	global_load_lds_dwordx4 v[224:225], off
	v_lshl_add_u64 v[226:227], s[52:53], 0, v[132:133]
	s_mov_b32 m0, s54
	v_lshl_add_u64 v[228:229], s[34:35], 0, v[130:131]
	global_load_lds_dwordx4 v[226:227], off
	v_lshl_add_u64 v[226:227], s[52:53], 0, v[128:129]
	s_add_i32 m0, s54, 0x2000
	s_nop 0
	global_load_lds_dwordx4 v[226:227], off
	v_lshl_add_u64 v[226:227], s[34:35], 0, v[134:135]
	s_mov_b32 m0, s21
	s_nop 0
	global_load_lds_dwordx4 v[226:227], off
	s_mov_b32 m0, s40
	s_nop 0
	global_load_lds_dwordx4 v[228:229], off
	s_waitcnt vmcnt(8)
	s_waitcnt lgkmcnt(0)
	s_barrier
	s_waitcnt lgkmcnt(0)
	v_mfma_f32_16x16x32_f16 v[60:63], v[158:161], v[190:193], v[60:63]
	v_mfma_f32_16x16x32_f16 v[56:59], v[166:169], v[190:193], v[56:59]
	v_mfma_f32_16x16x32_f16 v[44:47], v[158:161], v[198:201], v[44:47]
	v_mfma_f32_16x16x32_f16 v[40:43], v[166:169], v[198:201], v[40:43]
	v_mfma_f32_16x16x32_f16 v[28:31], v[158:161], v[206:209], v[28:31]
	v_mfma_f32_16x16x32_f16 v[24:27], v[166:169], v[206:209], v[24:27]
	v_mfma_f32_16x16x32_f16 v[12:15], v[158:161], v[214:217], v[12:15]
	v_mfma_f32_16x16x32_f16 v[8:11], v[166:169], v[214:217], v[8:11]
	v_mfma_f32_16x16x32_f16 v[60:63], v[162:165], v[194:197], v[60:63]
	v_mfma_f32_16x16x32_f16 v[56:59], v[170:173], v[194:197], v[56:59]
	v_mfma_f32_16x16x32_f16 v[44:47], v[162:165], v[202:205], v[44:47]
	v_mfma_f32_16x16x32_f16 v[40:43], v[170:173], v[202:205], v[40:43]
	v_mfma_f32_16x16x32_f16 v[28:31], v[162:165], v[210:213], v[28:31]
	v_mfma_f32_16x16x32_f16 v[24:27], v[170:173], v[210:213], v[24:27]
	v_mfma_f32_16x16x32_f16 v[12:15], v[162:165], v[218:221], v[12:15]
	v_mfma_f32_16x16x32_f16 v[8:11], v[170:173], v[218:221], v[8:11]
	v_mfma_f32_16x16x32_f16 v[52:55], v[174:177], v[190:193], v[52:55]
	v_mfma_f32_16x16x32_f16 v[48:51], v[182:185], v[190:193], v[48:51]
	v_mfma_f32_16x16x32_f16 v[36:39], v[174:177], v[198:201], v[36:39]
	v_mfma_f32_16x16x32_f16 v[32:35], v[182:185], v[198:201], v[32:35]
	v_mfma_f32_16x16x32_f16 v[20:23], v[174:177], v[206:209], v[20:23]
	v_mfma_f32_16x16x32_f16 v[16:19], v[182:185], v[206:209], v[16:19]
	v_mfma_f32_16x16x32_f16 v[4:7], v[174:177], v[214:217], v[4:7]
	v_mfma_f32_16x16x32_f16 v[0:3], v[182:185], v[214:217], v[0:3]
	v_mfma_f32_16x16x32_f16 v[52:55], v[178:181], v[194:197], v[52:55]
	v_mfma_f32_16x16x32_f16 v[48:51], v[186:189], v[194:197], v[48:51]
	v_mfma_f32_16x16x32_f16 v[36:39], v[178:181], v[202:205], v[36:39]
	v_mfma_f32_16x16x32_f16 v[32:35], v[186:189], v[202:205], v[32:35]
	v_mfma_f32_16x16x32_f16 v[20:23], v[178:181], v[210:213], v[20:23]
	v_mfma_f32_16x16x32_f16 v[16:19], v[186:189], v[210:213], v[16:19]
	v_mfma_f32_16x16x32_f16 v[4:7], v[178:181], v[218:221], v[4:7]
	v_mfma_f32_16x16x32_f16 v[0:3], v[186:189], v[218:221], v[0:3]
	s_barrier
	ds_read_b128 v[158:161], v154
	ds_read_b128 v[162:165], v154 offset:1024
	ds_read_b128 v[166:169], v154 offset:2048
	ds_read_b128 v[170:173], v154 offset:3072
	ds_read_b128 v[174:177], v155
	ds_read_b128 v[178:181], v155 offset:1024
	ds_read_b128 v[182:185], v155 offset:2048
	ds_read_b128 v[186:189], v155 offset:3072
	s_add_u32 s34, s34, 0x40000
	s_addc_u32 s35, s35, 0
	s_mov_b32 m0, s41
	v_lshl_add_u64 v[230:231], s[34:35], 0, v[134:135]
	ds_read_b128 v[190:193], v153 offset:32768
	ds_read_b128 v[194:197], v153 offset:33792
	ds_read_b128 v[198:201], v153 offset:34816
	ds_read_b128 v[202:205], v153 offset:35840
	ds_read_b128 v[206:209], v153 offset:36864
	ds_read_b128 v[210:213], v153 offset:37888
	ds_read_b128 v[214:217], v153 offset:38912
	ds_read_b128 v[218:221], v153 offset:39936
	global_load_lds_dwordx4 v[230:231], off
	v_lshl_add_u64 v[230:231], s[34:35], 0, v[130:131]
	s_mov_b32 m0, s42
	s_nop 0
	global_load_lds_dwordx4 v[230:231], off
	s_waitcnt vmcnt(8)
	s_waitcnt lgkmcnt(0)
	s_barrier
	s_waitcnt lgkmcnt(0)
	v_mfma_f32_16x16x32_f16 v[124:127], v[158:161], v[190:193], v[124:127]
	v_mfma_f32_16x16x32_f16 v[120:123], v[166:169], v[190:193], v[120:123]
	v_mfma_f32_16x16x32_f16 v[108:111], v[158:161], v[198:201], v[108:111]
	v_mfma_f32_16x16x32_f16 v[104:107], v[166:169], v[198:201], v[104:107]
	v_mfma_f32_16x16x32_f16 v[92:95], v[158:161], v[206:209], v[92:95]
	v_mfma_f32_16x16x32_f16 v[88:91], v[166:169], v[206:209], v[88:91]
	v_mfma_f32_16x16x32_f16 v[76:79], v[158:161], v[214:217], v[76:79]
	v_mfma_f32_16x16x32_f16 v[72:75], v[166:169], v[214:217], v[72:75]
	v_mfma_f32_16x16x32_f16 v[124:127], v[162:165], v[194:197], v[124:127]
	v_mfma_f32_16x16x32_f16 v[120:123], v[170:173], v[194:197], v[120:123]
	v_mfma_f32_16x16x32_f16 v[108:111], v[162:165], v[202:205], v[108:111]
	v_mfma_f32_16x16x32_f16 v[104:107], v[170:173], v[202:205], v[104:107]
	v_mfma_f32_16x16x32_f16 v[92:95], v[162:165], v[210:213], v[92:95]
	v_mfma_f32_16x16x32_f16 v[88:91], v[170:173], v[210:213], v[88:91]
	v_mfma_f32_16x16x32_f16 v[76:79], v[162:165], v[218:221], v[76:79]
	v_mfma_f32_16x16x32_f16 v[72:75], v[170:173], v[218:221], v[72:75]
	v_mfma_f32_16x16x32_f16 v[116:119], v[174:177], v[190:193], v[116:119]
	v_mfma_f32_16x16x32_f16 v[112:115], v[182:185], v[190:193], v[112:115]
	v_mfma_f32_16x16x32_f16 v[100:103], v[174:177], v[198:201], v[100:103]
	v_mfma_f32_16x16x32_f16 v[96:99], v[182:185], v[198:201], v[96:99]
	v_mfma_f32_16x16x32_f16 v[84:87], v[174:177], v[206:209], v[84:87]
	v_mfma_f32_16x16x32_f16 v[80:83], v[182:185], v[206:209], v[80:83]
	v_mfma_f32_16x16x32_f16 v[68:71], v[174:177], v[214:217], v[68:71]
	v_mfma_f32_16x16x32_f16 v[64:67], v[182:185], v[214:217], v[64:67]
	v_mfma_f32_16x16x32_f16 v[116:119], v[178:181], v[194:197], v[116:119]
	v_mfma_f32_16x16x32_f16 v[112:115], v[186:189], v[194:197], v[112:115]
	v_mfma_f32_16x16x32_f16 v[100:103], v[178:181], v[202:205], v[100:103]
	v_mfma_f32_16x16x32_f16 v[96:99], v[186:189], v[202:205], v[96:99]
	v_mfma_f32_16x16x32_f16 v[84:87], v[178:181], v[210:213], v[84:87]
	v_mfma_f32_16x16x32_f16 v[80:83], v[186:189], v[210:213], v[80:83]
	v_mfma_f32_16x16x32_f16 v[68:71], v[178:181], v[218:221], v[68:71]
	v_mfma_f32_16x16x32_f16 v[64:67], v[186:189], v[218:221], v[64:67]
	s_barrier
	s_add_i32 s34, s48, s3
	v_lshl_add_u64 v[222:223], v[222:223], 0, s[10:11]
	s_mov_b32 m0, s34
	ds_read_b128 v[190:193], v153 offset:49152
	ds_read_b128 v[194:197], v153 offset:50176
	ds_read_b128 v[198:201], v153 offset:51200
	ds_read_b128 v[202:205], v153 offset:52224
	ds_read_b128 v[206:209], v153 offset:53248
	ds_read_b128 v[210:213], v153 offset:54272
	ds_read_b128 v[214:217], v153 offset:55296
	ds_read_b128 v[218:221], v153 offset:56320
	global_load_lds_dwordx4 v[222:223], off
	s_add_i32 m0, s34, 0x2000
	s_add_u32 s30, s30, 0x40080
	v_lshl_add_u64 v[222:223], v[224:225], 0, s[10:11]
	s_addc_u32 s31, s31, 0
	s_add_i32 s34, s49, s3
	global_load_lds_dwordx4 v[222:223], off
	v_lshl_add_u64 v[222:223], s[30:31], 0, v[132:133]
	s_mov_b32 m0, s34
	s_nop 0
	global_load_lds_dwordx4 v[222:223], off
	v_lshl_add_u64 v[222:223], s[30:31], 0, v[128:129]
	s_add_i32 m0, s34, 0x2000
	s_nop 0
	global_load_lds_dwordx4 v[222:223], off
	v_lshl_add_u64 v[222:223], v[226:227], 0, s[10:11]
	s_mov_b32 m0, s43
	s_nop 0
	global_load_lds_dwordx4 v[222:223], off
	v_lshl_add_u64 v[222:223], v[228:229], 0, s[10:11]
	s_mov_b32 m0, s44
	s_nop 0
	global_load_lds_dwordx4 v[222:223], off
	s_waitcnt vmcnt(8)
	s_waitcnt lgkmcnt(0)
	s_barrier
	s_waitcnt lgkmcnt(0)
	v_mfma_f32_16x16x32_f16 v[60:63], v[158:161], v[190:193], v[60:63]
	v_mfma_f32_16x16x32_f16 v[56:59], v[166:169], v[190:193], v[56:59]
	v_mfma_f32_16x16x32_f16 v[44:47], v[158:161], v[198:201], v[44:47]
	v_mfma_f32_16x16x32_f16 v[40:43], v[166:169], v[198:201], v[40:43]
	v_mfma_f32_16x16x32_f16 v[28:31], v[158:161], v[206:209], v[28:31]
	v_mfma_f32_16x16x32_f16 v[24:27], v[166:169], v[206:209], v[24:27]
	v_mfma_f32_16x16x32_f16 v[12:15], v[158:161], v[214:217], v[12:15]
	v_mfma_f32_16x16x32_f16 v[8:11], v[166:169], v[214:217], v[8:11]
	v_mfma_f32_16x16x32_f16 v[60:63], v[162:165], v[194:197], v[60:63]
	v_mfma_f32_16x16x32_f16 v[56:59], v[170:173], v[194:197], v[56:59]
	v_mfma_f32_16x16x32_f16 v[44:47], v[162:165], v[202:205], v[44:47]
	v_mfma_f32_16x16x32_f16 v[40:43], v[170:173], v[202:205], v[40:43]
	v_mfma_f32_16x16x32_f16 v[28:31], v[162:165], v[210:213], v[28:31]
	v_mfma_f32_16x16x32_f16 v[24:27], v[170:173], v[210:213], v[24:27]
	v_mfma_f32_16x16x32_f16 v[12:15], v[162:165], v[218:221], v[12:15]
	v_mfma_f32_16x16x32_f16 v[8:11], v[170:173], v[218:221], v[8:11]
	v_mfma_f32_16x16x32_f16 v[52:55], v[174:177], v[190:193], v[52:55]
	v_mfma_f32_16x16x32_f16 v[48:51], v[182:185], v[190:193], v[48:51]
	v_mfma_f32_16x16x32_f16 v[36:39], v[174:177], v[198:201], v[36:39]
	v_mfma_f32_16x16x32_f16 v[32:35], v[182:185], v[198:201], v[32:35]
	v_mfma_f32_16x16x32_f16 v[20:23], v[174:177], v[206:209], v[20:23]
	v_mfma_f32_16x16x32_f16 v[16:19], v[182:185], v[206:209], v[16:19]
	v_mfma_f32_16x16x32_f16 v[4:7], v[174:177], v[214:217], v[4:7]
	v_mfma_f32_16x16x32_f16 v[0:3], v[182:185], v[214:217], v[0:3]
	v_mfma_f32_16x16x32_f16 v[52:55], v[178:181], v[194:197], v[52:55]
	v_mfma_f32_16x16x32_f16 v[48:51], v[186:189], v[194:197], v[48:51]
	v_mfma_f32_16x16x32_f16 v[36:39], v[178:181], v[202:205], v[36:39]
	v_mfma_f32_16x16x32_f16 v[32:35], v[186:189], v[202:205], v[32:35]
	v_mfma_f32_16x16x32_f16 v[20:23], v[178:181], v[210:213], v[20:23]
	v_mfma_f32_16x16x32_f16 v[16:19], v[186:189], v[210:213], v[16:19]
	v_mfma_f32_16x16x32_f16 v[4:7], v[178:181], v[218:221], v[4:7]
	v_mfma_f32_16x16x32_f16 v[0:3], v[186:189], v[218:221], v[0:3]
	s_barrier
	s_add_i32 s51, s51, 2
	s_add_u32 s22, s22, 0x100
	s_addc_u32 s23, s23, 0
	s_add_u32 s13, s13, 0x100
	s_addc_u32 s15, s15, 0
	s_cmp_gt_u32 s51, 13
	s_cbranch_scc0 .LBB0_1429
	s_and_b64 vcc, exec, s[26:27]
	s_cbranch_vccz .LBB0_1432
	s_barrier

.LBB0_1469:
	ds_read_b128 v[0:3], v146
	ds_read_b128 v[4:7], v146 offset:1024
	ds_read_b128 v[8:11], v146 offset:2048
	ds_read_b128 v[12:15], v146 offset:3072
	ds_read_b128 v[16:19], v147
	ds_read_b128 v[20:23], v147 offset:1024
	ds_read_b128 v[24:27], v147 offset:2048
	ds_read_b128 v[28:31], v147 offset:3072
	s_add_u32 s6, s8, 0x10080
	s_addc_u32 s7, s9, 0
	s_add_i32 s16, s63, 0xc000
	v_lshl_add_u64 v[64:65], s[6:7], 0, v[128:129]
	s_mov_b32 m0, s16
	ds_read_b128 v[32:35], v148
	ds_read_b128 v[36:39], v148 offset:1024
	ds_read_b128 v[40:43], v148 offset:2048
	ds_read_b128 v[44:47], v148 offset:3072
	ds_read_b128 v[48:51], v148 offset:4096
	ds_read_b128 v[52:55], v148 offset:5120
	ds_read_b128 v[56:59], v148 offset:6144
	ds_read_b128 v[60:63], v148 offset:7168
	global_load_lds_dwordx4 v[64:65], off
	v_lshl_add_u64 v[64:65], s[6:7], 0, v[132:133]
	s_add_i32 s6, s63, 0xe000
	s_mov_b32 m0, s6
	s_nop 0
	global_load_lds_dwordx4 v[64:65], off
	s_waitcnt vmcnt(8)
	s_waitcnt lgkmcnt(0)
	s_barrier
	s_waitcnt lgkmcnt(0)
	v_mfma_f32_16x16x32_f16 v[64:67], v[0:3], v[32:35], 0
	v_mfma_f32_16x16x32_f16 v[68:71], v[8:11], v[32:35], 0
	v_mfma_f32_16x16x32_f16 v[72:75], v[0:3], v[40:43], 0
	v_mfma_f32_16x16x32_f16 v[76:79], v[8:11], v[40:43], 0
	v_mfma_f32_16x16x32_f16 v[80:83], v[0:3], v[48:51], 0
	v_mfma_f32_16x16x32_f16 v[84:87], v[8:11], v[48:51], 0
	v_mfma_f32_16x16x32_f16 v[88:91], v[0:3], v[56:59], 0
	v_mfma_f32_16x16x32_f16 v[92:95], v[8:11], v[56:59], 0
	v_mfma_f32_16x16x32_f16 v[64:67], v[4:7], v[36:39], v[64:67]
	v_mfma_f32_16x16x32_f16 v[68:71], v[12:15], v[36:39], v[68:71]
	v_mfma_f32_16x16x32_f16 v[72:75], v[4:7], v[44:47], v[72:75]
	v_mfma_f32_16x16x32_f16 v[76:79], v[12:15], v[44:47], v[76:79]
	v_mfma_f32_16x16x32_f16 v[80:83], v[4:7], v[52:55], v[80:83]
	v_mfma_f32_16x16x32_f16 v[84:87], v[12:15], v[52:55], v[84:87]
	v_mfma_f32_16x16x32_f16 v[88:91], v[4:7], v[60:63], v[88:91]
	v_mfma_f32_16x16x32_f16 v[92:95], v[12:15], v[60:63], v[92:95]
	v_mfma_f32_16x16x32_f16 v[96:99], v[16:19], v[32:35], 0
	v_mfma_f32_16x16x32_f16 v[32:35], v[24:27], v[32:35], 0
	v_mfma_f32_16x16x32_f16 v[96:99], v[20:23], v[36:39], v[96:99]
	v_mfma_f32_16x16x32_f16 v[32:35], v[28:31], v[36:39], v[32:35]
	v_mfma_f32_16x16x32_f16 v[36:39], v[16:19], v[40:43], 0
	v_mfma_f32_16x16x32_f16 v[40:43], v[24:27], v[40:43], 0
	v_mfma_f32_16x16x32_f16 v[36:39], v[20:23], v[44:47], v[36:39]
	v_mfma_f32_16x16x32_f16 v[40:43], v[28:31], v[44:47], v[40:43]
	v_mfma_f32_16x16x32_f16 v[44:47], v[16:19], v[48:51], 0
	v_mfma_f32_16x16x32_f16 v[48:51], v[24:27], v[48:51], 0
	v_mfma_f32_16x16x32_f16 v[44:47], v[20:23], v[52:55], v[44:47]
	v_mfma_f32_16x16x32_f16 v[48:51], v[28:31], v[52:55], v[48:51]
	v_mfma_f32_16x16x32_f16 v[52:55], v[16:19], v[56:59], 0
	v_mfma_f32_16x16x32_f16 v[56:59], v[24:27], v[56:59], 0
	v_mfma_f32_16x16x32_f16 v[52:55], v[20:23], v[60:63], v[52:55]
	v_mfma_f32_16x16x32_f16 v[56:59], v[28:31], v[60:63], v[56:59]
	s_barrier
	s_add_i32 s15, s82, s3
	v_lshl_add_u64 v[142:143], s[10:11], 0, v[130:131]
	s_add_i32 s7, s15, 0x2000
	v_lshl_add_u64 v[154:155], v[142:143], 0, s[38:39]
	s_mov_b32 m0, s15
	v_lshl_add_u64 v[218:219], s[10:11], 0, v[134:135]
	s_add_u32 s18, s10, 0x10100
	ds_read_b128 v[60:63], v148 offset:16384
	ds_read_b128 v[100:103], v148 offset:17408
	ds_read_b128 v[104:107], v148 offset:18432
	ds_read_b128 v[108:111], v148 offset:19456
	ds_read_b128 v[112:115], v148 offset:20480
	ds_read_b128 v[116:119], v148 offset:21504
	ds_read_b128 v[120:123], v148 offset:22528
	ds_read_b128 v[124:127], v148 offset:23552
	global_load_lds_dwordx4 v[154:155], off
	v_lshl_add_u64 v[154:155], v[218:219], 0, s[38:39]
	s_mov_b32 m0, s7
	s_addc_u32 s19, s11, 0
	s_add_i32 s12, s83, s3
	global_load_lds_dwordx4 v[154:155], off
	v_lshl_add_u64 v[154:155], s[18:19], 0, v[130:131]
	s_mov_b32 m0, s12
	s_add_i32 s13, s12, 0x2000
	global_load_lds_dwordx4 v[154:155], off
	v_lshl_add_u64 v[154:155], s[18:19], 0, v[134:135]
	s_mov_b32 m0, s13
	v_lshl_add_u64 v[220:221], s[8:9], 0, v[128:129]
	global_load_lds_dwordx4 v[154:155], off
	v_lshl_add_u64 v[154:155], v[220:221], 0, s[38:39]
	s_mov_b32 m0, s63
	v_lshl_add_u64 v[222:223], s[8:9], 0, v[132:133]
	global_load_lds_dwordx4 v[154:155], off
	v_lshl_add_u64 v[154:155], v[222:223], 0, s[38:39]
	s_mov_b32 m0, s64
	s_nop 0
	global_load_lds_dwordx4 v[154:155], off
	s_waitcnt vmcnt(8)
	s_waitcnt lgkmcnt(0)
	s_barrier
	s_waitcnt lgkmcnt(0)
	v_mfma_f32_16x16x32_f16 v[154:157], v[0:3], v[60:63], 0
	v_mfma_f32_16x16x32_f16 v[162:165], v[0:3], v[104:107], 0
	v_mfma_f32_16x16x32_f16 v[170:173], v[0:3], v[112:115], 0
	v_mfma_f32_16x16x32_f16 v[0:3], v[0:3], v[120:123], 0
	v_mfma_f32_16x16x32_f16 v[154:157], v[4:7], v[100:103], v[154:157]
	v_mfma_f32_16x16x32_f16 v[162:165], v[4:7], v[108:111], v[162:165]
	v_mfma_f32_16x16x32_f16 v[170:173], v[4:7], v[116:119], v[170:173]
	v_mfma_f32_16x16x32_f16 v[0:3], v[4:7], v[124:127], v[0:3]
	v_mfma_f32_16x16x32_f16 v[4:7], v[8:11], v[120:123], 0
	v_mfma_f32_16x16x32_f16 v[158:161], v[8:11], v[60:63], 0
	v_mfma_f32_16x16x32_f16 v[166:169], v[8:11], v[104:107], 0
	v_mfma_f32_16x16x32_f16 v[174:177], v[8:11], v[112:115], 0
	v_mfma_f32_16x16x32_f16 v[4:7], v[12:15], v[124:127], v[4:7]
	v_mfma_f32_16x16x32_f16 v[158:161], v[12:15], v[100:103], v[158:161]
	v_mfma_f32_16x16x32_f16 v[166:169], v[12:15], v[108:111], v[166:169]
	v_mfma_f32_16x16x32_f16 v[174:177], v[12:15], v[116:119], v[174:177]
	v_mfma_f32_16x16x32_f16 v[8:11], v[16:19], v[60:63], 0
	v_mfma_f32_16x16x32_f16 v[12:15], v[24:27], v[60:63], 0
	v_mfma_f32_16x16x32_f16 v[8:11], v[20:23], v[100:103], v[8:11]
	v_mfma_f32_16x16x32_f16 v[12:15], v[28:31], v[100:103], v[12:15]
	v_mfma_f32_16x16x32_f16 v[60:63], v[16:19], v[104:107], 0
	v_mfma_f32_16x16x32_f16 v[100:103], v[24:27], v[104:107], 0
	v_mfma_f32_16x16x32_f16 v[104:107], v[16:19], v[112:115], 0
	v_mfma_f32_16x16x32_f16 v[16:19], v[16:19], v[120:123], 0
	v_mfma_f32_16x16x32_f16 v[60:63], v[20:23], v[108:111], v[60:63]
	v_mfma_f32_16x16x32_f16 v[100:103], v[28:31], v[108:111], v[100:103]
	v_mfma_f32_16x16x32_f16 v[104:107], v[20:23], v[116:119], v[104:107]
	v_mfma_f32_16x16x32_f16 v[108:111], v[24:27], v[112:115], 0
	v_mfma_f32_16x16x32_f16 v[16:19], v[20:23], v[124:127], v[16:19]
	v_mfma_f32_16x16x32_f16 v[20:23], v[24:27], v[120:123], 0
	v_mfma_f32_16x16x32_f16 v[108:111], v[28:31], v[116:119], v[108:111]
	v_mfma_f32_16x16x32_f16 v[20:23], v[28:31], v[124:127], v[20:23]
	s_barrier
	ds_read_b128 v[24:27], v149
	ds_read_b128 v[28:31], v149 offset:1024
	ds_read_b128 v[112:115], v149 offset:2048
	ds_read_b128 v[116:119], v149 offset:3072
	ds_read_b128 v[120:123], v150
	ds_read_b128 v[124:127], v150 offset:1024
	ds_read_b128 v[178:181], v150 offset:2048
	ds_read_b128 v[182:185], v150 offset:3072
	s_add_u32 s18, s8, 0x10100
	s_addc_u32 s19, s9, 0
	s_mov_b32 m0, s65
	v_lshl_add_u64 v[224:225], s[18:19], 0, v[128:129]
	ds_read_b128 v[186:189], v148 offset:32768
	ds_read_b128 v[190:193], v148 offset:33792
	ds_read_b128 v[194:197], v148 offset:34816
	ds_read_b128 v[198:201], v148 offset:35840
	ds_read_b128 v[202:205], v148 offset:36864
	ds_read_b128 v[206:209], v148 offset:37888
	ds_read_b128 v[210:213], v148 offset:38912
	ds_read_b128 v[214:217], v148 offset:39936
	global_load_lds_dwordx4 v[224:225], off
	v_lshl_add_u64 v[224:225], s[18:19], 0, v[132:133]
	s_mov_b32 m0, s66
	s_nop 0
	global_load_lds_dwordx4 v[224:225], off
	s_waitcnt vmcnt(8)
	s_waitcnt lgkmcnt(0)
	s_barrier
	s_waitcnt lgkmcnt(0)
	v_mfma_f32_16x16x32_f16 v[64:67], v[24:27], v[186:189], v[64:67]
	v_mfma_f32_16x16x32_f16 v[68:71], v[112:115], v[186:189], v[68:71]
	v_mfma_f32_16x16x32_f16 v[72:75], v[24:27], v[194:197], v[72:75]
	v_mfma_f32_16x16x32_f16 v[76:79], v[112:115], v[194:197], v[76:79]
	v_mfma_f32_16x16x32_f16 v[80:83], v[24:27], v[202:205], v[80:83]
	v_mfma_f32_16x16x32_f16 v[84:87], v[112:115], v[202:205], v[84:87]
	v_mfma_f32_16x16x32_f16 v[88:91], v[24:27], v[210:213], v[88:91]
	v_mfma_f32_16x16x32_f16 v[92:95], v[112:115], v[210:213], v[92:95]
	v_mfma_f32_16x16x32_f16 v[64:67], v[28:31], v[190:193], v[64:67]
	v_mfma_f32_16x16x32_f16 v[68:71], v[116:119], v[190:193], v[68:71]
	v_mfma_f32_16x16x32_f16 v[72:75], v[28:31], v[198:201], v[72:75]
	v_mfma_f32_16x16x32_f16 v[76:79], v[116:119], v[198:201], v[76:79]
	v_mfma_f32_16x16x32_f16 v[80:83], v[28:31], v[206:209], v[80:83]
	v_mfma_f32_16x16x32_f16 v[84:87], v[116:119], v[206:209], v[84:87]
	v_mfma_f32_16x16x32_f16 v[88:91], v[28:31], v[214:217], v[88:91]
	v_mfma_f32_16x16x32_f16 v[92:95], v[116:119], v[214:217], v[92:95]
	v_mfma_f32_16x16x32_f16 v[96:99], v[120:123], v[186:189], v[96:99]
	v_mfma_f32_16x16x32_f16 v[32:35], v[178:181], v[186:189], v[32:35]
	v_mfma_f32_16x16x32_f16 v[36:39], v[120:123], v[194:197], v[36:39]
	v_mfma_f32_16x16x32_f16 v[40:43], v[178:181], v[194:197], v[40:43]
	v_mfma_f32_16x16x32_f16 v[44:47], v[120:123], v[202:205], v[44:47]
	v_mfma_f32_16x16x32_f16 v[48:51], v[178:181], v[202:205], v[48:51]
	v_mfma_f32_16x16x32_f16 v[52:55], v[120:123], v[210:213], v[52:55]
	v_mfma_f32_16x16x32_f16 v[56:59], v[178:181], v[210:213], v[56:59]
	v_mfma_f32_16x16x32_f16 v[96:99], v[124:127], v[190:193], v[96:99]
	v_mfma_f32_16x16x32_f16 v[32:35], v[182:185], v[190:193], v[32:35]
	v_mfma_f32_16x16x32_f16 v[36:39], v[124:127], v[198:201], v[36:39]
	v_mfma_f32_16x16x32_f16 v[40:43], v[182:185], v[198:201], v[40:43]
	v_mfma_f32_16x16x32_f16 v[44:47], v[124:127], v[206:209], v[44:47]
	v_mfma_f32_16x16x32_f16 v[48:51], v[182:185], v[206:209], v[48:51]
	v_mfma_f32_16x16x32_f16 v[52:55], v[124:127], v[214:217], v[52:55]
	v_mfma_f32_16x16x32_f16 v[56:59], v[182:185], v[214:217], v[56:59]
	s_barrier
	s_add_i32 s17, s84, s3
	s_add_i32 s14, s17, 0x2000
	v_lshl_add_u64 v[142:143], v[142:143], 0, s[40:41]
	s_mov_b32 m0, s17
	s_add_u32 s18, s10, 0x10180
	ds_read_b128 v[186:189], v148 offset:49152
	ds_read_b128 v[190:193], v148 offset:50176
	ds_read_b128 v[194:197], v148 offset:51200
	ds_read_b128 v[198:201], v148 offset:52224
	ds_read_b128 v[202:205], v148 offset:53248
	ds_read_b128 v[206:209], v148 offset:54272
	ds_read_b128 v[210:213], v148 offset:55296
	ds_read_b128 v[214:217], v148 offset:56320
	global_load_lds_dwordx4 v[142:143], off
	v_lshl_add_u64 v[142:143], v[218:219], 0, s[40:41]
	s_mov_b32 m0, s14
	s_addc_u32 s19, s11, 0
	s_add_i32 s10, s85, s3
	global_load_lds_dwordx4 v[142:143], off
	v_lshl_add_u64 v[142:143], s[18:19], 0, v[130:131]
	s_mov_b32 m0, s10
	s_add_i32 s11, s10, 0x2000
	global_load_lds_dwordx4 v[142:143], off
	v_lshl_add_u64 v[142:143], s[18:19], 0, v[134:135]
	s_mov_b32 m0, s11
	s_nop 0
	global_load_lds_dwordx4 v[142:143], off
	v_lshl_add_u64 v[142:143], v[220:221], 0, s[40:41]
	s_mov_b32 m0, s67
	s_nop 0
	global_load_lds_dwordx4 v[142:143], off
	v_lshl_add_u64 v[142:143], v[222:223], 0, s[40:41]
	s_mov_b32 m0, s68
	s_nop 0
	global_load_lds_dwordx4 v[142:143], off
	s_waitcnt vmcnt(8)
	s_waitcnt lgkmcnt(0)
	s_barrier
	s_waitcnt lgkmcnt(0)
	v_mfma_f32_16x16x32_f16 v[0:3], v[24:27], v[210:213], v[0:3]
	v_mfma_f32_16x16x32_f16 v[4:7], v[112:115], v[210:213], v[4:7]
	v_mfma_f32_16x16x32_f16 v[154:157], v[24:27], v[186:189], v[154:157]
	v_mfma_f32_16x16x32_f16 v[158:161], v[112:115], v[186:189], v[158:161]
	v_mfma_f32_16x16x32_f16 v[162:165], v[24:27], v[194:197], v[162:165]
	v_mfma_f32_16x16x32_f16 v[166:169], v[112:115], v[194:197], v[166:169]
	v_mfma_f32_16x16x32_f16 v[170:173], v[24:27], v[202:205], v[170:173]
	v_mfma_f32_16x16x32_f16 v[174:177], v[112:115], v[202:205], v[174:177]
	v_mfma_f32_16x16x32_f16 v[0:3], v[28:31], v[214:217], v[0:3]
	v_mfma_f32_16x16x32_f16 v[4:7], v[116:119], v[214:217], v[4:7]
	v_mfma_f32_16x16x32_f16 v[154:157], v[28:31], v[190:193], v[154:157]
	v_mfma_f32_16x16x32_f16 v[158:161], v[116:119], v[190:193], v[158:161]
	v_mfma_f32_16x16x32_f16 v[162:165], v[28:31], v[198:201], v[162:165]
	v_mfma_f32_16x16x32_f16 v[166:169], v[116:119], v[198:201], v[166:169]
	v_mfma_f32_16x16x32_f16 v[170:173], v[28:31], v[206:209], v[170:173]
	v_mfma_f32_16x16x32_f16 v[174:177], v[116:119], v[206:209], v[174:177]
	v_mfma_f32_16x16x32_f16 v[8:11], v[120:123], v[186:189], v[8:11]
	v_mfma_f32_16x16x32_f16 v[12:15], v[178:181], v[186:189], v[12:15]
	v_mfma_f32_16x16x32_f16 v[24:27], v[120:123], v[194:197], v[60:63]
	v_mfma_f32_16x16x32_f16 v[28:31], v[178:181], v[194:197], v[100:103]
	v_mfma_f32_16x16x32_f16 v[60:63], v[120:123], v[202:205], v[104:107]
	v_mfma_f32_16x16x32_f16 v[100:103], v[178:181], v[202:205], v[108:111]
	v_mfma_f32_16x16x32_f16 v[16:19], v[120:123], v[210:213], v[16:19]
	v_mfma_f32_16x16x32_f16 v[20:23], v[178:181], v[210:213], v[20:23]
	v_mfma_f32_16x16x32_f16 v[8:11], v[124:127], v[190:193], v[8:11]
	v_mfma_f32_16x16x32_f16 v[12:15], v[182:185], v[190:193], v[12:15]
	v_mfma_f32_16x16x32_f16 v[24:27], v[124:127], v[198:201], v[24:27]
	v_mfma_f32_16x16x32_f16 v[28:31], v[182:185], v[198:201], v[28:31]
	v_mfma_f32_16x16x32_f16 v[60:63], v[124:127], v[206:209], v[60:63]
	v_mfma_f32_16x16x32_f16 v[100:103], v[182:185], v[206:209], v[100:103]
	v_mfma_f32_16x16x32_f16 v[16:19], v[124:127], v[214:217], v[16:19]
	v_mfma_f32_16x16x32_f16 v[20:23], v[182:185], v[214:217], v[20:23]
	s_barrier
	ds_read_b128 v[104:107], v146
	ds_read_b128 v[108:111], v146 offset:1024
	ds_read_b128 v[112:115], v146 offset:2048
	ds_read_b128 v[116:119], v146 offset:3072
	ds_read_b128 v[120:123], v147
	ds_read_b128 v[124:127], v147 offset:1024
	ds_read_b128 v[178:181], v147 offset:2048
	ds_read_b128 v[182:185], v147 offset:3072
	s_add_u32 s8, s8, 0x10180
	s_addc_u32 s9, s9, 0
	s_mov_b32 m0, s16
	v_lshl_add_u64 v[142:143], s[8:9], 0, v[128:129]
	ds_read_b128 v[186:189], v148
	ds_read_b128 v[190:193], v148 offset:1024
	ds_read_b128 v[194:197], v148 offset:2048
	ds_read_b128 v[198:201], v148 offset:3072
	ds_read_b128 v[202:205], v148 offset:4096
	ds_read_b128 v[206:209], v148 offset:5120
	ds_read_b128 v[210:213], v148 offset:6144
	ds_read_b128 v[214:217], v148 offset:7168
	global_load_lds_dwordx4 v[142:143], off
	v_lshl_add_u64 v[142:143], s[8:9], 0, v[132:133]
	s_mov_b32 m0, s6
	s_nop 0
	global_load_lds_dwordx4 v[142:143], off
	s_waitcnt vmcnt(8)
	s_waitcnt lgkmcnt(0)
	s_barrier
	s_waitcnt lgkmcnt(0)
	v_mfma_f32_16x16x32_f16 v[64:67], v[104:107], v[186:189], v[64:67]
	v_mfma_f32_16x16x32_f16 v[68:71], v[112:115], v[186:189], v[68:71]
	v_mfma_f32_16x16x32_f16 v[72:75], v[104:107], v[194:197], v[72:75]
	v_mfma_f32_16x16x32_f16 v[76:79], v[112:115], v[194:197], v[76:79]
	v_mfma_f32_16x16x32_f16 v[80:83], v[104:107], v[202:205], v[80:83]
	v_mfma_f32_16x16x32_f16 v[84:87], v[112:115], v[202:205], v[84:87]
	v_mfma_f32_16x16x32_f16 v[88:91], v[104:107], v[210:213], v[88:91]
	v_mfma_f32_16x16x32_f16 v[64:67], v[108:111], v[190:193], v[64:67]
	v_mfma_f32_16x16x32_f16 v[68:71], v[116:119], v[190:193], v[68:71]
	v_mfma_f32_16x16x32_f16 v[72:75], v[108:111], v[198:201], v[72:75]
	v_mfma_f32_16x16x32_f16 v[76:79], v[116:119], v[198:201], v[76:79]
	v_mfma_f32_16x16x32_f16 v[80:83], v[108:111], v[206:209], v[80:83]
	v_mfma_f32_16x16x32_f16 v[84:87], v[116:119], v[206:209], v[84:87]
	v_mfma_f32_16x16x32_f16 v[88:91], v[108:111], v[214:217], v[88:91]
	v_mfma_f32_16x16x32_f16 v[92:95], v[112:115], v[210:213], v[92:95]
	v_mfma_f32_16x16x32_f16 v[218:221], v[116:119], v[214:217], v[92:95]
	v_mfma_f32_16x16x32_f16 v[92:95], v[120:123], v[186:189], v[96:99]
	v_mfma_f32_16x16x32_f16 v[32:35], v[178:181], v[186:189], v[32:35]
	v_mfma_f32_16x16x32_f16 v[36:39], v[120:123], v[194:197], v[36:39]
	v_mfma_f32_16x16x32_f16 v[40:43], v[178:181], v[194:197], v[40:43]
	v_mfma_f32_16x16x32_f16 v[44:47], v[120:123], v[202:205], v[44:47]
	v_mfma_f32_16x16x32_f16 v[48:51], v[178:181], v[202:205], v[48:51]
	v_mfma_f32_16x16x32_f16 v[52:55], v[120:123], v[210:213], v[52:55]
	v_mfma_f32_16x16x32_f16 v[56:59], v[178:181], v[210:213], v[56:59]
	v_mfma_f32_16x16x32_f16 v[96:99], v[124:127], v[190:193], v[92:95]
	v_mfma_f32_16x16x32_f16 v[32:35], v[182:185], v[190:193], v[32:35]
	v_mfma_f32_16x16x32_f16 v[36:39], v[124:127], v[198:201], v[36:39]
	v_mfma_f32_16x16x32_f16 v[40:43], v[182:185], v[198:201], v[40:43]
	v_mfma_f32_16x16x32_f16 v[44:47], v[124:127], v[206:209], v[44:47]
	v_mfma_f32_16x16x32_f16 v[48:51], v[182:185], v[206:209], v[48:51]
	v_mfma_f32_16x16x32_f16 v[52:55], v[124:127], v[214:217], v[52:55]
	v_mfma_f32_16x16x32_f16 v[56:59], v[182:185], v[214:217], v[56:59]
	s_barrier
	s_mov_b32 m0, s15
	v_lshl_add_u64 v[142:143], s[48:49], 0, v[130:131]
	s_add_u32 s6, s48, 0x10000
	ds_read_b128 v[92:95], v148 offset:16384
	ds_read_b128 v[186:189], v148 offset:17408
	ds_read_b128 v[190:193], v148 offset:18432
	ds_read_b128 v[194:197], v148 offset:19456
	ds_read_b128 v[198:201], v148 offset:20480
	ds_read_b128 v[202:205], v148 offset:21504
	ds_read_b128 v[206:209], v148 offset:22528
	ds_read_b128 v[210:213], v148 offset:23552
	global_load_lds_dwordx4 v[142:143], off
	v_lshl_add_u64 v[250:251], s[48:49], 0, v[134:135]
	s_mov_b32 m0, s7
	s_addc_u32 s7, s49, 0
	global_load_lds_dwordx4 v[250:251], off
	v_lshl_add_u64 v[214:215], s[6:7], 0, v[130:131]
	s_mov_b32 m0, s12
	v_lshl_add_u64 v[252:253], s[46:47], 0, v[128:129]
	global_load_lds_dwordx4 v[214:215], off
	v_lshl_add_u64 v[214:215], s[6:7], 0, v[134:135]
	s_mov_b32 m0, s13
	v_lshl_add_u64 v[152:153], s[46:47], 0, v[132:133]
	global_load_lds_dwordx4 v[214:215], off
	s_mov_b32 m0, s63
	s_nop 0
	global_load_lds_dwordx4 v[252:253], off
	s_mov_b32 m0, s64
	s_nop 0
	global_load_lds_dwordx4 v[152:153], off
	s_waitcnt vmcnt(8)
	s_waitcnt lgkmcnt(0)
	s_barrier
	s_waitcnt lgkmcnt(0)
	v_mfma_f32_16x16x32_f16 v[0:3], v[104:107], v[206:209], v[0:3]
	v_mfma_f32_16x16x32_f16 v[4:7], v[112:115], v[206:209], v[4:7]
	v_mfma_f32_16x16x32_f16 v[154:157], v[104:107], v[92:95], v[154:157]
	v_mfma_f32_16x16x32_f16 v[158:161], v[112:115], v[92:95], v[158:161]
	v_mfma_f32_16x16x32_f16 v[162:165], v[104:107], v[190:193], v[162:165]
	v_mfma_f32_16x16x32_f16 v[166:169], v[112:115], v[190:193], v[166:169]
	v_mfma_f32_16x16x32_f16 v[170:173], v[104:107], v[198:201], v[170:173]
	v_mfma_f32_16x16x32_f16 v[174:177], v[112:115], v[198:201], v[174:177]
	v_mfma_f32_16x16x32_f16 v[0:3], v[108:111], v[210:213], v[0:3]
	v_mfma_f32_16x16x32_f16 v[4:7], v[116:119], v[210:213], v[4:7]
	v_mfma_f32_16x16x32_f16 v[154:157], v[108:111], v[186:189], v[154:157]
	v_mfma_f32_16x16x32_f16 v[158:161], v[116:119], v[186:189], v[158:161]
	v_mfma_f32_16x16x32_f16 v[162:165], v[108:111], v[194:197], v[162:165]
	v_mfma_f32_16x16x32_f16 v[166:169], v[116:119], v[194:197], v[166:169]
	v_mfma_f32_16x16x32_f16 v[170:173], v[108:111], v[202:205], v[170:173]
	v_mfma_f32_16x16x32_f16 v[174:177], v[116:119], v[202:205], v[174:177]
	v_mfma_f32_16x16x32_f16 v[8:11], v[120:123], v[92:95], v[8:11]
	v_mfma_f32_16x16x32_f16 v[12:15], v[178:181], v[92:95], v[12:15]
	v_mfma_f32_16x16x32_f16 v[8:11], v[124:127], v[186:189], v[8:11]
	v_mfma_f32_16x16x32_f16 v[186:189], v[182:185], v[186:189], v[12:15]
	v_mfma_f32_16x16x32_f16 v[12:15], v[120:123], v[190:193], v[24:27]
	v_mfma_f32_16x16x32_f16 v[24:27], v[124:127], v[194:197], v[12:15]
	v_mfma_f32_16x16x32_f16 v[12:15], v[178:181], v[190:193], v[28:31]
	v_mfma_f32_16x16x32_f16 v[190:193], v[182:185], v[194:197], v[12:15]
	v_mfma_f32_16x16x32_f16 v[12:15], v[120:123], v[198:201], v[60:63]
	v_mfma_f32_16x16x32_f16 v[194:197], v[124:127], v[202:205], v[12:15]
	v_mfma_f32_16x16x32_f16 v[12:15], v[178:181], v[198:201], v[100:103]
	v_mfma_f32_16x16x32_f16 v[198:201], v[182:185], v[202:205], v[12:15]
	v_mfma_f32_16x16x32_f16 v[12:15], v[120:123], v[206:209], v[16:19]
	v_mfma_f32_16x16x32_f16 v[202:205], v[124:127], v[210:213], v[12:15]
	v_mfma_f32_16x16x32_f16 v[12:15], v[178:181], v[206:209], v[20:23]
	v_mfma_f32_16x16x32_f16 v[178:181], v[182:185], v[210:213], v[12:15]
	s_barrier
	s_nop 4
	ds_read_b128 v[12:15], v149
	ds_read_b128 v[16:19], v149 offset:1024
	ds_read_b128 v[182:185], v149 offset:2048
	ds_read_b128 v[206:209], v149 offset:3072
	ds_read_b128 v[210:213], v150
	ds_read_b128 v[214:217], v150 offset:1024
	ds_read_b128 v[222:225], v150 offset:2048
	ds_read_b128 v[226:229], v150 offset:3072
	s_add_u32 s6, s46, 0x10000
	s_addc_u32 s7, s47, 0
	s_mov_b32 m0, s65
	v_lshl_add_u64 v[92:93], s[6:7], 0, v[128:129]
	ds_read_b128 v[20:23], v148 offset:32768
	ds_read_b128 v[28:31], v148 offset:33792
	ds_read_b128 v[60:63], v148 offset:34816
	ds_read_b128 v[230:233], v148 offset:35840
	ds_read_b128 v[234:237], v148 offset:36864
	ds_read_b128 v[238:241], v148 offset:37888
	ds_read_b128 v[242:245], v148 offset:38912
	ds_read_b128 v[246:249], v148 offset:39936
	global_load_lds_dwordx4 v[92:93], off
	v_lshl_add_u64 v[92:93], s[6:7], 0, v[132:133]
	s_mov_b32 m0, s66
	s_nop 0
	global_load_lds_dwordx4 v[92:93], off
	s_waitcnt vmcnt(8)
	s_waitcnt lgkmcnt(0)
	s_barrier
	s_waitcnt lgkmcnt(0)
	v_mfma_f32_16x16x32_f16 v[64:67], v[12:15], v[20:23], v[64:67]
	v_mfma_f32_16x16x32_f16 v[124:127], v[16:19], v[28:31], v[64:67]
	v_mfma_f32_16x16x32_f16 v[64:67], v[182:185], v[20:23], v[68:71]
	v_mfma_f32_16x16x32_f16 v[116:119], v[206:209], v[28:31], v[64:67]
	v_mfma_f32_16x16x32_f16 v[64:67], v[12:15], v[60:63], v[72:75]
	v_mfma_f32_16x16x32_f16 v[108:111], v[16:19], v[230:233], v[64:67]
	v_mfma_f32_16x16x32_f16 v[64:67], v[182:185], v[60:63], v[76:79]
	v_mfma_f32_16x16x32_f16 v[100:103], v[206:209], v[230:233], v[64:67]
	v_mfma_f32_16x16x32_f16 v[64:67], v[12:15], v[234:237], v[80:83]
	v_mfma_f32_16x16x32_f16 v[92:95], v[16:19], v[238:241], v[64:67]
	v_mfma_f32_16x16x32_f16 v[64:67], v[182:185], v[234:237], v[84:87]
	v_mfma_f32_16x16x32_f16 v[84:87], v[206:209], v[238:241], v[64:67]
	v_mfma_f32_16x16x32_f16 v[64:67], v[12:15], v[242:245], v[88:91]
	v_mfma_f32_16x16x32_f16 v[76:79], v[16:19], v[246:249], v[64:67]
	v_mfma_f32_16x16x32_f16 v[64:67], v[182:185], v[242:245], v[218:221]
	v_mfma_f32_16x16x32_f16 v[68:71], v[206:209], v[246:249], v[64:67]
	v_mfma_f32_16x16x32_f16 v[64:67], v[210:213], v[20:23], v[96:99]
	v_mfma_f32_16x16x32_f16 v[20:23], v[222:225], v[20:23], v[32:35]
	v_mfma_f32_16x16x32_f16 v[112:115], v[226:229], v[28:31], v[20:23]
	v_mfma_f32_16x16x32_f16 v[20:23], v[210:213], v[60:63], v[36:39]
	v_mfma_f32_16x16x32_f16 v[104:107], v[214:217], v[230:233], v[20:23]
	v_mfma_f32_16x16x32_f16 v[20:23], v[222:225], v[60:63], v[40:43]
	v_mfma_f32_16x16x32_f16 v[96:99], v[226:229], v[230:233], v[20:23]
	v_mfma_f32_16x16x32_f16 v[20:23], v[210:213], v[234:237], v[44:47]
	v_mfma_f32_16x16x32_f16 v[88:91], v[214:217], v[238:241], v[20:23]
	v_mfma_f32_16x16x32_f16 v[20:23], v[222:225], v[234:237], v[48:51]
	v_mfma_f32_16x16x32_f16 v[80:83], v[226:229], v[238:241], v[20:23]
	v_mfma_f32_16x16x32_f16 v[20:23], v[210:213], v[242:245], v[52:55]
	v_mfma_f32_16x16x32_f16 v[72:75], v[214:217], v[246:249], v[20:23]
	v_mfma_f32_16x16x32_f16 v[20:23], v[222:225], v[242:245], v[56:59]
	v_mfma_f32_16x16x32_f16 v[120:123], v[214:217], v[28:31], v[64:67]
	v_mfma_f32_16x16x32_f16 v[64:67], v[226:229], v[246:249], v[20:23]
	s_barrier
	s_mov_b32 m0, s17
	s_nop 2
	v_lshl_add_u64 v[20:21], v[142:143], 0, s[34:35]
	s_add_u32 s6, s48, 0x10080
	ds_read_b128 v[32:35], v148 offset:49152
	ds_read_b128 v[40:43], v148 offset:50176
	ds_read_b128 v[218:221], v148 offset:51200
	ds_read_b128 v[230:233], v148 offset:52224
	ds_read_b128 v[234:237], v148 offset:53248
	ds_read_b128 v[238:241], v148 offset:54272
	ds_read_b128 v[242:245], v148 offset:55296
	ds_read_b128 v[246:249], v148 offset:56320
	global_load_lds_dwordx4 v[20:21], off
	v_lshl_add_u64 v[20:21], v[250:251], 0, s[34:35]
	s_mov_b32 m0, s14
	s_addc_u32 s7, s49, 0
	global_load_lds_dwordx4 v[20:21], off
	v_lshl_add_u64 v[20:21], s[6:7], 0, v[130:131]
	s_mov_b32 m0, s10
	s_nop 0
	global_load_lds_dwordx4 v[20:21], off
	v_lshl_add_u64 v[20:21], s[6:7], 0, v[134:135]
	s_mov_b32 m0, s11
	s_nop 0
	global_load_lds_dwordx4 v[20:21], off
	v_lshl_add_u64 v[20:21], v[252:253], 0, s[34:35]
	s_mov_b32 m0, s67
	s_nop 0
	global_load_lds_dwordx4 v[20:21], off
	v_lshl_add_u64 v[20:21], v[152:153], 0, s[34:35]
	s_mov_b32 m0, s68
	s_nop 0
	global_load_lds_dwordx4 v[20:21], off
	s_waitcnt vmcnt(8)
	s_waitcnt lgkmcnt(0)
	s_barrier
	s_waitcnt lgkmcnt(0)
	v_mfma_f32_16x16x32_f16 v[20:23], v[12:15], v[32:35], v[154:157]
	v_mfma_f32_16x16x32_f16 v[60:63], v[16:19], v[40:43], v[20:23]
	v_mfma_f32_16x16x32_f16 v[20:23], v[182:185], v[32:35], v[158:161]
	v_mfma_f32_16x16x32_f16 v[52:55], v[206:209], v[40:43], v[20:23]
	v_mfma_f32_16x16x32_f16 v[20:23], v[12:15], v[218:221], v[162:165]
	v_mfma_f32_16x16x32_f16 v[44:47], v[16:19], v[230:233], v[20:23]
	v_mfma_f32_16x16x32_f16 v[20:23], v[182:185], v[218:221], v[166:169]
	v_mfma_f32_16x16x32_f16 v[36:39], v[206:209], v[230:233], v[20:23]
	v_mfma_f32_16x16x32_f16 v[20:23], v[12:15], v[234:237], v[170:173]
	v_mfma_f32_16x16x32_f16 v[0:3], v[12:15], v[242:245], v[0:3]
	v_mfma_f32_16x16x32_f16 v[28:31], v[16:19], v[238:241], v[20:23]
	v_mfma_f32_16x16x32_f16 v[20:23], v[182:185], v[234:237], v[174:177]
	v_mfma_f32_16x16x32_f16 v[12:15], v[16:19], v[246:249], v[0:3]
	v_mfma_f32_16x16x32_f16 v[0:3], v[182:185], v[242:245], v[4:7]
	v_mfma_f32_16x16x32_f16 v[20:23], v[206:209], v[238:241], v[20:23]
	v_mfma_f32_16x16x32_f16 v[4:7], v[206:209], v[246:249], v[0:3]
	v_mfma_f32_16x16x32_f16 v[0:3], v[210:213], v[32:35], v[8:11]
	v_mfma_f32_16x16x32_f16 v[56:59], v[214:217], v[40:43], v[0:3]
	v_mfma_f32_16x16x32_f16 v[0:3], v[222:225], v[32:35], v[186:189]
	v_mfma_f32_16x16x32_f16 v[48:51], v[226:229], v[40:43], v[0:3]
	v_mfma_f32_16x16x32_f16 v[0:3], v[210:213], v[218:221], v[24:27]
	v_mfma_f32_16x16x32_f16 v[40:43], v[214:217], v[230:233], v[0:3]
	v_mfma_f32_16x16x32_f16 v[0:3], v[222:225], v[218:221], v[190:193]
	v_mfma_f32_16x16x32_f16 v[32:35], v[226:229], v[230:233], v[0:3]
	v_mfma_f32_16x16x32_f16 v[0:3], v[210:213], v[234:237], v[194:197]
	v_mfma_f32_16x16x32_f16 v[24:27], v[214:217], v[238:241], v[0:3]
	v_mfma_f32_16x16x32_f16 v[0:3], v[222:225], v[234:237], v[198:201]
	v_mfma_f32_16x16x32_f16 v[16:19], v[226:229], v[238:241], v[0:3]
	v_mfma_f32_16x16x32_f16 v[0:3], v[210:213], v[242:245], v[202:205]
	v_mfma_f32_16x16x32_f16 v[8:11], v[214:217], v[246:249], v[0:3]
	v_mfma_f32_16x16x32_f16 v[0:3], v[222:225], v[242:245], v[178:181]
	v_mfma_f32_16x16x32_f16 v[0:3], v[226:229], v[246:249], v[0:3]
	s_barrier
	s_andn2_b64 vcc, exec, s[26:27]
	s_cbranch_vccnz .LBB0_1471
	s_barrier
